# GEMM K-loops: per-segment setprio toggling replaced by one static priority raise for waves 4-7 (on v32)
# baseline (speedup 1.0000x reference)
;     __device__ bool next(int i, Unit& u) const {
;         const long L = (long)i * G + c; if (L >= nwg) return false;
;         int wgid = (int)L; { const int q = nwg / NXCD, r = nwg % NXCD, xcd = wgid % NXCD, off = wgid / NXCD; wgid = (xcd < r ? xcd * (q + 1) : r * (q + 1) + (xcd - r) * q) + off; }
;         const int nig = WGM * nN, gid = wgid / nig, fm = gid * WGM, gsz = (nM - fm) < WGM ? (nM - fm) : WGM;
;         u.pm = fm + ((wgid % nig) % gsz); u.pn = (wgid % nig) / gsz; return true;
;     }
; template <class Epi, bool ALIGN_EPI, int K, int LDA, int LDB>
; __device__ __forceinline__ void gemm_phase(LAS unsigned char* lds, const int wid, const Gemm g, const StaticOrder& S, const Epi& E) {
;     const int lane = lane_id_(), tid = wid * 64 + lane, wr = wid >> 2, wc = wid & 3, fr = lane & 15, fq = lane >> 4;
;     constexpr int nt = K / BK;
;     unsigned voffA[2], voffB[2];
; #pragma unroll
;     for (int i = 0; i < 2; ++i) { int R, C; stage_rc(tid * 16 + i * 8192, R, C); const int Rb = Epi::PERM ? ((R & ~31) + perm32(R & 31)) : R;
;         voffA[i] = (unsigned)(R * LDA + C) * 2u; voffB[i] = (unsigned)(Rb * LDB + C) * 2u; }
;     constexpr size_t kstep = (size_t)(BK * 2);
;     constexpr size_t hA = (size_t)HALF * LDA * 2, hB = (size_t)HALF * LDB * 2;
;     constexpr size_t tA = 2 * hA, tB = 2 * hB;
;     const unsigned ldsw = (unsigned)wid * 1024u;
;     const int aoff = lds_byte(wr * 64 + fr, fq * 8), boff = lds_byte(wc * 32 + fr, fq * 8);
;     ...
;     Unit cur, nxt; int ui = 0;
;     if (!S.next(0, cur)) return;
;     f32x4 acc[2][2][4][2];
; #pragma unroll
;     for (int a = 0; a < 2; ++a)
; #pragma unroll
;         for (int b = 0; b < 2; ++b)
; #pragma unroll
;             for (int m = 0; m < 4; ++m)
; #pragma unroll
;                 for (int n = 0; n < 2; ++n) acc[a][b][m][n] = (f32x4){0.f, 0.f, 0.f, 0.f};
;     bf16x8 At[4][2], B0[2][2], B1[2][2];
;     const char* cA = (const char*)g.A + (size_t)cur.pm * tA; const char* cB = (const char*)g.Bt + (size_t)cur.pn * tB;
;     PG8_STAGE(PG8_SB(0, 0), cB, voffB); PG8_STAGE(PG8_SB(0, 1), cB + hB, voffB); PG8_STAGE(PG8_SA(0, 0), cA, voffA); PG8_STAGE(PG8_SA(0, 1), cA + hA, voffA);
;     if (wr == 1) PG8_BAR;
;     PG8_WAIT_V(2); PG8_BAR;
;     PG8_STAGE(PG8_SB(1, 0), cB + kstep, voffB); PG8_STAGE(PG8_SA(1, 0), cA + kstep, voffA); PG8_STAGE(PG8_SB(1, 1), cB + hB + kstep, voffB);
.LBB0_222:
	s_add_u32 s0, s46, 0x4200000
	v_writelane_b32 v254, s0, 0
	s_addc_u32 s0, s47, 0
	s_add_u32 s70, s46, 0xc200000
	s_addc_u32 s71, s47, 0
	s_cmp_lt_i32 s84, 3
	v_writelane_b32 v254, s0, 1
	s_cselect_b64 s[0:1], -1, 0
	s_cmp_gt_i32 s85, 2
	s_cselect_b64 s[4:5], -1, 0
	s_and_b64 s[0:1], s[0:1], s[4:5]
	s_andn2_b64 vcc, exec, s[0:1]
	s_cbranch_vccnz .LBB0_295
	s_mov_b64 s[0:1], s[88:89]
	s_cmpk_lt_i32 s2, 0xa00
	v_mbcnt_lo_u32_b32 v8, -1, 0
	v_mbcnt_hi_u32_b32 v8, -1, v8
	s_cbranch_scc0 .LBB0_239
	s_add_u32 s0, s46, 0x400000
	s_addc_u32 s1, s47, 0
	s_lshr_b32 s5, s86, 8
	s_lshl_b32 s3, s50, 10
	s_cmp_eq_u32 s5, 1
	s_cselect_b64 s[6:7], -1, 0
	s_ashr_i32 s28, s2, 31
	s_lshr_b32 s4, s28, 29
	s_add_i32 s4, s2, s4
	s_ashr_i32 s8, s4, 3
	s_and_b32 s4, s4, -8
	s_sub_i32 s4, s2, s4
	s_cmp_lt_i32 s4, 0
	s_movk_i32 s29, 0x141
	s_cselect_b32 s9, s29, 0x140
	s_mul_i32 s4, s4, s9
	s_add_i32 s4, s4, s8
	s_mul_hi_i32 s8, s4, 0x66666667
	s_lshr_b32 s9, s8, 31
	s_ashr_i32 s8, s8, 5
	s_add_i32 s8, s8, s9
	s_lshl_b32 s9, s8, 3
	s_mulk_i32 s8, 0x50
	v_lshl_add_u32 v0, v8, 4, s3
	s_sub_i32 s8, s4, s8
	v_add_u32_e32 v1, 0x2000, v0
	s_bfe_i32 s4, s8, 0x80000
	v_ashrrev_i32_e32 v2, 31, v1
	s_bfe_u32 s4, s4, 0x3000c
	v_lshrrev_b32_e32 v2, 22, v2
	s_add_i32 s10, s8, s4
	v_add_u32_e32 v2, v1, v2
	s_bfe_i32 s4, s10, 0x80000
	s_and_b32 s10, s10, 0xf8
	v_ashrrev_i32_e32 v9, 10, v2
	s_sub_i32 s8, s8, s10
	v_mul_i32_i24_e32 v2, 0x400, v9
	s_sext_i32_i16 s4, s4
	s_sext_i32_i8 s8, s8
	v_sub_u32_e32 v1, v1, v2
	s_lshr_b32 s4, s4, 3
	s_add_i32 s12, s9, s8
	v_lshrrev_b32_e32 v2, 4, v1
	s_ashr_i32 s13, s12, 31
	s_bfe_i64 s[10:11], s[4:5], 0x100000
	v_bitop3_b32 v1, v2, v1, 32 bitop3:0x6c
	s_lshl_b64 s[8:9], s[12:13], 19
	s_lshl_b64 s[10:11], s[10:11], 19
	v_ashrrev_i32_e32 v2, 31, v1
	s_add_u32 s24, s0, s10
	v_lshrrev_b32_e32 v2, 26, v2
	s_addc_u32 s25, s1, s11
	s_add_i32 s13, s3, 0
	v_add_u32_e32 v2, v1, v2
	s_add_i32 m0, s13, 0x10000
	s_add_i32 s14, s13, 0x12000
	v_ashrrev_i32_e32 v10, 6, v2
	v_lshlrev_b32_e32 v3, 3, v9
	v_and_b32_e32 v2, 0xffc0, v2
	s_add_u32 s10, s24, 0x40000
	v_and_b32_e32 v3, -16, v3
	v_sub_u32_e32 v1, v1, v2
	s_addc_u32 s11, s25, 0
	s_add_i32 s15, s13, 0x14000
	s_add_i32 s16, s13, 0x16000
	v_readlane_b32 s17, v254, 0
	v_add_u32_e32 v3, v10, v3
	v_lshrrev_b16_e32 v2, 7, v1
	s_add_u32 s22, s17, s8
	v_and_b32_e32 v4, 3, v10
	s_mov_b32 s17, 0x1fffe0
	v_lshrrev_b32_e32 v5, 2, v3
	v_lshlrev_b32_e32 v6, 1, v3
	v_and_b32_e32 v2, 1, v2
	v_and_or_b32 v4, v3, s17, v4
	v_and_b32_e32 v5, 4, v5
	v_and_b32_e32 v6, 24, v6
	v_add_u16_e32 v1, v1, v2
	v_mov_b32_e32 v2, 1
	v_or3_b32 v4, v4, v5, v6
	v_lshlrev_b32_e32 v5, 5, v9
	v_ashrrev_i16_sdwa v1, v2, sext(v1) dst_sel:DWORD dst_unused:UNUSED_PAD src0_sel:DWORD src1_sel:BYTE_0
	v_and_b32_e32 v5, 32, v5
	v_bfe_i32 v11, v1, 0, 16
	v_add_lshl_u32 v1, v5, v11, 1
	v_lshl_add_u32 v128, v4, 11, v1
	v_lshl_add_u32 v130, v3, 11, v1
	v_ashrrev_i32_e32 v1, 31, v0
	v_lshrrev_b32_e32 v1, 22, v1
	v_add_u32_e32 v1, v0, v1
	v_ashrrev_i32_e32 v12, 10, v1
	v_mul_i32_i24_e32 v1, 0x400, v12
	v_sub_u32_e32 v0, v0, v1
	v_lshrrev_b32_e32 v1, 4, v0
	v_bitop3_b32 v0, v1, v0, 32 bitop3:0x6c
	v_ashrrev_i32_e32 v1, 31, v0
	v_lshrrev_b32_e32 v1, 26, v1
	v_add_u32_e32 v1, v0, v1
	v_lshlrev_b32_e32 v3, 3, v12
	v_ashrrev_i32_e32 v13, 6, v1
	v_and_b32_e32 v3, -16, v3
	v_add_u32_e32 v3, v13, v3
	v_and_b32_e32 v4, 3, v13
	v_lshrrev_b32_e32 v5, 2, v3
	v_lshlrev_b32_e32 v6, 1, v3
	v_and_b32_e32 v1, 0xc0, v1
	v_and_or_b32 v4, v3, s17, v4
	v_and_b32_e32 v5, 4, v5
	v_and_b32_e32 v6, 24, v6
	v_sub_u32_e32 v0, v0, v1
	v_or3_b32 v4, v4, v5, v6
	v_lshlrev_b32_e32 v5, 5, v12
	v_ashrrev_i16_sdwa v0, v2, sext(v0) dst_sel:DWORD dst_unused:UNUSED_PAD src0_sel:DWORD src1_sel:BYTE_0
	v_and_b32_e32 v5, 32, v5
	v_bfe_i32 v14, v0, 0, 16
	v_add_lshl_u32 v0, v5, v14, 1
	v_lshl_add_u32 v132, v4, 11, v0
	global_load_lds_dwordx4 v132, s[24:25]
	s_mov_b32 m0, s14
	v_readlane_b32 s8, v254, 1
	global_load_lds_dwordx4 v128, s[24:25]
	s_mov_b32 m0, s15
	s_addc_u32 s23, s8, s9
	s_add_i32 s30, s13, 0x2000
	global_load_lds_dwordx4 v132, s[10:11]
	s_mov_b32 m0, s16
	s_add_u32 s8, s22, 0x40000
	v_lshl_add_u32 v134, v3, 11, v0
	global_load_lds_dwordx4 v128, s[10:11]
	s_mov_b32 m0, s13
	s_addc_u32 s9, s23, 0
	s_add_i32 s31, s13, 0x4000
	global_load_lds_dwordx4 v134, s[22:23]
	s_mov_b32 m0, s30
	s_add_i32 s33, s13, 0x6000
	global_load_lds_dwordx4 v130, s[22:23]
	s_mov_b32 m0, s31
	v_mov_b32_e32 v133, 0
	global_load_lds_dwordx4 v134, s[8:9]
	s_mov_b32 m0, s33
	v_mov_b32_e32 v129, v133
	global_load_lds_dwordx4 v130, s[8:9]
	v_mov_b32_e32 v135, v133
	v_mov_b32_e32 v131, v133
	s_mov_b32 s34, 0
	s_cmp_lg_u32 s5, 1
	v_lshl_add_u64 v[6:7], s[24:25], 0, v[132:133]
	v_lshl_add_u64 v[4:5], s[24:25], 0, v[128:129]
	v_lshl_add_u64 v[2:3], s[22:23], 0, v[134:135]
	v_lshl_add_u64 v[0:1], s[22:23], 0, v[130:131]
	s_cbranch_scc1 .LBB0_226
	s_setprio 1
	s_barrier

; #define PG8_STAGE(bufoff, gbase, voff) do { _Pragma("unroll") for (int _i = 0; _i < 2; ++_i) \
;         __builtin_amdgcn_global_load_lds((const unsigned*)((const char*)(gbase) + (voff)[_i]), (LAS unsigned*)(lds + (bufoff) + ldsw + _i * 8192), 16, 0, 0); } while (0)
; #define PG8_LDA(dst, b, h) do { _Pragma("unroll") for (int m = 0; m < 4; ++m) _Pragma("unroll") for (int k = 0; k < 2; ++k) dst[m][k] = *(const LAS bf16x8*)(lds + PG8_SA(b, h) + aoff + m * 2048 + k * 1024); } while (0)
; #define PG8_LDB(dst, b, h) do { _Pragma("unroll") for (int n = 0; n < 2; ++n) _Pragma("unroll") for (int k = 0; k < 2; ++k) dst[n][k] = *(const LAS bf16x8*)(lds + PG8_SB(b, h) + boff + n * 2048 + k * 1024); } while (0)
; #define PG8_MMA(ai, bj, At, Bt) do { __builtin_amdgcn_s_setprio(1); _Pragma("unroll") for (int m = 0; m < 4; ++m) _Pragma("unroll") for (int n = 0; n < 2; ++n) _Pragma("unroll") for (int k = 0; k < 2; ++k) \
;         acc[ai][bj][m][n] = __builtin_amdgcn_mfma_f32_16x16x32_bf16(Bt[n][k], At[m][k], acc[ai][bj][m][n], 0, 0, 0); __builtin_amdgcn_s_setprio(0); } while (0)
; #define PG8_WAIT_V(n) asm volatile("s_waitcnt vmcnt(" #n ")" ::: "memory")
; #define PG8_WAIT_L(n) asm volatile("s_waitcnt lgkmcnt(" #n ")" ::: "memory")
; #define PG8_BAR __builtin_amdgcn_s_barrier()
; template <class Epi, bool ALIGN_EPI, int K, int LDA, int LDB>
; __device__ __forceinline__ void gemm_phase(LAS unsigned char* lds, const int wid, const Gemm g, const StaticOrder& S, const Epi& E) {
;     ...
;         for (int t = 0; t < nt; t += 2) {
;             const bool last = (t == nt - 2);
;             const char* a1 = cA + (size_t)(t + 1) * kstep;
;             const char* a2 = last ? nA : cA + (size_t)(t + 2) * kstep; const char* b2 = last ? nB : cB + (size_t)(t + 2) * kstep;
;             const char* a3 = a2 + kstep; const char* b3 = b2 + kstep;
;             PG8_LDB(B0, 0, 0); PG8_LDB(B1, 0, 1); PG8_SCHED; PG8_LDA(At, 0, 0); PG8_STAGE(PG8_SA(1, 1), a1 + hA, voffA);
;             PG8_WAIT_V(8); PG8_WAIT_L(0); PG8_BAR; PG8_MMA(0, 0, At, B0); PG8_MMA(0, 1, At, B1); PG8_BAR; PG8_SCHED;
;             PG8_LDA(At, 0, 1); PG8_STAGE(PG8_SB(0, 0), b2, voffB); PG8_STAGE(PG8_SB(0, 1), b2 + hB, voffB); PG8_STAGE(PG8_SA(0, 0), a2, voffA);
;             PG8_WAIT_V(8); PG8_WAIT_L(0); PG8_BAR; PG8_MMA(1, 0, At, B0); PG8_MMA(1, 1, At, B1); PG8_BAR; PG8_SCHED;
.LBB0_232:
	ds_read_b128 v[148:151], v145
	ds_read_b128 v[152:155], v145 offset:1024
	ds_read_b128 v[156:159], v145 offset:2048
	ds_read_b128 v[160:163], v145 offset:3072
	ds_read_b128 v[164:167], v146
	ds_read_b128 v[168:171], v146 offset:1024
	ds_read_b128 v[172:175], v146 offset:2048
	ds_read_b128 v[176:179], v146 offset:3072
	s_add_u32 s24, s22, 0xfffc0080
	s_addc_u32 s25, s23, -1
	s_cmp_eq_u32 s55, 12
	s_cselect_b32 s27, s17, s25
	s_cselect_b32 s26, s48, s24
	s_cselect_b32 s25, s15, s54
	s_cselect_b32 s24, s49, s51
	s_add_i32 m0, s13, 0xc000
	ds_read_b128 v[180:183], v147
	ds_read_b128 v[184:187], v147 offset:1024
	ds_read_b128 v[188:191], v147 offset:2048
	ds_read_b128 v[192:195], v147 offset:3072
	ds_read_b128 v[196:199], v147 offset:4096
	ds_read_b128 v[200:203], v147 offset:5120
	ds_read_b128 v[204:207], v147 offset:6144
	ds_read_b128 v[208:211], v147 offset:7168
	global_load_lds_dwordx4 v136, s[22:23]
	s_add_i32 m0, s13, 0xe000
	s_nop 0
	global_load_lds_dwordx4 v138, s[22:23]
	s_waitcnt vmcnt(8)
	s_waitcnt lgkmcnt(0)
	s_barrier
	s_waitcnt lgkmcnt(0)
	v_mfma_f32_16x16x32_bf16 v[124:127], v[148:151], v[180:183], v[124:127]
	v_mfma_f32_16x16x32_bf16 v[120:123], v[156:159], v[180:183], v[120:123]
	v_mfma_f32_16x16x32_bf16 v[116:119], v[148:151], v[188:191], v[116:119]
	v_mfma_f32_16x16x32_bf16 v[112:115], v[156:159], v[188:191], v[112:115]
	v_mfma_f32_16x16x32_bf16 v[100:103], v[148:151], v[196:199], v[100:103]
	v_mfma_f32_16x16x32_bf16 v[96:99], v[156:159], v[196:199], v[96:99]
	v_mfma_f32_16x16x32_bf16 v[84:87], v[148:151], v[204:207], v[84:87]
	v_mfma_f32_16x16x32_bf16 v[80:83], v[156:159], v[204:207], v[80:83]
	v_mfma_f32_16x16x32_bf16 v[124:127], v[152:155], v[184:187], v[124:127]
	v_mfma_f32_16x16x32_bf16 v[120:123], v[160:163], v[184:187], v[120:123]
	v_mfma_f32_16x16x32_bf16 v[116:119], v[152:155], v[192:195], v[116:119]
	v_mfma_f32_16x16x32_bf16 v[112:115], v[160:163], v[192:195], v[112:115]
	v_mfma_f32_16x16x32_bf16 v[100:103], v[152:155], v[200:203], v[100:103]
	v_mfma_f32_16x16x32_bf16 v[96:99], v[160:163], v[200:203], v[96:99]
	v_mfma_f32_16x16x32_bf16 v[84:87], v[152:155], v[208:211], v[84:87]
	v_mfma_f32_16x16x32_bf16 v[80:83], v[160:163], v[208:211], v[80:83]
	v_mfma_f32_16x16x32_bf16 v[108:111], v[164:167], v[180:183], v[108:111]
	v_mfma_f32_16x16x32_bf16 v[104:107], v[172:175], v[180:183], v[104:107]
	v_mfma_f32_16x16x32_bf16 v[92:95], v[164:167], v[188:191], v[92:95]
	v_mfma_f32_16x16x32_bf16 v[88:91], v[172:175], v[188:191], v[88:91]
	v_mfma_f32_16x16x32_bf16 v[76:79], v[164:167], v[196:199], v[76:79]
	v_mfma_f32_16x16x32_bf16 v[72:75], v[172:175], v[196:199], v[72:75]
	v_mfma_f32_16x16x32_bf16 v[68:71], v[164:167], v[204:207], v[68:71]
	v_mfma_f32_16x16x32_bf16 v[64:67], v[172:175], v[204:207], v[64:67]
	v_mfma_f32_16x16x32_bf16 v[108:111], v[168:171], v[184:187], v[108:111]
	v_mfma_f32_16x16x32_bf16 v[104:107], v[176:179], v[184:187], v[104:107]
	v_mfma_f32_16x16x32_bf16 v[92:95], v[168:171], v[192:195], v[92:95]
	v_mfma_f32_16x16x32_bf16 v[88:91], v[176:179], v[192:195], v[88:91]
	v_mfma_f32_16x16x32_bf16 v[76:79], v[168:171], v[200:203], v[76:79]
	v_mfma_f32_16x16x32_bf16 v[72:75], v[176:179], v[200:203], v[72:75]
	v_mfma_f32_16x16x32_bf16 v[68:71], v[168:171], v[208:211], v[68:71]
	v_mfma_f32_16x16x32_bf16 v[64:67], v[176:179], v[208:211], v[64:67]
	s_barrier
	s_add_u32 s98, s24, s10
	s_addc_u32 s99, s25, s11
	s_add_u32 s100, s26, s10
	s_addc_u32 s101, s27, s11
	s_add_i32 s56, s40, s3
	s_mov_b32 m0, s56
	ds_read_b128 v[180:183], v147 offset:16384
	ds_read_b128 v[184:187], v147 offset:17408
	ds_read_b128 v[188:191], v147 offset:18432
	ds_read_b128 v[192:195], v147 offset:19456
	ds_read_b128 v[196:199], v147 offset:20480
	ds_read_b128 v[200:203], v147 offset:21504
	ds_read_b128 v[204:207], v147 offset:22528
	ds_read_b128 v[208:211], v147 offset:23552
	global_load_lds_dwordx4 v132, s[24:25]
	s_add_i32 m0, s56, 0x2000
	s_add_u32 s56, s24, 0x40000
	s_addc_u32 s57, s25, 0
	s_add_i32 s58, s41, s3
	global_load_lds_dwordx4 v128, s[24:25]
	s_mov_b32 m0, s58
	s_nop 0
	global_load_lds_dwordx4 v132, s[56:57]
	s_add_i32 m0, s58, 0x2000
	s_nop 0
	global_load_lds_dwordx4 v128, s[56:57]
	s_mov_b32 m0, s13
	s_nop 0
	global_load_lds_dwordx4 v134, s[26:27]
	s_mov_b32 m0, s30
	s_nop 0
	global_load_lds_dwordx4 v130, s[26:27]
	s_waitcnt vmcnt(8)
	s_waitcnt lgkmcnt(0)
	s_barrier
	s_waitcnt lgkmcnt(0)
	v_mfma_f32_16x16x32_bf16 v[60:63], v[148:151], v[180:183], v[60:63]
	v_mfma_f32_16x16x32_bf16 v[56:59], v[156:159], v[180:183], v[56:59]
	v_mfma_f32_16x16x32_bf16 v[52:55], v[148:151], v[188:191], v[52:55]
	v_mfma_f32_16x16x32_bf16 v[48:51], v[156:159], v[188:191], v[48:51]
	v_mfma_f32_16x16x32_bf16 v[36:39], v[148:151], v[196:199], v[36:39]
	v_mfma_f32_16x16x32_bf16 v[32:35], v[156:159], v[196:199], v[32:35]
	v_mfma_f32_16x16x32_bf16 v[20:23], v[148:151], v[204:207], v[20:23]
	v_mfma_f32_16x16x32_bf16 v[16:19], v[156:159], v[204:207], v[16:19]
	v_mfma_f32_16x16x32_bf16 v[60:63], v[152:155], v[184:187], v[60:63]
	v_mfma_f32_16x16x32_bf16 v[56:59], v[160:163], v[184:187], v[56:59]
	v_mfma_f32_16x16x32_bf16 v[52:55], v[152:155], v[192:195], v[52:55]
	v_mfma_f32_16x16x32_bf16 v[48:51], v[160:163], v[192:195], v[48:51]
	v_mfma_f32_16x16x32_bf16 v[36:39], v[152:155], v[200:203], v[36:39]
	v_mfma_f32_16x16x32_bf16 v[32:35], v[160:163], v[200:203], v[32:35]
	v_mfma_f32_16x16x32_bf16 v[20:23], v[152:155], v[208:211], v[20:23]
	v_mfma_f32_16x16x32_bf16 v[16:19], v[160:163], v[208:211], v[16:19]
	v_mfma_f32_16x16x32_bf16 v[44:47], v[164:167], v[180:183], v[44:47]
	v_mfma_f32_16x16x32_bf16 v[40:43], v[172:175], v[180:183], v[40:43]
	v_mfma_f32_16x16x32_bf16 v[28:31], v[164:167], v[188:191], v[28:31]
	v_mfma_f32_16x16x32_bf16 v[24:27], v[172:175], v[188:191], v[24:27]
	v_mfma_f32_16x16x32_bf16 v[12:15], v[164:167], v[196:199], v[12:15]
	v_mfma_f32_16x16x32_bf16 v[8:11], v[172:175], v[196:199], v[8:11]
	v_mfma_f32_16x16x32_bf16 v[4:7], v[164:167], v[204:207], v[4:7]
	v_mfma_f32_16x16x32_bf16 v[0:3], v[172:175], v[204:207], v[0:3]
	v_mfma_f32_16x16x32_bf16 v[44:47], v[168:171], v[184:187], v[44:47]
	v_mfma_f32_16x16x32_bf16 v[40:43], v[176:179], v[184:187], v[40:43]
	v_mfma_f32_16x16x32_bf16 v[28:31], v[168:171], v[192:195], v[28:31]
	v_mfma_f32_16x16x32_bf16 v[24:27], v[176:179], v[192:195], v[24:27]
	v_mfma_f32_16x16x32_bf16 v[12:15], v[168:171], v[200:203], v[12:15]
	v_mfma_f32_16x16x32_bf16 v[8:11], v[176:179], v[200:203], v[8:11]
	v_mfma_f32_16x16x32_bf16 v[4:7], v[168:171], v[208:211], v[4:7]
	v_mfma_f32_16x16x32_bf16 v[0:3], v[176:179], v[208:211], v[0:3]
	s_barrier
; __device__ __forceinline__ int lane_id_() { int l; asm volatile("v_mbcnt_lo_u32_b32 %0, -1, 0\n\tv_mbcnt_hi_u32_b32 %0, -1, %0" : "=v"(l)); return l; }
; #define PG8_STAGE(bufoff, gbase, voff) do { _Pragma("unroll") for (int _i = 0; _i < 2; ++_i) \
;         __builtin_amdgcn_global_load_lds((const unsigned*)((const char*)(gbase) + (voff)[_i]), (LAS unsigned*)(lds + (bufoff) + ldsw + _i * 8192), 16, 0, 0); } while (0)
; #define PG8_LDA(dst, b, h) do { _Pragma("unroll") for (int m = 0; m < 4; ++m) _Pragma("unroll") for (int k = 0; k < 2; ++k) dst[m][k] = *(const LAS bf16x8*)(lds + PG8_SA(b, h) + aoff + m * 2048 + k * 1024); } while (0)
; #define PG8_LDB(dst, b, h) do { _Pragma("unroll") for (int n = 0; n < 2; ++n) _Pragma("unroll") for (int k = 0; k < 2; ++k) dst[n][k] = *(const LAS bf16x8*)(lds + PG8_SB(b, h) + boff + n * 2048 + k * 1024); } while (0)
; #define PG8_MMA(ai, bj, At, Bt) do { __builtin_amdgcn_s_setprio(1); _Pragma("unroll") for (int m = 0; m < 4; ++m) _Pragma("unroll") for (int n = 0; n < 2; ++n) _Pragma("unroll") for (int k = 0; k < 2; ++k) \
;         acc[ai][bj][m][n] = __builtin_amdgcn_mfma_f32_16x16x32_bf16(Bt[n][k], At[m][k], acc[ai][bj][m][n], 0, 0, 0); __builtin_amdgcn_s_setprio(0); } while (0)
; #define PG8_WAIT_V(n) asm volatile("s_waitcnt vmcnt(" #n ")" ::: "memory")
; #define PG8_WAIT_L(n) asm volatile("s_waitcnt lgkmcnt(" #n ")" ::: "memory")
; #define PG8_BAR __builtin_amdgcn_s_barrier()
; #define PG8_SCHED __builtin_amdgcn_sched_barrier(0)
; template <class Epi, bool ALIGN_EPI, int K, int LDA, int LDB>
; __device__ __forceinline__ void gemm_phase(LAS unsigned char* lds, const int wid, const Gemm g, const StaticOrder& S, const Epi& E) {
;     ...
;             PG8_LDB(B0, 1, 0); PG8_LDB(B1, 1, 1); PG8_SCHED; PG8_LDA(At, 1, 0); PG8_STAGE(PG8_SA(0, 1), a2 + hA, voffA);
;             PG8_WAIT_V(8); PG8_WAIT_L(0); PG8_BAR; PG8_MMA(0, 0, At, B0); PG8_MMA(0, 1, At, B1); PG8_BAR; PG8_SCHED;
;             PG8_LDA(At, 1, 1); PG8_STAGE(PG8_SB(1, 0), b3, voffB); PG8_STAGE(PG8_SB(1, 1), b3 + hB, voffB); PG8_STAGE(PG8_SA(1, 0), a3, voffA);
;             PG8_WAIT_V(8); PG8_WAIT_L(0); PG8_BAR; PG8_MMA(1, 0, At, B0); PG8_MMA(1, 1, At, B1); PG8_BAR; PG8_SCHED;
;         }
;         if constexpr (ALIGN_EPI) { if (wr == 0) PG8_BAR; }
;         { const int l2 = lane_id_(); E(acc, cur, wid >> 2, wid & 3, l2 & 15, l2 >> 4); }
;         if (!has_next) break;
	s_add_i32 s56, 0, 0x18000
	s_add_i32 s57, 0, 0x1c000
	v_add_u32_e32 v160, s56, v144
	v_add_u32_e32 v176, s57, v144
	ds_read_b128 v[148:151], v160
	ds_read_b128 v[152:155], v160 offset:1024
	ds_read_b128 v[156:159], v160 offset:2048
	ds_read_b128 v[160:163], v160 offset:3072
	ds_read_b128 v[164:167], v176
	ds_read_b128 v[168:171], v176 offset:1024
	ds_read_b128 v[172:175], v176 offset:2048
	ds_read_b128 v[176:179], v176 offset:3072
	s_add_u32 s26, s26, 0x40000
	s_addc_u32 s27, s27, 0
	s_mov_b32 m0, s31
	ds_read_b128 v[180:183], v147 offset:32768
	ds_read_b128 v[184:187], v147 offset:33792
	ds_read_b128 v[188:191], v147 offset:34816
	ds_read_b128 v[192:195], v147 offset:35840
	ds_read_b128 v[196:199], v147 offset:36864
	ds_read_b128 v[200:203], v147 offset:37888
	ds_read_b128 v[204:207], v147 offset:38912
	ds_read_b128 v[208:211], v147 offset:39936
	global_load_lds_dwordx4 v134, s[26:27]
	s_mov_b32 m0, s33
	s_nop 0
	global_load_lds_dwordx4 v130, s[26:27]
	s_waitcnt vmcnt(8)
	s_waitcnt lgkmcnt(0)
	s_barrier
	s_waitcnt lgkmcnt(0)
	v_mfma_f32_16x16x32_bf16 v[124:127], v[148:151], v[180:183], v[124:127]
	v_mfma_f32_16x16x32_bf16 v[120:123], v[156:159], v[180:183], v[120:123]
	v_mfma_f32_16x16x32_bf16 v[116:119], v[148:151], v[188:191], v[116:119]
	v_mfma_f32_16x16x32_bf16 v[112:115], v[156:159], v[188:191], v[112:115]
	v_mfma_f32_16x16x32_bf16 v[100:103], v[148:151], v[196:199], v[100:103]
	v_mfma_f32_16x16x32_bf16 v[96:99], v[156:159], v[196:199], v[96:99]
	v_mfma_f32_16x16x32_bf16 v[84:87], v[148:151], v[204:207], v[84:87]
	v_mfma_f32_16x16x32_bf16 v[80:83], v[156:159], v[204:207], v[80:83]
	v_mfma_f32_16x16x32_bf16 v[124:127], v[152:155], v[184:187], v[124:127]
	v_mfma_f32_16x16x32_bf16 v[120:123], v[160:163], v[184:187], v[120:123]
	v_mfma_f32_16x16x32_bf16 v[116:119], v[152:155], v[192:195], v[116:119]
	v_mfma_f32_16x16x32_bf16 v[112:115], v[160:163], v[192:195], v[112:115]
	v_mfma_f32_16x16x32_bf16 v[100:103], v[152:155], v[200:203], v[100:103]
	v_mfma_f32_16x16x32_bf16 v[96:99], v[160:163], v[200:203], v[96:99]
	v_mfma_f32_16x16x32_bf16 v[84:87], v[152:155], v[208:211], v[84:87]
	v_mfma_f32_16x16x32_bf16 v[80:83], v[160:163], v[208:211], v[80:83]
	v_mfma_f32_16x16x32_bf16 v[108:111], v[164:167], v[180:183], v[108:111]
	v_mfma_f32_16x16x32_bf16 v[104:107], v[172:175], v[180:183], v[104:107]
	v_mfma_f32_16x16x32_bf16 v[92:95], v[164:167], v[188:191], v[92:95]
	v_mfma_f32_16x16x32_bf16 v[88:91], v[172:175], v[188:191], v[88:91]
	v_mfma_f32_16x16x32_bf16 v[76:79], v[164:167], v[196:199], v[76:79]
	v_mfma_f32_16x16x32_bf16 v[72:75], v[172:175], v[196:199], v[72:75]
	v_mfma_f32_16x16x32_bf16 v[68:71], v[164:167], v[204:207], v[68:71]
	v_mfma_f32_16x16x32_bf16 v[64:67], v[172:175], v[204:207], v[64:67]
	v_mfma_f32_16x16x32_bf16 v[108:111], v[168:171], v[184:187], v[108:111]
	v_mfma_f32_16x16x32_bf16 v[104:107], v[176:179], v[184:187], v[104:107]
	v_mfma_f32_16x16x32_bf16 v[92:95], v[168:171], v[192:195], v[92:95]
	v_mfma_f32_16x16x32_bf16 v[88:91], v[176:179], v[192:195], v[88:91]
	v_mfma_f32_16x16x32_bf16 v[76:79], v[168:171], v[200:203], v[76:79]
	v_mfma_f32_16x16x32_bf16 v[72:75], v[176:179], v[200:203], v[72:75]
	v_mfma_f32_16x16x32_bf16 v[68:71], v[168:171], v[208:211], v[68:71]
	v_mfma_f32_16x16x32_bf16 v[64:67], v[176:179], v[208:211], v[64:67]
	s_barrier
	s_add_i32 s26, s56, s3
	s_mov_b32 m0, s26
	ds_read_b128 v[180:183], v147 offset:49152
	ds_read_b128 v[184:187], v147 offset:50176
	ds_read_b128 v[188:191], v147 offset:51200
	ds_read_b128 v[192:195], v147 offset:52224
	ds_read_b128 v[196:199], v147 offset:53248
	ds_read_b128 v[200:203], v147 offset:54272
	ds_read_b128 v[204:207], v147 offset:55296
	ds_read_b128 v[208:211], v147 offset:56320
	global_load_lds_dwordx4 v132, s[98:99]
	s_add_i32 m0, s26, 0x2000
	s_add_u32 s24, s24, 0x40080
	s_addc_u32 s25, s25, 0
	s_add_i32 s26, s57, s3
	global_load_lds_dwordx4 v128, s[98:99]
	s_mov_b32 m0, s26
	s_nop 0
	global_load_lds_dwordx4 v132, s[24:25]
	s_add_i32 m0, s26, 0x2000
	s_nop 0
	global_load_lds_dwordx4 v128, s[24:25]
	s_mov_b32 m0, s38
	s_nop 0
	global_load_lds_dwordx4 v134, s[100:101]
	s_mov_b32 m0, s39
	s_nop 0
	global_load_lds_dwordx4 v130, s[100:101]
	s_waitcnt vmcnt(8)
	s_waitcnt lgkmcnt(0)
	s_barrier
	s_waitcnt lgkmcnt(0)
	v_mfma_f32_16x16x32_bf16 v[60:63], v[148:151], v[180:183], v[60:63]
	v_mfma_f32_16x16x32_bf16 v[56:59], v[156:159], v[180:183], v[56:59]
	v_mfma_f32_16x16x32_bf16 v[52:55], v[148:151], v[188:191], v[52:55]
	v_mfma_f32_16x16x32_bf16 v[48:51], v[156:159], v[188:191], v[48:51]
	v_mfma_f32_16x16x32_bf16 v[36:39], v[148:151], v[196:199], v[36:39]
	v_mfma_f32_16x16x32_bf16 v[32:35], v[156:159], v[196:199], v[32:35]
	v_mfma_f32_16x16x32_bf16 v[20:23], v[148:151], v[204:207], v[20:23]
	v_mfma_f32_16x16x32_bf16 v[16:19], v[156:159], v[204:207], v[16:19]
	v_mfma_f32_16x16x32_bf16 v[60:63], v[152:155], v[184:187], v[60:63]
	v_mfma_f32_16x16x32_bf16 v[56:59], v[160:163], v[184:187], v[56:59]
	v_mfma_f32_16x16x32_bf16 v[52:55], v[152:155], v[192:195], v[52:55]
	v_mfma_f32_16x16x32_bf16 v[48:51], v[160:163], v[192:195], v[48:51]
	v_mfma_f32_16x16x32_bf16 v[36:39], v[152:155], v[200:203], v[36:39]
	v_mfma_f32_16x16x32_bf16 v[32:35], v[160:163], v[200:203], v[32:35]
	v_mfma_f32_16x16x32_bf16 v[20:23], v[152:155], v[208:211], v[20:23]
	v_mfma_f32_16x16x32_bf16 v[16:19], v[160:163], v[208:211], v[16:19]
	v_mfma_f32_16x16x32_bf16 v[44:47], v[164:167], v[180:183], v[44:47]
	v_mfma_f32_16x16x32_bf16 v[40:43], v[172:175], v[180:183], v[40:43]
	v_mfma_f32_16x16x32_bf16 v[28:31], v[164:167], v[188:191], v[28:31]
	v_mfma_f32_16x16x32_bf16 v[24:27], v[172:175], v[188:191], v[24:27]
	v_mfma_f32_16x16x32_bf16 v[12:15], v[164:167], v[196:199], v[12:15]
	v_mfma_f32_16x16x32_bf16 v[8:11], v[172:175], v[196:199], v[8:11]
	v_mfma_f32_16x16x32_bf16 v[4:7], v[164:167], v[204:207], v[4:7]
	v_mfma_f32_16x16x32_bf16 v[0:3], v[172:175], v[204:207], v[0:3]
	v_mfma_f32_16x16x32_bf16 v[44:47], v[168:171], v[184:187], v[44:47]
	v_mfma_f32_16x16x32_bf16 v[40:43], v[176:179], v[184:187], v[40:43]
	v_mfma_f32_16x16x32_bf16 v[28:31], v[168:171], v[192:195], v[28:31]
	v_mfma_f32_16x16x32_bf16 v[24:27], v[176:179], v[192:195], v[24:27]
	v_mfma_f32_16x16x32_bf16 v[12:15], v[168:171], v[200:203], v[12:15]
	v_mfma_f32_16x16x32_bf16 v[8:11], v[176:179], v[200:203], v[8:11]
	v_mfma_f32_16x16x32_bf16 v[4:7], v[168:171], v[208:211], v[4:7]
	v_mfma_f32_16x16x32_bf16 v[0:3], v[176:179], v[208:211], v[0:3]
	s_barrier
	s_add_i32 s55, s55, 2
	s_add_u32 s22, s22, 0x100
	s_addc_u32 s23, s23, 0
	s_add_u32 s51, s51, 0x100
	s_addc_u32 s54, s54, 0
	s_cmp_gt_u32 s55, 13
	s_cbranch_scc0 .LBB0_232
	s_and_b64 vcc, exec, s[8:9]
	s_cbranch_vccz .LBB0_235
	s_barrier

; #define PG8_WAIT_V(n) asm volatile("s_waitcnt vmcnt(" #n ")" ::: "memory")
; #define PG8_BAR __builtin_amdgcn_s_barrier()
; template <class Epi, bool ALIGN_EPI, int K, int LDA, int LDB>
; __device__ __forceinline__ void gemm_phase(LAS unsigned char* lds, const int wid, const Gemm g, const StaticOrder& S, const Epi& E) {
;     ...
;     PG8_WAIT_V(0);
;     if constexpr (!ALIGN_EPI) { if (wr == 0) PG8_BAR; }
;     PG8_BAR;
.LBB0_238:
	s_setprio 0
	s_waitcnt vmcnt(0)
	s_barrier

;     __device__ bool next(int i, Unit& u) const {
;         const long L = (long)i * G + c; if (L >= nwg) return false;
;         int wgid = (int)L; { const int q = nwg / NXCD, r = nwg % NXCD, xcd = wgid % NXCD, off = wgid / NXCD; wgid = (xcd < r ? xcd * (q + 1) : r * (q + 1) + (xcd - r) * q) + off; }
;         const int nig = WGM * nN, gid = wgid / nig, fm = gid * WGM, gsz = (nM - fm) < WGM ? (nM - fm) : WGM;
;         u.pm = fm + ((wgid % nig) % gsz); u.pn = (wgid % nig) / gsz; return true;
;     }
; template <class Epi, bool ALIGN_EPI, int K, int LDA, int LDB>
; __device__ __forceinline__ void gemm_phase(LAS unsigned char* lds, const int wid, const Gemm g, const StaticOrder& S, const Epi& E) {
;     const int lane = lane_id_(), tid = wid * 64 + lane, wr = wid >> 2, wc = wid & 3, fr = lane & 15, fq = lane >> 4;
;     constexpr int nt = K / BK;
;     unsigned voffA[2], voffB[2];
; #pragma unroll
;     for (int i = 0; i < 2; ++i) { int R, C; stage_rc(tid * 16 + i * 8192, R, C); const int Rb = Epi::PERM ? ((R & ~31) + perm32(R & 31)) : R;
;         voffA[i] = (unsigned)(R * LDA + C) * 2u; voffB[i] = (unsigned)(Rb * LDB + C) * 2u; }
;     constexpr size_t kstep = (size_t)(BK * 2);
;     constexpr size_t hA = (size_t)HALF * LDA * 2, hB = (size_t)HALF * LDB * 2;
;     constexpr size_t tA = 2 * hA, tB = 2 * hB;
;     const unsigned ldsw = (unsigned)wid * 1024u;
;     const int aoff = lds_byte(wr * 64 + fr, fq * 8), boff = lds_byte(wc * 32 + fr, fq * 8);
;     ...
;     Unit cur, nxt; int ui = 0;
;     if (!S.next(0, cur)) return;
;     f32x4 acc[2][2][4][2];
; #pragma unroll
;     for (int a = 0; a < 2; ++a)
; #pragma unroll
;         for (int b = 0; b < 2; ++b)
; #pragma unroll
;             for (int m = 0; m < 4; ++m)
; #pragma unroll
;                 for (int n = 0; n < 2; ++n) acc[a][b][m][n] = (f32x4){0.f, 0.f, 0.f, 0.f};
;     bf16x8 At[4][2], B0[2][2], B1[2][2];
;     const char* cA = (const char*)g.A + (size_t)cur.pm * tA; const char* cB = (const char*)g.Bt + (size_t)cur.pn * tB;
;     PG8_STAGE(PG8_SB(0, 0), cB, voffB); PG8_STAGE(PG8_SB(0, 1), cB + hB, voffB); PG8_STAGE(PG8_SA(0, 0), cA, voffA); PG8_STAGE(PG8_SA(0, 1), cA + hA, voffA);
;     if (wr == 1) PG8_BAR;
;     PG8_WAIT_V(2); PG8_BAR;
;     PG8_STAGE(PG8_SB(1, 0), cB + kstep, voffB); PG8_STAGE(PG8_SA(1, 0), cA + kstep, voffA); PG8_STAGE(PG8_SB(1, 1), cB + hB + kstep, voffB);
.LBB0_905:
	s_ashr_i32 s6, s1, 3
	s_add_u32 s1, s46, 0xc00000
	s_addc_u32 s3, s47, 0
	s_lshl_b32 s33, s50, 10
	s_waitcnt lgkmcnt(0)
	v_lshl_add_u32 v0, v8, 4, s33
	v_ashrrev_i32_e32 v1, 31, v0
	v_lshrrev_b32_e32 v1, 22, v1
	v_add_u32_e32 v1, v0, v1
	v_ashrrev_i32_e32 v9, 10, v1
	v_mul_i32_i24_e32 v1, 0x400, v9
	v_sub_u32_e32 v1, v0, v1
	v_lshrrev_b32_e32 v2, 4, v1
	v_bitop3_b32 v1, v2, v1, 32 bitop3:0x6c
	v_ashrrev_i32_e32 v3, 31, v1
	v_lshrrev_b32_e32 v3, 26, v3
	v_add_u32_e32 v3, v1, v3
	v_lshlrev_b32_e32 v2, 3, v9
	v_ashrrev_i32_e32 v10, 6, v3
	v_and_b32_e32 v3, 0xc0, v3
	v_and_b32_e32 v2, -16, v2
	v_sub_u32_e32 v1, v1, v3
	v_mov_b32_e32 v3, 1
	v_add_u32_e32 v2, v10, v2
	v_ashrrev_i16_sdwa v1, v3, sext(v1) dst_sel:DWORD dst_unused:UNUSED_PAD src0_sel:DWORD src1_sel:BYTE_0
	v_lshlrev_b32_e32 v4, 5, v9
	v_bfe_i32 v11, v1, 0, 16
	v_lshlrev_b32_e32 v1, 1, v2
	v_lshrrev_b32_e32 v5, 2, v2
	v_and_b32_e32 v6, 3, v10
	s_mov_b32 s7, 0x1fffe0
	v_and_b32_e32 v4, 32, v4
	v_and_b32_e32 v1, 24, v1
	v_and_b32_e32 v5, 4, v5
	v_and_or_b32 v6, v2, s7, v6
	v_or3_b32 v1, v6, v5, v1
	v_add_lshl_u32 v4, v4, v11, 1
	v_add_u32_e32 v0, 0x2000, v0
	v_lshl_add_u32 v146, v1, 11, v4
	v_ashrrev_i32_e32 v1, 31, v0
	v_lshrrev_b32_e32 v1, 22, v1
	v_add_u32_e32 v1, v0, v1
	v_ashrrev_i32_e32 v12, 10, v1
	v_mul_i32_i24_e32 v1, 0x400, v12
	v_sub_u32_e32 v0, v0, v1
	v_lshrrev_b32_e32 v1, 4, v0
	v_bitop3_b32 v0, v1, v0, 32 bitop3:0x6c
	v_lshl_add_u32 v144, v2, 11, v4
	v_ashrrev_i32_e32 v2, 31, v0
	v_lshrrev_b32_e32 v2, 26, v2
	v_add_u32_e32 v2, v0, v2
	v_ashrrev_i32_e32 v13, 6, v2
	v_and_b32_e32 v2, 0xffc0, v2
	v_sub_u32_e32 v0, v0, v2
	v_lshrrev_b16_e32 v2, 7, v0
	v_lshlrev_b32_e32 v1, 3, v12
	v_and_b32_e32 v2, 1, v2
	v_and_b32_e32 v1, -16, v1
	v_add_u16_e32 v0, v0, v2
	v_add_u32_e32 v1, v13, v1
	v_ashrrev_i16_sdwa v0, v3, sext(v0) dst_sel:DWORD dst_unused:UNUSED_PAD src0_sel:DWORD src1_sel:BYTE_0
	v_and_b32_e32 v3, 3, v13
	s_add_i32 s6, s9, s6
	v_and_or_b32 v3, v1, s7, v3
	s_ashr_i32 s7, s6, 31
	s_lshr_b32 s7, s7, 27
	s_add_i32 s7, s6, s7
	s_ashr_i32 s9, s7, 5
	s_andn2_b32 s7, s7, 31
	s_sub_i32 s6, s6, s7
	s_bfe_i32 s7, s6, 0x80000
	s_bfe_u32 s7, s7, 0x3000c
	s_add_i32 s7, s6, s7
	s_bfe_i32 s10, s7, 0x80000
	s_and_b32 s7, s7, 0xf8
	s_sub_i32 s6, s6, s7
	s_lshl_b32 s9, s9, 3
	s_sext_i32_i16 s10, s10
	s_sext_i32_i8 s6, s6
	s_lshr_b32 s14, s10, 3
	s_add_i32 s34, s9, s6
	s_ashr_i32 s35, s34, 31
	s_bfe_i64 s[10:11], s[14:15], 0x100000
	s_lshr_b32 s8, s86, 8
	s_lshl_b64 s[6:7], s[34:35], 19
	s_lshl_b64 s[10:11], s[10:11], 19
	s_add_u32 s38, s1, s10
	v_lshlrev_b32_e32 v4, 5, v12
	v_bfe_i32 v14, v0, 0, 16
	v_lshlrev_b32_e32 v0, 1, v1
	v_lshrrev_b32_e32 v2, 2, v1
	s_addc_u32 s39, s3, s11
	s_add_i32 s35, s33, 0
	v_and_b32_e32 v4, 32, v4
	v_and_b32_e32 v0, 24, v0
	v_and_b32_e32 v2, 4, v2
	s_add_i32 m0, s35, 0x10000
	v_or3_b32 v0, v3, v2, v0
	v_add_lshl_u32 v2, v4, v14, 1
	global_load_lds_dwordx4 v146, s[38:39]
	s_add_i32 m0, s35, 0x12000
	v_lshl_add_u32 v150, v0, 11, v2
	s_add_u32 s10, s38, 0x40000
	global_load_lds_dwordx4 v150, s[38:39]
	s_addc_u32 s11, s39, 0
	s_add_i32 m0, s35, 0x14000
	v_readlane_b32 s9, v254, 0
	global_load_lds_dwordx4 v146, s[10:11]
	s_add_i32 m0, s35, 0x16000
	s_add_u32 s36, s9, s6
	v_readlane_b32 s6, v254, 1
	s_addc_u32 s37, s6, s7
	s_add_i32 s42, s35, 0x2000
	global_load_lds_dwordx4 v150, s[10:11]
	s_mov_b32 m0, s35
	s_add_u32 s6, s36, 0x40000
	v_lshl_add_u32 v148, v1, 11, v2
	global_load_lds_dwordx4 v144, s[36:37]
	s_mov_b32 m0, s42
	s_addc_u32 s7, s37, 0
	s_add_i32 s43, s35, 0x4000
	global_load_lds_dwordx4 v148, s[36:37]
	s_mov_b32 m0, s43
	s_add_i32 s48, s35, 0x6000
	global_load_lds_dwordx4 v144, s[6:7]
	s_mov_b32 m0, s48
	v_mov_b32_e32 v147, 0
	global_load_lds_dwordx4 v148, s[6:7]
	s_load_dwordx2 s[6:7], s[4:5], 0x0
	v_mov_b32_e32 v151, v147
	v_mov_b32_e32 v145, v147
	v_mov_b32_e32 v149, v147
	s_cmp_eq_u32 s8, 1
	s_mov_b32 s9, 0
	v_lshl_add_u64 v[6:7], s[38:39], 0, v[146:147]
	v_lshl_add_u64 v[4:5], s[38:39], 0, v[150:151]
	v_lshl_add_u64 v[0:1], s[36:37], 0, v[144:145]
	s_cselect_b64 s[10:11], -1, 0
	s_cmp_lg_u32 s8, 1
	v_lshl_add_u64 v[2:3], s[36:37], 0, v[148:149]
	s_cbranch_scc1 .LBB0_907
	s_setprio 1
	s_barrier

; #define PG8_STAGE(bufoff, gbase, voff) do { _Pragma("unroll") for (int _i = 0; _i < 2; ++_i) \
;         __builtin_amdgcn_global_load_lds((const unsigned*)((const char*)(gbase) + (voff)[_i]), (LAS unsigned*)(lds + (bufoff) + ldsw + _i * 8192), 16, 0, 0); } while (0)
; #define PG8_LDA(dst, b, h) do { _Pragma("unroll") for (int m = 0; m < 4; ++m) _Pragma("unroll") for (int k = 0; k < 2; ++k) dst[m][k] = *(const LAS bf16x8*)(lds + PG8_SA(b, h) + aoff + m * 2048 + k * 1024); } while (0)
; #define PG8_LDB(dst, b, h) do { _Pragma("unroll") for (int n = 0; n < 2; ++n) _Pragma("unroll") for (int k = 0; k < 2; ++k) dst[n][k] = *(const LAS bf16x8*)(lds + PG8_SB(b, h) + boff + n * 2048 + k * 1024); } while (0)
; #define PG8_MMA(ai, bj, At, Bt) do { __builtin_amdgcn_s_setprio(1); _Pragma("unroll") for (int m = 0; m < 4; ++m) _Pragma("unroll") for (int n = 0; n < 2; ++n) _Pragma("unroll") for (int k = 0; k < 2; ++k) \
;         acc[ai][bj][m][n] = __builtin_amdgcn_mfma_f32_16x16x32_bf16(Bt[n][k], At[m][k], acc[ai][bj][m][n], 0, 0, 0); __builtin_amdgcn_s_setprio(0); } while (0)
; #define PG8_WAIT_V(n) asm volatile("s_waitcnt vmcnt(" #n ")" ::: "memory")
; #define PG8_WAIT_L(n) asm volatile("s_waitcnt lgkmcnt(" #n ")" ::: "memory")
; #define PG8_BAR __builtin_amdgcn_s_barrier()
; template <class Epi, bool ALIGN_EPI, int K, int LDA, int LDB>
; __device__ __forceinline__ void gemm_phase(LAS unsigned char* lds, const int wid, const Gemm g, const StaticOrder& S, const Epi& E) {
;     ...
;         for (int t = 0; t < nt; t += 2) {
;             const bool last = (t == nt - 2);
;             const char* a1 = cA + (size_t)(t + 1) * kstep;
;             const char* a2 = last ? nA : cA + (size_t)(t + 2) * kstep; const char* b2 = last ? nB : cB + (size_t)(t + 2) * kstep;
;             const char* a3 = a2 + kstep; const char* b3 = b2 + kstep;
;             PG8_LDB(B0, 0, 0); PG8_LDB(B1, 0, 1); PG8_SCHED; PG8_LDA(At, 0, 0); PG8_STAGE(PG8_SA(1, 1), a1 + hA, voffA);
;             PG8_WAIT_V(8); PG8_WAIT_L(0); PG8_BAR; PG8_MMA(0, 0, At, B0); PG8_MMA(0, 1, At, B1); PG8_BAR; PG8_SCHED;
;             PG8_LDA(At, 0, 1); PG8_STAGE(PG8_SB(0, 0), b2, voffB); PG8_STAGE(PG8_SB(0, 1), b2 + hB, voffB); PG8_STAGE(PG8_SA(0, 0), a2, voffA);
;             PG8_WAIT_V(8); PG8_WAIT_L(0); PG8_BAR; PG8_MMA(1, 0, At, B0); PG8_MMA(1, 1, At, B1); PG8_BAR; PG8_SCHED;
.LBB0_917:
	ds_read_b128 v[128:131], v163
	ds_read_b128 v[132:135], v163 offset:1024
	ds_read_b128 v[136:139], v163 offset:2048
	ds_read_b128 v[140:143], v163 offset:3072
	ds_read_b128 v[166:169], v164
	ds_read_b128 v[170:173], v164 offset:1024
	ds_read_b128 v[174:177], v164 offset:2048
	ds_read_b128 v[178:181], v164 offset:3072
	s_add_u32 s38, s36, 0xfffc0080
	s_addc_u32 s39, s37, -1
	s_cmp_eq_u32 s67, 12
	s_cselect_b32 s41, s27, s39
	s_cselect_b32 s40, s63, s38
	s_cselect_b32 s39, s25, s66
	s_cselect_b32 s38, s64, s65
	s_add_i32 m0, s35, 0xc000
	ds_read_b128 v[182:185], v165
	ds_read_b128 v[186:189], v165 offset:1024
	ds_read_b128 v[190:193], v165 offset:2048
	ds_read_b128 v[194:197], v165 offset:3072
	ds_read_b128 v[198:201], v165 offset:4096
	ds_read_b128 v[202:205], v165 offset:5120
	ds_read_b128 v[206:209], v165 offset:6144
	ds_read_b128 v[210:213], v165 offset:7168
	global_load_lds_dwordx4 v152, s[36:37]
	s_add_i32 m0, s35, 0xe000
	s_nop 0
	global_load_lds_dwordx4 v154, s[36:37]
	s_waitcnt vmcnt(8)
	s_waitcnt lgkmcnt(0)
	s_barrier
	s_waitcnt lgkmcnt(0)
	v_mfma_f32_16x16x32_bf16 v[124:127], v[128:131], v[182:185], v[124:127]
	v_mfma_f32_16x16x32_bf16 v[120:123], v[136:139], v[182:185], v[120:123]
	v_mfma_f32_16x16x32_bf16 v[108:111], v[128:131], v[190:193], v[108:111]
	v_mfma_f32_16x16x32_bf16 v[104:107], v[136:139], v[190:193], v[104:107]
	v_mfma_f32_16x16x32_bf16 v[92:95], v[128:131], v[198:201], v[92:95]
	v_mfma_f32_16x16x32_bf16 v[88:91], v[136:139], v[198:201], v[88:91]
	v_mfma_f32_16x16x32_bf16 v[76:79], v[128:131], v[206:209], v[76:79]
	v_mfma_f32_16x16x32_bf16 v[72:75], v[136:139], v[206:209], v[72:75]
	v_mfma_f32_16x16x32_bf16 v[124:127], v[132:135], v[186:189], v[124:127]
	v_mfma_f32_16x16x32_bf16 v[120:123], v[140:143], v[186:189], v[120:123]
	v_mfma_f32_16x16x32_bf16 v[108:111], v[132:135], v[194:197], v[108:111]
	v_mfma_f32_16x16x32_bf16 v[104:107], v[140:143], v[194:197], v[104:107]
	v_mfma_f32_16x16x32_bf16 v[92:95], v[132:135], v[202:205], v[92:95]
	v_mfma_f32_16x16x32_bf16 v[88:91], v[140:143], v[202:205], v[88:91]
	v_mfma_f32_16x16x32_bf16 v[76:79], v[132:135], v[210:213], v[76:79]
	v_mfma_f32_16x16x32_bf16 v[72:75], v[140:143], v[210:213], v[72:75]
	v_mfma_f32_16x16x32_bf16 v[116:119], v[166:169], v[182:185], v[116:119]
	v_mfma_f32_16x16x32_bf16 v[112:115], v[174:177], v[182:185], v[112:115]
	v_mfma_f32_16x16x32_bf16 v[100:103], v[166:169], v[190:193], v[100:103]
	v_mfma_f32_16x16x32_bf16 v[96:99], v[174:177], v[190:193], v[96:99]
	v_mfma_f32_16x16x32_bf16 v[84:87], v[166:169], v[198:201], v[84:87]
	v_mfma_f32_16x16x32_bf16 v[80:83], v[174:177], v[198:201], v[80:83]
	v_mfma_f32_16x16x32_bf16 v[68:71], v[166:169], v[206:209], v[68:71]
	v_mfma_f32_16x16x32_bf16 v[64:67], v[174:177], v[206:209], v[64:67]
	v_mfma_f32_16x16x32_bf16 v[116:119], v[170:173], v[186:189], v[116:119]
	v_mfma_f32_16x16x32_bf16 v[112:115], v[178:181], v[186:189], v[112:115]
	v_mfma_f32_16x16x32_bf16 v[100:103], v[170:173], v[194:197], v[100:103]
	v_mfma_f32_16x16x32_bf16 v[96:99], v[178:181], v[194:197], v[96:99]
	v_mfma_f32_16x16x32_bf16 v[84:87], v[170:173], v[202:205], v[84:87]
	v_mfma_f32_16x16x32_bf16 v[80:83], v[178:181], v[202:205], v[80:83]
	v_mfma_f32_16x16x32_bf16 v[68:71], v[170:173], v[210:213], v[68:71]
	v_mfma_f32_16x16x32_bf16 v[64:67], v[178:181], v[210:213], v[64:67]
	s_barrier
	s_add_u32 s98, s38, s12
	s_addc_u32 s99, s39, s13
	s_add_u32 s100, s40, s12
	s_addc_u32 s101, s41, s13
	s_add_i32 s52, s58, s33
	s_mov_b32 m0, s52
	ds_read_b128 v[182:185], v165 offset:16384
	ds_read_b128 v[186:189], v165 offset:17408
	ds_read_b128 v[190:193], v165 offset:18432
	ds_read_b128 v[194:197], v165 offset:19456
	ds_read_b128 v[198:201], v165 offset:20480
	ds_read_b128 v[202:205], v165 offset:21504
	ds_read_b128 v[206:209], v165 offset:22528
	ds_read_b128 v[210:213], v165 offset:23552
	global_load_lds_dwordx4 v146, s[38:39]
	s_add_i32 m0, s52, 0x2000
	s_add_u32 s68, s38, 0x40000
	s_addc_u32 s69, s39, 0
	s_add_i32 s52, s59, s33
	global_load_lds_dwordx4 v150, s[38:39]
	s_mov_b32 m0, s52
	s_nop 0
	global_load_lds_dwordx4 v146, s[68:69]
	s_add_i32 m0, s52, 0x2000
	s_nop 0
	global_load_lds_dwordx4 v150, s[68:69]
	s_mov_b32 m0, s35
	s_nop 0
	global_load_lds_dwordx4 v144, s[40:41]
	s_mov_b32 m0, s42
	s_nop 0
	global_load_lds_dwordx4 v148, s[40:41]
	s_waitcnt vmcnt(8)
	s_waitcnt lgkmcnt(0)
	s_barrier
	s_waitcnt lgkmcnt(0)
	v_mfma_f32_16x16x32_bf16 v[60:63], v[128:131], v[182:185], v[60:63]
	v_mfma_f32_16x16x32_bf16 v[56:59], v[136:139], v[182:185], v[56:59]
	v_mfma_f32_16x16x32_bf16 v[44:47], v[128:131], v[190:193], v[44:47]
	v_mfma_f32_16x16x32_bf16 v[40:43], v[136:139], v[190:193], v[40:43]
	v_mfma_f32_16x16x32_bf16 v[28:31], v[128:131], v[198:201], v[28:31]
	v_mfma_f32_16x16x32_bf16 v[24:27], v[136:139], v[198:201], v[24:27]
	v_mfma_f32_16x16x32_bf16 v[12:15], v[128:131], v[206:209], v[12:15]
	v_mfma_f32_16x16x32_bf16 v[8:11], v[136:139], v[206:209], v[8:11]
	v_mfma_f32_16x16x32_bf16 v[60:63], v[132:135], v[186:189], v[60:63]
	v_mfma_f32_16x16x32_bf16 v[56:59], v[140:143], v[186:189], v[56:59]
	v_mfma_f32_16x16x32_bf16 v[44:47], v[132:135], v[194:197], v[44:47]
	v_mfma_f32_16x16x32_bf16 v[40:43], v[140:143], v[194:197], v[40:43]
	v_mfma_f32_16x16x32_bf16 v[28:31], v[132:135], v[202:205], v[28:31]
	v_mfma_f32_16x16x32_bf16 v[24:27], v[140:143], v[202:205], v[24:27]
	v_mfma_f32_16x16x32_bf16 v[12:15], v[132:135], v[210:213], v[12:15]
	v_mfma_f32_16x16x32_bf16 v[8:11], v[140:143], v[210:213], v[8:11]
	v_mfma_f32_16x16x32_bf16 v[52:55], v[166:169], v[182:185], v[52:55]
	v_mfma_f32_16x16x32_bf16 v[48:51], v[174:177], v[182:185], v[48:51]
	v_mfma_f32_16x16x32_bf16 v[36:39], v[166:169], v[190:193], v[36:39]
	v_mfma_f32_16x16x32_bf16 v[32:35], v[174:177], v[190:193], v[32:35]
	v_mfma_f32_16x16x32_bf16 v[20:23], v[166:169], v[198:201], v[20:23]
	v_mfma_f32_16x16x32_bf16 v[16:19], v[174:177], v[198:201], v[16:19]
	v_mfma_f32_16x16x32_bf16 v[4:7], v[166:169], v[206:209], v[4:7]
	v_mfma_f32_16x16x32_bf16 v[0:3], v[174:177], v[206:209], v[0:3]
	v_mfma_f32_16x16x32_bf16 v[52:55], v[170:173], v[186:189], v[52:55]
	v_mfma_f32_16x16x32_bf16 v[48:51], v[178:181], v[186:189], v[48:51]
	v_mfma_f32_16x16x32_bf16 v[36:39], v[170:173], v[194:197], v[36:39]
	v_mfma_f32_16x16x32_bf16 v[32:35], v[178:181], v[194:197], v[32:35]
	v_mfma_f32_16x16x32_bf16 v[20:23], v[170:173], v[202:205], v[20:23]
	v_mfma_f32_16x16x32_bf16 v[16:19], v[178:181], v[202:205], v[16:19]
	v_mfma_f32_16x16x32_bf16 v[4:7], v[170:173], v[210:213], v[4:7]
	v_mfma_f32_16x16x32_bf16 v[0:3], v[178:181], v[210:213], v[0:3]
	s_barrier
; __device__ __forceinline__ int lane_id_() { int l; asm volatile("v_mbcnt_lo_u32_b32 %0, -1, 0\n\tv_mbcnt_hi_u32_b32 %0, -1, %0" : "=v"(l)); return l; }
; #define PG8_STAGE(bufoff, gbase, voff) do { _Pragma("unroll") for (int _i = 0; _i < 2; ++_i) \
;         __builtin_amdgcn_global_load_lds((const unsigned*)((const char*)(gbase) + (voff)[_i]), (LAS unsigned*)(lds + (bufoff) + ldsw + _i * 8192), 16, 0, 0); } while (0)
; #define PG8_LDA(dst, b, h) do { _Pragma("unroll") for (int m = 0; m < 4; ++m) _Pragma("unroll") for (int k = 0; k < 2; ++k) dst[m][k] = *(const LAS bf16x8*)(lds + PG8_SA(b, h) + aoff + m * 2048 + k * 1024); } while (0)
; #define PG8_LDB(dst, b, h) do { _Pragma("unroll") for (int n = 0; n < 2; ++n) _Pragma("unroll") for (int k = 0; k < 2; ++k) dst[n][k] = *(const LAS bf16x8*)(lds + PG8_SB(b, h) + boff + n * 2048 + k * 1024); } while (0)
; #define PG8_MMA(ai, bj, At, Bt) do { __builtin_amdgcn_s_setprio(1); _Pragma("unroll") for (int m = 0; m < 4; ++m) _Pragma("unroll") for (int n = 0; n < 2; ++n) _Pragma("unroll") for (int k = 0; k < 2; ++k) \
;         acc[ai][bj][m][n] = __builtin_amdgcn_mfma_f32_16x16x32_bf16(Bt[n][k], At[m][k], acc[ai][bj][m][n], 0, 0, 0); __builtin_amdgcn_s_setprio(0); } while (0)
; #define PG8_WAIT_V(n) asm volatile("s_waitcnt vmcnt(" #n ")" ::: "memory")
; #define PG8_WAIT_L(n) asm volatile("s_waitcnt lgkmcnt(" #n ")" ::: "memory")
; #define PG8_BAR __builtin_amdgcn_s_barrier()
; #define PG8_SCHED __builtin_amdgcn_sched_barrier(0)
; template <class Epi, bool ALIGN_EPI, int K, int LDA, int LDB>
; __device__ __forceinline__ void gemm_phase(LAS unsigned char* lds, const int wid, const Gemm g, const StaticOrder& S, const Epi& E) {
;     ...
;             PG8_LDB(B0, 1, 0); PG8_LDB(B1, 1, 1); PG8_SCHED; PG8_LDA(At, 1, 0); PG8_STAGE(PG8_SA(0, 1), a2 + hA, voffA);
;             PG8_WAIT_V(8); PG8_WAIT_L(0); PG8_BAR; PG8_MMA(0, 0, At, B0); PG8_MMA(0, 1, At, B1); PG8_BAR; PG8_SCHED;
;             PG8_LDA(At, 1, 1); PG8_STAGE(PG8_SB(1, 0), b3, voffB); PG8_STAGE(PG8_SB(1, 1), b3 + hB, voffB); PG8_STAGE(PG8_SA(1, 0), a3, voffA);
;             PG8_WAIT_V(8); PG8_WAIT_L(0); PG8_BAR; PG8_MMA(1, 0, At, B0); PG8_MMA(1, 1, At, B1); PG8_BAR; PG8_SCHED;
;         }
;         if constexpr (ALIGN_EPI) { if (wr == 0) PG8_BAR; }
;         { const int l2 = lane_id_(); E(acc, cur, wid >> 2, wid & 3, l2 & 15, l2 >> 4); }
;         if (!has_next) break;
	s_add_i32 s52, 0, 0x18000
	s_add_i32 s53, 0, 0x1c000
	v_add_u32_e32 v140, s52, v162
	v_add_u32_e32 v178, s53, v162
	ds_read_b128 v[128:131], v140
	ds_read_b128 v[132:135], v140 offset:1024
	ds_read_b128 v[136:139], v140 offset:2048
	ds_read_b128 v[140:143], v140 offset:3072
	ds_read_b128 v[166:169], v178
	ds_read_b128 v[170:173], v178 offset:1024
	ds_read_b128 v[174:177], v178 offset:2048
	ds_read_b128 v[178:181], v178 offset:3072
	s_add_u32 s40, s40, 0x40000
	s_addc_u32 s41, s41, 0
	s_mov_b32 m0, s43
	ds_read_b128 v[182:185], v165 offset:32768
	ds_read_b128 v[186:189], v165 offset:33792
	ds_read_b128 v[190:193], v165 offset:34816
	ds_read_b128 v[194:197], v165 offset:35840
	ds_read_b128 v[198:201], v165 offset:36864
	ds_read_b128 v[202:205], v165 offset:37888
	ds_read_b128 v[206:209], v165 offset:38912
	ds_read_b128 v[210:213], v165 offset:39936
	global_load_lds_dwordx4 v144, s[40:41]
	s_mov_b32 m0, s48
	s_nop 0
	global_load_lds_dwordx4 v148, s[40:41]
	s_waitcnt vmcnt(8)
	s_waitcnt lgkmcnt(0)
	s_barrier
	s_waitcnt lgkmcnt(0)
	v_mfma_f32_16x16x32_bf16 v[124:127], v[128:131], v[182:185], v[124:127]
	v_mfma_f32_16x16x32_bf16 v[120:123], v[136:139], v[182:185], v[120:123]
	v_mfma_f32_16x16x32_bf16 v[108:111], v[128:131], v[190:193], v[108:111]
	v_mfma_f32_16x16x32_bf16 v[104:107], v[136:139], v[190:193], v[104:107]
	v_mfma_f32_16x16x32_bf16 v[92:95], v[128:131], v[198:201], v[92:95]
	v_mfma_f32_16x16x32_bf16 v[88:91], v[136:139], v[198:201], v[88:91]
	v_mfma_f32_16x16x32_bf16 v[76:79], v[128:131], v[206:209], v[76:79]
	v_mfma_f32_16x16x32_bf16 v[72:75], v[136:139], v[206:209], v[72:75]
	v_mfma_f32_16x16x32_bf16 v[124:127], v[132:135], v[186:189], v[124:127]
	v_mfma_f32_16x16x32_bf16 v[120:123], v[140:143], v[186:189], v[120:123]
	v_mfma_f32_16x16x32_bf16 v[108:111], v[132:135], v[194:197], v[108:111]
	v_mfma_f32_16x16x32_bf16 v[104:107], v[140:143], v[194:197], v[104:107]
	v_mfma_f32_16x16x32_bf16 v[92:95], v[132:135], v[202:205], v[92:95]
	v_mfma_f32_16x16x32_bf16 v[88:91], v[140:143], v[202:205], v[88:91]
	v_mfma_f32_16x16x32_bf16 v[76:79], v[132:135], v[210:213], v[76:79]
	v_mfma_f32_16x16x32_bf16 v[72:75], v[140:143], v[210:213], v[72:75]
	v_mfma_f32_16x16x32_bf16 v[116:119], v[166:169], v[182:185], v[116:119]
	v_mfma_f32_16x16x32_bf16 v[112:115], v[174:177], v[182:185], v[112:115]
	v_mfma_f32_16x16x32_bf16 v[100:103], v[166:169], v[190:193], v[100:103]
	v_mfma_f32_16x16x32_bf16 v[96:99], v[174:177], v[190:193], v[96:99]
	v_mfma_f32_16x16x32_bf16 v[84:87], v[166:169], v[198:201], v[84:87]
	v_mfma_f32_16x16x32_bf16 v[80:83], v[174:177], v[198:201], v[80:83]
	v_mfma_f32_16x16x32_bf16 v[68:71], v[166:169], v[206:209], v[68:71]
	v_mfma_f32_16x16x32_bf16 v[64:67], v[174:177], v[206:209], v[64:67]
	v_mfma_f32_16x16x32_bf16 v[116:119], v[170:173], v[186:189], v[116:119]
	v_mfma_f32_16x16x32_bf16 v[112:115], v[178:181], v[186:189], v[112:115]
	v_mfma_f32_16x16x32_bf16 v[100:103], v[170:173], v[194:197], v[100:103]
	v_mfma_f32_16x16x32_bf16 v[96:99], v[178:181], v[194:197], v[96:99]
	v_mfma_f32_16x16x32_bf16 v[84:87], v[170:173], v[202:205], v[84:87]
	v_mfma_f32_16x16x32_bf16 v[80:83], v[178:181], v[202:205], v[80:83]
	v_mfma_f32_16x16x32_bf16 v[68:71], v[170:173], v[210:213], v[68:71]
	v_mfma_f32_16x16x32_bf16 v[64:67], v[178:181], v[210:213], v[64:67]
	s_barrier
	s_add_i32 s40, s52, s33
	s_mov_b32 m0, s40
	ds_read_b128 v[182:185], v165 offset:49152
	ds_read_b128 v[186:189], v165 offset:50176
	ds_read_b128 v[190:193], v165 offset:51200
	ds_read_b128 v[194:197], v165 offset:52224
	ds_read_b128 v[198:201], v165 offset:53248
	ds_read_b128 v[202:205], v165 offset:54272
	ds_read_b128 v[206:209], v165 offset:55296
	ds_read_b128 v[210:213], v165 offset:56320
	global_load_lds_dwordx4 v146, s[98:99]
	s_add_i32 m0, s40, 0x2000
	s_add_u32 s38, s38, 0x40080
	s_addc_u32 s39, s39, 0
	s_add_i32 s40, s53, s33
	global_load_lds_dwordx4 v150, s[98:99]
	s_mov_b32 m0, s40
	s_nop 0
	global_load_lds_dwordx4 v146, s[38:39]
	s_add_i32 m0, s40, 0x2000
	s_nop 0
	global_load_lds_dwordx4 v150, s[38:39]
	s_mov_b32 m0, s55
	s_nop 0
	global_load_lds_dwordx4 v144, s[100:101]
	s_mov_b32 m0, s56
	s_nop 0
	global_load_lds_dwordx4 v148, s[100:101]
	s_waitcnt vmcnt(8)
	s_waitcnt lgkmcnt(0)
	s_barrier
	s_waitcnt lgkmcnt(0)
	v_mfma_f32_16x16x32_bf16 v[60:63], v[128:131], v[182:185], v[60:63]
	v_mfma_f32_16x16x32_bf16 v[56:59], v[136:139], v[182:185], v[56:59]
	v_mfma_f32_16x16x32_bf16 v[44:47], v[128:131], v[190:193], v[44:47]
	v_mfma_f32_16x16x32_bf16 v[40:43], v[136:139], v[190:193], v[40:43]
	v_mfma_f32_16x16x32_bf16 v[28:31], v[128:131], v[198:201], v[28:31]
	v_mfma_f32_16x16x32_bf16 v[24:27], v[136:139], v[198:201], v[24:27]
	v_mfma_f32_16x16x32_bf16 v[12:15], v[128:131], v[206:209], v[12:15]
	v_mfma_f32_16x16x32_bf16 v[8:11], v[136:139], v[206:209], v[8:11]
	v_mfma_f32_16x16x32_bf16 v[60:63], v[132:135], v[186:189], v[60:63]
	v_mfma_f32_16x16x32_bf16 v[56:59], v[140:143], v[186:189], v[56:59]
	v_mfma_f32_16x16x32_bf16 v[44:47], v[132:135], v[194:197], v[44:47]
	v_mfma_f32_16x16x32_bf16 v[40:43], v[140:143], v[194:197], v[40:43]
	v_mfma_f32_16x16x32_bf16 v[28:31], v[132:135], v[202:205], v[28:31]
	v_mfma_f32_16x16x32_bf16 v[24:27], v[140:143], v[202:205], v[24:27]
	v_mfma_f32_16x16x32_bf16 v[12:15], v[132:135], v[210:213], v[12:15]
	v_mfma_f32_16x16x32_bf16 v[8:11], v[140:143], v[210:213], v[8:11]
	v_mfma_f32_16x16x32_bf16 v[52:55], v[166:169], v[182:185], v[52:55]
	v_mfma_f32_16x16x32_bf16 v[48:51], v[174:177], v[182:185], v[48:51]
	v_mfma_f32_16x16x32_bf16 v[36:39], v[166:169], v[190:193], v[36:39]
	v_mfma_f32_16x16x32_bf16 v[32:35], v[174:177], v[190:193], v[32:35]
	v_mfma_f32_16x16x32_bf16 v[20:23], v[166:169], v[198:201], v[20:23]
	v_mfma_f32_16x16x32_bf16 v[16:19], v[174:177], v[198:201], v[16:19]
	v_mfma_f32_16x16x32_bf16 v[4:7], v[166:169], v[206:209], v[4:7]
	v_mfma_f32_16x16x32_bf16 v[0:3], v[174:177], v[206:209], v[0:3]
	v_mfma_f32_16x16x32_bf16 v[52:55], v[170:173], v[186:189], v[52:55]
	v_mfma_f32_16x16x32_bf16 v[48:51], v[178:181], v[186:189], v[48:51]
	v_mfma_f32_16x16x32_bf16 v[36:39], v[170:173], v[194:197], v[36:39]
	v_mfma_f32_16x16x32_bf16 v[32:35], v[178:181], v[194:197], v[32:35]
	v_mfma_f32_16x16x32_bf16 v[20:23], v[170:173], v[202:205], v[20:23]
	v_mfma_f32_16x16x32_bf16 v[16:19], v[178:181], v[202:205], v[16:19]
	v_mfma_f32_16x16x32_bf16 v[4:7], v[170:173], v[210:213], v[4:7]
	v_mfma_f32_16x16x32_bf16 v[0:3], v[178:181], v[210:213], v[0:3]
	s_barrier
	s_add_i32 s67, s67, 2
	s_add_u32 s36, s36, 0x100
	s_addc_u32 s37, s37, 0
	s_add_u32 s65, s65, 0x100
	s_addc_u32 s66, s66, 0
	s_cmp_gt_u32 s67, 13
	s_cbranch_scc0 .LBB0_917
	s_and_b64 vcc, exec, s[14:15]
	s_cbranch_vccz .LBB0_920
	s_barrier

;     __device__ bool next(int i, Unit& u) const {
;         const long L = (long)i * G + c; if (L >= nwg) return false;
;         int wgid = (int)L; { const int q = nwg / NXCD, r = nwg % NXCD, xcd = wgid % NXCD, off = wgid / NXCD; wgid = (xcd < r ? xcd * (q + 1) : r * (q + 1) + (xcd - r) * q) + off; }
;         const int nig = WGM * nN, gid = wgid / nig, fm = gid * WGM, gsz = (nM - fm) < WGM ? (nM - fm) : WGM;
;         u.pm = fm + ((wgid % nig) % gsz); u.pn = (wgid % nig) / gsz; return true;
;     }
; template <class Epi, bool ALIGN_EPI, int K, int LDA, int LDB>
; __device__ __forceinline__ void gemm_phase(LAS unsigned char* lds, const int wid, const Gemm g, const StaticOrder& S, const Epi& E) {
;     const int lane = lane_id_(), tid = wid * 64 + lane, wr = wid >> 2, wc = wid & 3, fr = lane & 15, fq = lane >> 4;
;     constexpr int nt = K / BK;
;     unsigned voffA[2], voffB[2];
; #pragma unroll
;     for (int i = 0; i < 2; ++i) { int R, C; stage_rc(tid * 16 + i * 8192, R, C); const int Rb = Epi::PERM ? ((R & ~31) + perm32(R & 31)) : R;
;         voffA[i] = (unsigned)(R * LDA + C) * 2u; voffB[i] = (unsigned)(Rb * LDB + C) * 2u; }
;     constexpr size_t kstep = (size_t)(BK * 2);
;     constexpr size_t hA = (size_t)HALF * LDA * 2, hB = (size_t)HALF * LDB * 2;
;     constexpr size_t tA = 2 * hA, tB = 2 * hB;
;     const unsigned ldsw = (unsigned)wid * 1024u;
;     const int aoff = lds_byte(wr * 64 + fr, fq * 8), boff = lds_byte(wc * 32 + fr, fq * 8);
;     ...
;     Unit cur, nxt; int ui = 0;
;     if (!S.next(0, cur)) return;
;     f32x4 acc[2][2][4][2];
; #pragma unroll
;     for (int a = 0; a < 2; ++a)
; #pragma unroll
;         for (int b = 0; b < 2; ++b)
; #pragma unroll
;             for (int m = 0; m < 4; ++m)
; #pragma unroll
;                 for (int n = 0; n < 2; ++n) acc[a][b][m][n] = (f32x4){0.f, 0.f, 0.f, 0.f};
;     bf16x8 At[4][2], B0[2][2], B1[2][2];
;     const char* cA = (const char*)g.A + (size_t)cur.pm * tA; const char* cB = (const char*)g.Bt + (size_t)cur.pn * tB;
;     PG8_STAGE(PG8_SB(0, 0), cB, voffB); PG8_STAGE(PG8_SB(0, 1), cB + hB, voffB); PG8_STAGE(PG8_SA(0, 0), cA, voffA); PG8_STAGE(PG8_SA(0, 1), cA + hA, voffA);
;     if (wr == 1) PG8_BAR;
;     PG8_WAIT_V(2); PG8_BAR;
;     PG8_STAGE(PG8_SB(1, 0), cB + kstep, voffB); PG8_STAGE(PG8_SA(1, 0), cA + kstep, voffA); PG8_STAGE(PG8_SB(1, 1), cB + hB + kstep, voffB);
.LBB0_1042:
	s_cmp_lt_i32 s84, 9
	s_cselect_b64 s[0:1], -1, 0
	s_cmp_gt_i32 s85, 8
	s_cselect_b64 s[4:5], -1, 0
	s_and_b64 s[0:1], s[0:1], s[4:5]
	s_andn2_b64 vcc, exec, s[0:1]
	s_cbranch_vccnz .LBB0_1115
	s_mov_b64 s[0:1], s[88:89]
	s_cmpk_lt_i32 s2, 0x1600
	v_mbcnt_lo_u32_b32 v8, -1, 0
	v_mbcnt_hi_u32_b32 v8, -1, v8
	s_cbranch_scc0 .LBB0_1059
	s_add_u32 s0, s46, 0x1800000
	s_addc_u32 s1, s47, 0
	s_lshr_b32 s5, s86, 8
	s_lshl_b32 s3, s50, 10
	s_cmp_eq_u32 s5, 1
	s_cselect_b64 s[6:7], -1, 0
	s_ashr_i32 s28, s2, 31
	s_lshr_b32 s4, s28, 29
	s_add_i32 s4, s2, s4
	s_ashr_i32 s8, s4, 3
	s_and_b32 s4, s4, -8
	s_sub_i32 s4, s2, s4
	s_cmp_lt_i32 s4, 0
	s_movk_i32 s29, 0x2c1
	s_cselect_b32 s9, s29, 0x2c0
	s_mul_i32 s4, s4, s9
	s_add_i32 s4, s4, s8
	s_mul_hi_i32 s8, s4, 0x2e8ba2e9
	s_lshr_b32 s9, s8, 31
	s_ashr_i32 s8, s8, 5
	s_add_i32 s8, s8, s9
	s_lshl_b32 s9, s8, 3
	s_mulk_i32 s8, 0xb0
	s_waitcnt lgkmcnt(0)
	v_lshl_add_u32 v0, v8, 4, s3
	s_sub_i32 s8, s4, s8
	v_add_u32_e32 v1, 0x2000, v0
	s_sext_i32_i16 s4, s8
	v_ashrrev_i32_e32 v2, 31, v1
	s_bfe_u32 s4, s4, 0x3001c
	v_lshrrev_b32_e32 v2, 22, v2
	s_add_i32 s10, s8, s4
	v_add_u32_e32 v2, v1, v2
	s_sext_i32_i16 s4, s10
	s_and_b32 s10, s10, 0xfff8
	v_ashrrev_i32_e32 v9, 10, v2
	s_sub_i32 s8, s8, s10
	v_mul_i32_i24_e32 v2, 0x400, v9
	s_sext_i32_i16 s8, s8
	v_sub_u32_e32 v1, v1, v2
	s_lshr_b32 s4, s4, 3
	s_add_i32 s20, s9, s8
	v_lshrrev_b32_e32 v2, 4, v1
	s_ashr_i32 s21, s20, 31
	s_bfe_i64 s[10:11], s[4:5], 0x100000
	v_bitop3_b32 v1, v2, v1, 32 bitop3:0x6c
	s_lshl_b64 s[8:9], s[20:21], 19
	s_lshl_b64 s[10:11], s[10:11], 19
	v_ashrrev_i32_e32 v2, 31, v1
	s_add_u32 s24, s0, s10
	v_lshrrev_b32_e32 v2, 26, v2
	s_addc_u32 s25, s1, s11
	s_add_i32 s21, s3, 0
	v_add_u32_e32 v2, v1, v2
	s_add_i32 m0, s21, 0x10000
	s_add_i32 s12, s21, 0x12000
	v_ashrrev_i32_e32 v10, 6, v2
	v_lshlrev_b32_e32 v3, 3, v9
	v_and_b32_e32 v2, 0xffc0, v2
	s_add_u32 s10, s24, 0x40000
	v_and_b32_e32 v3, -16, v3
	v_sub_u32_e32 v1, v1, v2
	s_addc_u32 s11, s25, 0
	s_add_i32 s13, s21, 0x14000
	s_add_i32 s14, s21, 0x16000
	v_readlane_b32 s15, v254, 0
	v_add_u32_e32 v3, v10, v3
	v_lshrrev_b16_e32 v2, 7, v1
	s_add_u32 s22, s15, s8
	v_and_b32_e32 v4, 3, v10
	s_mov_b32 s15, 0x1fffe0
	v_lshrrev_b32_e32 v5, 2, v3
	v_lshlrev_b32_e32 v6, 1, v3
	v_and_b32_e32 v2, 1, v2
	v_and_or_b32 v4, v3, s15, v4
	v_and_b32_e32 v5, 4, v5
	v_and_b32_e32 v6, 24, v6
	v_add_u16_e32 v1, v1, v2
	v_mov_b32_e32 v2, 1
	v_or3_b32 v4, v4, v5, v6
	v_lshlrev_b32_e32 v5, 5, v9
	v_ashrrev_i16_sdwa v1, v2, sext(v1) dst_sel:DWORD dst_unused:UNUSED_PAD src0_sel:DWORD src1_sel:BYTE_0
	v_and_b32_e32 v5, 32, v5
	v_bfe_i32 v11, v1, 0, 16
	v_add_lshl_u32 v1, v5, v11, 1
	v_lshl_add_u32 v128, v4, 11, v1
	v_lshl_add_u32 v130, v3, 11, v1
	v_ashrrev_i32_e32 v1, 31, v0
	v_lshrrev_b32_e32 v1, 22, v1
	v_add_u32_e32 v1, v0, v1
	v_ashrrev_i32_e32 v12, 10, v1
	v_mul_i32_i24_e32 v1, 0x400, v12
	v_sub_u32_e32 v0, v0, v1
	v_lshrrev_b32_e32 v1, 4, v0
	v_bitop3_b32 v0, v1, v0, 32 bitop3:0x6c
	v_ashrrev_i32_e32 v1, 31, v0
	v_lshrrev_b32_e32 v1, 26, v1
	v_add_u32_e32 v1, v0, v1
	v_lshlrev_b32_e32 v3, 3, v12
	v_ashrrev_i32_e32 v13, 6, v1
	v_and_b32_e32 v3, -16, v3
	v_add_u32_e32 v3, v13, v3
	v_and_b32_e32 v4, 3, v13
	v_lshrrev_b32_e32 v5, 2, v3
	v_lshlrev_b32_e32 v6, 1, v3
	v_and_b32_e32 v1, 0xc0, v1
	v_and_or_b32 v4, v3, s15, v4
	v_and_b32_e32 v5, 4, v5
	v_and_b32_e32 v6, 24, v6
	v_sub_u32_e32 v0, v0, v1
	v_or3_b32 v4, v4, v5, v6
	v_lshlrev_b32_e32 v5, 5, v12
	v_ashrrev_i16_sdwa v0, v2, sext(v0) dst_sel:DWORD dst_unused:UNUSED_PAD src0_sel:DWORD src1_sel:BYTE_0
	v_and_b32_e32 v5, 32, v5
	v_bfe_i32 v14, v0, 0, 16
	v_add_lshl_u32 v0, v5, v14, 1
	v_lshl_add_u32 v132, v4, 11, v0
	global_load_lds_dwordx4 v132, s[24:25]
	s_mov_b32 m0, s12
	v_readlane_b32 s8, v254, 1
	global_load_lds_dwordx4 v128, s[24:25]
	s_mov_b32 m0, s13
	s_addc_u32 s23, s8, s9
	s_add_i32 s30, s21, 0x2000
	global_load_lds_dwordx4 v132, s[10:11]
	s_mov_b32 m0, s14
	s_add_u32 s8, s22, 0x40000
	v_lshl_add_u32 v134, v3, 11, v0
	global_load_lds_dwordx4 v128, s[10:11]
	s_mov_b32 m0, s21
	s_addc_u32 s9, s23, 0
	s_add_i32 s31, s21, 0x4000
	global_load_lds_dwordx4 v134, s[22:23]
	s_mov_b32 m0, s30
	s_add_i32 s33, s21, 0x6000
	global_load_lds_dwordx4 v130, s[22:23]
	s_mov_b32 m0, s31
	v_mov_b32_e32 v133, 0
	global_load_lds_dwordx4 v134, s[8:9]
	s_mov_b32 m0, s33
	v_mov_b32_e32 v129, v133
	global_load_lds_dwordx4 v130, s[8:9]
	v_mov_b32_e32 v135, v133
	v_mov_b32_e32 v131, v133
	s_mov_b32 s34, 0
	s_cmp_lg_u32 s5, 1
	v_lshl_add_u64 v[6:7], s[24:25], 0, v[132:133]
	v_lshl_add_u64 v[4:5], s[24:25], 0, v[128:129]
	v_lshl_add_u64 v[2:3], s[22:23], 0, v[134:135]
	v_lshl_add_u64 v[0:1], s[22:23], 0, v[130:131]
	s_cbranch_scc1 .LBB0_1046
	s_setprio 1
	s_barrier

; #define PG8_STAGE(bufoff, gbase, voff) do { _Pragma("unroll") for (int _i = 0; _i < 2; ++_i) \
;         __builtin_amdgcn_global_load_lds((const unsigned*)((const char*)(gbase) + (voff)[_i]), (LAS unsigned*)(lds + (bufoff) + ldsw + _i * 8192), 16, 0, 0); } while (0)
; #define PG8_LDA(dst, b, h) do { _Pragma("unroll") for (int m = 0; m < 4; ++m) _Pragma("unroll") for (int k = 0; k < 2; ++k) dst[m][k] = *(const LAS bf16x8*)(lds + PG8_SA(b, h) + aoff + m * 2048 + k * 1024); } while (0)
; #define PG8_LDB(dst, b, h) do { _Pragma("unroll") for (int n = 0; n < 2; ++n) _Pragma("unroll") for (int k = 0; k < 2; ++k) dst[n][k] = *(const LAS bf16x8*)(lds + PG8_SB(b, h) + boff + n * 2048 + k * 1024); } while (0)
; #define PG8_MMA(ai, bj, At, Bt) do { __builtin_amdgcn_s_setprio(1); _Pragma("unroll") for (int m = 0; m < 4; ++m) _Pragma("unroll") for (int n = 0; n < 2; ++n) _Pragma("unroll") for (int k = 0; k < 2; ++k) \
;         acc[ai][bj][m][n] = __builtin_amdgcn_mfma_f32_16x16x32_bf16(Bt[n][k], At[m][k], acc[ai][bj][m][n], 0, 0, 0); __builtin_amdgcn_s_setprio(0); } while (0)
; #define PG8_WAIT_V(n) asm volatile("s_waitcnt vmcnt(" #n ")" ::: "memory")
; #define PG8_WAIT_L(n) asm volatile("s_waitcnt lgkmcnt(" #n ")" ::: "memory")
; #define PG8_BAR __builtin_amdgcn_s_barrier()
; template <class Epi, bool ALIGN_EPI, int K, int LDA, int LDB>
; __device__ __forceinline__ void gemm_phase(LAS unsigned char* lds, const int wid, const Gemm g, const StaticOrder& S, const Epi& E) {
;     ...
;         for (int t = 0; t < nt; t += 2) {
;             const bool last = (t == nt - 2);
;             const char* a1 = cA + (size_t)(t + 1) * kstep;
;             const char* a2 = last ? nA : cA + (size_t)(t + 2) * kstep; const char* b2 = last ? nB : cB + (size_t)(t + 2) * kstep;
;             const char* a3 = a2 + kstep; const char* b3 = b2 + kstep;
;             PG8_LDB(B0, 0, 0); PG8_LDB(B1, 0, 1); PG8_SCHED; PG8_LDA(At, 0, 0); PG8_STAGE(PG8_SA(1, 1), a1 + hA, voffA);
;             PG8_WAIT_V(8); PG8_WAIT_L(0); PG8_BAR; PG8_MMA(0, 0, At, B0); PG8_MMA(0, 1, At, B1); PG8_BAR; PG8_SCHED;
;             PG8_LDA(At, 0, 1); PG8_STAGE(PG8_SB(0, 0), b2, voffB); PG8_STAGE(PG8_SB(0, 1), b2 + hB, voffB); PG8_STAGE(PG8_SA(0, 0), a2, voffA);
;             PG8_WAIT_V(8); PG8_WAIT_L(0); PG8_BAR; PG8_MMA(1, 0, At, B0); PG8_MMA(1, 1, At, B1); PG8_BAR; PG8_SCHED;
.LBB0_1052:
	ds_read_b128 v[148:151], v145
	ds_read_b128 v[152:155], v145 offset:1024
	ds_read_b128 v[156:159], v145 offset:2048
	ds_read_b128 v[160:163], v145 offset:3072
	ds_read_b128 v[164:167], v146
	ds_read_b128 v[168:171], v146 offset:1024
	ds_read_b128 v[172:175], v146 offset:2048
	ds_read_b128 v[176:179], v146 offset:3072
	s_add_u32 s24, s22, 0xfffc0080
	s_addc_u32 s25, s23, -1
	s_cmp_eq_u32 s55, 12
	s_cselect_b32 s27, s15, s25
	s_cselect_b32 s26, s48, s24
	s_cselect_b32 s25, s13, s54
	s_cselect_b32 s24, s49, s51
	s_add_i32 m0, s21, 0xc000
	ds_read_b128 v[180:183], v147
	ds_read_b128 v[184:187], v147 offset:1024
	ds_read_b128 v[188:191], v147 offset:2048
	ds_read_b128 v[192:195], v147 offset:3072
	ds_read_b128 v[196:199], v147 offset:4096
	ds_read_b128 v[200:203], v147 offset:5120
	ds_read_b128 v[204:207], v147 offset:6144
	ds_read_b128 v[208:211], v147 offset:7168
	global_load_lds_dwordx4 v136, s[22:23]
	s_add_i32 m0, s21, 0xe000
	s_nop 0
	global_load_lds_dwordx4 v138, s[22:23]
	s_waitcnt vmcnt(8)
	s_waitcnt lgkmcnt(0)
	s_barrier
	s_waitcnt lgkmcnt(0)
	v_mfma_f32_16x16x32_bf16 v[124:127], v[148:151], v[180:183], v[124:127]
	v_mfma_f32_16x16x32_bf16 v[120:123], v[156:159], v[180:183], v[120:123]
	v_mfma_f32_16x16x32_bf16 v[108:111], v[148:151], v[188:191], v[108:111]
	v_mfma_f32_16x16x32_bf16 v[104:107], v[156:159], v[188:191], v[104:107]
	v_mfma_f32_16x16x32_bf16 v[92:95], v[148:151], v[196:199], v[92:95]
	v_mfma_f32_16x16x32_bf16 v[88:91], v[156:159], v[196:199], v[88:91]
	v_mfma_f32_16x16x32_bf16 v[76:79], v[148:151], v[204:207], v[76:79]
	v_mfma_f32_16x16x32_bf16 v[72:75], v[156:159], v[204:207], v[72:75]
	v_mfma_f32_16x16x32_bf16 v[124:127], v[152:155], v[184:187], v[124:127]
	v_mfma_f32_16x16x32_bf16 v[120:123], v[160:163], v[184:187], v[120:123]
	v_mfma_f32_16x16x32_bf16 v[108:111], v[152:155], v[192:195], v[108:111]
	v_mfma_f32_16x16x32_bf16 v[104:107], v[160:163], v[192:195], v[104:107]
	v_mfma_f32_16x16x32_bf16 v[92:95], v[152:155], v[200:203], v[92:95]
	v_mfma_f32_16x16x32_bf16 v[88:91], v[160:163], v[200:203], v[88:91]
	v_mfma_f32_16x16x32_bf16 v[76:79], v[152:155], v[208:211], v[76:79]
	v_mfma_f32_16x16x32_bf16 v[72:75], v[160:163], v[208:211], v[72:75]
	v_mfma_f32_16x16x32_bf16 v[116:119], v[164:167], v[180:183], v[116:119]
	v_mfma_f32_16x16x32_bf16 v[112:115], v[172:175], v[180:183], v[112:115]
	v_mfma_f32_16x16x32_bf16 v[100:103], v[164:167], v[188:191], v[100:103]
	v_mfma_f32_16x16x32_bf16 v[96:99], v[172:175], v[188:191], v[96:99]
	v_mfma_f32_16x16x32_bf16 v[84:87], v[164:167], v[196:199], v[84:87]
	v_mfma_f32_16x16x32_bf16 v[80:83], v[172:175], v[196:199], v[80:83]
	v_mfma_f32_16x16x32_bf16 v[68:71], v[164:167], v[204:207], v[68:71]
	v_mfma_f32_16x16x32_bf16 v[64:67], v[172:175], v[204:207], v[64:67]
	v_mfma_f32_16x16x32_bf16 v[116:119], v[168:171], v[184:187], v[116:119]
	v_mfma_f32_16x16x32_bf16 v[112:115], v[176:179], v[184:187], v[112:115]
	v_mfma_f32_16x16x32_bf16 v[100:103], v[168:171], v[192:195], v[100:103]
	v_mfma_f32_16x16x32_bf16 v[96:99], v[176:179], v[192:195], v[96:99]
	v_mfma_f32_16x16x32_bf16 v[84:87], v[168:171], v[200:203], v[84:87]
	v_mfma_f32_16x16x32_bf16 v[80:83], v[176:179], v[200:203], v[80:83]
	v_mfma_f32_16x16x32_bf16 v[68:71], v[168:171], v[208:211], v[68:71]
	v_mfma_f32_16x16x32_bf16 v[64:67], v[176:179], v[208:211], v[64:67]
	s_barrier
	s_add_u32 s98, s24, s10
	s_addc_u32 s99, s25, s11
	s_add_u32 s100, s26, s10
	s_addc_u32 s101, s27, s11
	s_add_i32 s52, s40, s3
	s_mov_b32 m0, s52
	ds_read_b128 v[180:183], v147 offset:16384
	ds_read_b128 v[184:187], v147 offset:17408
	ds_read_b128 v[188:191], v147 offset:18432
	ds_read_b128 v[192:195], v147 offset:19456
	ds_read_b128 v[196:199], v147 offset:20480
	ds_read_b128 v[200:203], v147 offset:21504
	ds_read_b128 v[204:207], v147 offset:22528
	ds_read_b128 v[208:211], v147 offset:23552
	global_load_lds_dwordx4 v132, s[24:25]
	s_add_i32 m0, s52, 0x2000
	s_add_u32 s56, s24, 0x40000
	s_addc_u32 s57, s25, 0
	s_add_i32 s52, s41, s3
	global_load_lds_dwordx4 v128, s[24:25]
	s_mov_b32 m0, s52
	s_nop 0
	global_load_lds_dwordx4 v132, s[56:57]
	s_add_i32 m0, s52, 0x2000
	s_nop 0
	global_load_lds_dwordx4 v128, s[56:57]
	s_mov_b32 m0, s21
	s_nop 0
	global_load_lds_dwordx4 v134, s[26:27]
	s_mov_b32 m0, s30
	s_nop 0
	global_load_lds_dwordx4 v130, s[26:27]
	s_waitcnt vmcnt(8)
	s_waitcnt lgkmcnt(0)
	s_barrier
	s_waitcnt lgkmcnt(0)
	v_mfma_f32_16x16x32_bf16 v[60:63], v[148:151], v[180:183], v[60:63]
	v_mfma_f32_16x16x32_bf16 v[56:59], v[156:159], v[180:183], v[56:59]
	v_mfma_f32_16x16x32_bf16 v[44:47], v[148:151], v[188:191], v[44:47]
	v_mfma_f32_16x16x32_bf16 v[40:43], v[156:159], v[188:191], v[40:43]
	v_mfma_f32_16x16x32_bf16 v[28:31], v[148:151], v[196:199], v[28:31]
	v_mfma_f32_16x16x32_bf16 v[24:27], v[156:159], v[196:199], v[24:27]
	v_mfma_f32_16x16x32_bf16 v[12:15], v[148:151], v[204:207], v[12:15]
	v_mfma_f32_16x16x32_bf16 v[8:11], v[156:159], v[204:207], v[8:11]
	v_mfma_f32_16x16x32_bf16 v[60:63], v[152:155], v[184:187], v[60:63]
	v_mfma_f32_16x16x32_bf16 v[56:59], v[160:163], v[184:187], v[56:59]
	v_mfma_f32_16x16x32_bf16 v[44:47], v[152:155], v[192:195], v[44:47]
	v_mfma_f32_16x16x32_bf16 v[40:43], v[160:163], v[192:195], v[40:43]
	v_mfma_f32_16x16x32_bf16 v[28:31], v[152:155], v[200:203], v[28:31]
	v_mfma_f32_16x16x32_bf16 v[24:27], v[160:163], v[200:203], v[24:27]
	v_mfma_f32_16x16x32_bf16 v[12:15], v[152:155], v[208:211], v[12:15]
	v_mfma_f32_16x16x32_bf16 v[8:11], v[160:163], v[208:211], v[8:11]
	v_mfma_f32_16x16x32_bf16 v[52:55], v[164:167], v[180:183], v[52:55]
	v_mfma_f32_16x16x32_bf16 v[48:51], v[172:175], v[180:183], v[48:51]
	v_mfma_f32_16x16x32_bf16 v[36:39], v[164:167], v[188:191], v[36:39]
	v_mfma_f32_16x16x32_bf16 v[32:35], v[172:175], v[188:191], v[32:35]
	v_mfma_f32_16x16x32_bf16 v[20:23], v[164:167], v[196:199], v[20:23]
	v_mfma_f32_16x16x32_bf16 v[16:19], v[172:175], v[196:199], v[16:19]
	v_mfma_f32_16x16x32_bf16 v[4:7], v[164:167], v[204:207], v[4:7]
	v_mfma_f32_16x16x32_bf16 v[0:3], v[172:175], v[204:207], v[0:3]
	v_mfma_f32_16x16x32_bf16 v[52:55], v[168:171], v[184:187], v[52:55]
	v_mfma_f32_16x16x32_bf16 v[48:51], v[176:179], v[184:187], v[48:51]
	v_mfma_f32_16x16x32_bf16 v[36:39], v[168:171], v[192:195], v[36:39]
	v_mfma_f32_16x16x32_bf16 v[32:35], v[176:179], v[192:195], v[32:35]
	v_mfma_f32_16x16x32_bf16 v[20:23], v[168:171], v[200:203], v[20:23]
	v_mfma_f32_16x16x32_bf16 v[16:19], v[176:179], v[200:203], v[16:19]
	v_mfma_f32_16x16x32_bf16 v[4:7], v[168:171], v[208:211], v[4:7]
	v_mfma_f32_16x16x32_bf16 v[0:3], v[176:179], v[208:211], v[0:3]
	s_barrier
; #define PG8_STAGE(bufoff, gbase, voff) do { _Pragma("unroll") for (int _i = 0; _i < 2; ++_i) \
;         __builtin_amdgcn_global_load_lds((const unsigned*)((const char*)(gbase) + (voff)[_i]), (LAS unsigned*)(lds + (bufoff) + ldsw + _i * 8192), 16, 0, 0); } while (0)
; #define PG8_LDA(dst, b, h) do { _Pragma("unroll") for (int m = 0; m < 4; ++m) _Pragma("unroll") for (int k = 0; k < 2; ++k) dst[m][k] = *(const LAS bf16x8*)(lds + PG8_SA(b, h) + aoff + m * 2048 + k * 1024); } while (0)
; #define PG8_LDB(dst, b, h) do { _Pragma("unroll") for (int n = 0; n < 2; ++n) _Pragma("unroll") for (int k = 0; k < 2; ++k) dst[n][k] = *(const LAS bf16x8*)(lds + PG8_SB(b, h) + boff + n * 2048 + k * 1024); } while (0)
; #define PG8_MMA(ai, bj, At, Bt) do { __builtin_amdgcn_s_setprio(1); _Pragma("unroll") for (int m = 0; m < 4; ++m) _Pragma("unroll") for (int n = 0; n < 2; ++n) _Pragma("unroll") for (int k = 0; k < 2; ++k) \
;         acc[ai][bj][m][n] = __builtin_amdgcn_mfma_f32_16x16x32_bf16(Bt[n][k], At[m][k], acc[ai][bj][m][n], 0, 0, 0); __builtin_amdgcn_s_setprio(0); } while (0)
; #define PG8_WAIT_V(n) asm volatile("s_waitcnt vmcnt(" #n ")" ::: "memory")
; #define PG8_WAIT_L(n) asm volatile("s_waitcnt lgkmcnt(" #n ")" ::: "memory")
; #define PG8_BAR __builtin_amdgcn_s_barrier()
; #define PG8_SCHED __builtin_amdgcn_sched_barrier(0)
; template <class Epi, bool ALIGN_EPI, int K, int LDA, int LDB>
; __device__ __forceinline__ void gemm_phase(LAS unsigned char* lds, const int wid, const Gemm g, const StaticOrder& S, const Epi& E) {
;     ...
;             PG8_LDB(B0, 1, 0); PG8_LDB(B1, 1, 1); PG8_SCHED; PG8_LDA(At, 1, 0); PG8_STAGE(PG8_SA(0, 1), a2 + hA, voffA);
;             PG8_WAIT_V(8); PG8_WAIT_L(0); PG8_BAR; PG8_MMA(0, 0, At, B0); PG8_MMA(0, 1, At, B1); PG8_BAR; PG8_SCHED;
;             PG8_LDA(At, 1, 1); PG8_STAGE(PG8_SB(1, 0), b3, voffB); PG8_STAGE(PG8_SB(1, 1), b3 + hB, voffB); PG8_STAGE(PG8_SA(1, 0), a3, voffA);
;             PG8_WAIT_V(8); PG8_WAIT_L(0); PG8_BAR; PG8_MMA(1, 0, At, B0); PG8_MMA(1, 1, At, B1); PG8_BAR; PG8_SCHED;
;         }
;         if constexpr (ALIGN_EPI) { if (wr == 0) PG8_BAR; }
	s_add_i32 s52, 0, 0x18000
	s_add_i32 s53, 0, 0x1c000
	v_add_u32_e32 v160, s52, v144
	v_add_u32_e32 v176, s53, v144
	ds_read_b128 v[148:151], v160
	ds_read_b128 v[152:155], v160 offset:1024
	ds_read_b128 v[156:159], v160 offset:2048
	ds_read_b128 v[160:163], v160 offset:3072
	ds_read_b128 v[164:167], v176
	ds_read_b128 v[168:171], v176 offset:1024
	ds_read_b128 v[172:175], v176 offset:2048
	ds_read_b128 v[176:179], v176 offset:3072
	s_add_u32 s26, s26, 0x40000
	s_addc_u32 s27, s27, 0
	s_mov_b32 m0, s31
	ds_read_b128 v[180:183], v147 offset:32768
	ds_read_b128 v[184:187], v147 offset:33792
	ds_read_b128 v[188:191], v147 offset:34816
	ds_read_b128 v[192:195], v147 offset:35840
	ds_read_b128 v[196:199], v147 offset:36864
	ds_read_b128 v[200:203], v147 offset:37888
	ds_read_b128 v[204:207], v147 offset:38912
	ds_read_b128 v[208:211], v147 offset:39936
	global_load_lds_dwordx4 v134, s[26:27]
	s_mov_b32 m0, s33
	s_nop 0
	global_load_lds_dwordx4 v130, s[26:27]
	s_waitcnt vmcnt(8)
	s_waitcnt lgkmcnt(0)
	s_barrier
	s_waitcnt lgkmcnt(0)
	v_mfma_f32_16x16x32_bf16 v[124:127], v[148:151], v[180:183], v[124:127]
	v_mfma_f32_16x16x32_bf16 v[120:123], v[156:159], v[180:183], v[120:123]
	v_mfma_f32_16x16x32_bf16 v[108:111], v[148:151], v[188:191], v[108:111]
	v_mfma_f32_16x16x32_bf16 v[104:107], v[156:159], v[188:191], v[104:107]
	v_mfma_f32_16x16x32_bf16 v[92:95], v[148:151], v[196:199], v[92:95]
	v_mfma_f32_16x16x32_bf16 v[88:91], v[156:159], v[196:199], v[88:91]
	v_mfma_f32_16x16x32_bf16 v[76:79], v[148:151], v[204:207], v[76:79]
	v_mfma_f32_16x16x32_bf16 v[72:75], v[156:159], v[204:207], v[72:75]
	v_mfma_f32_16x16x32_bf16 v[124:127], v[152:155], v[184:187], v[124:127]
	v_mfma_f32_16x16x32_bf16 v[120:123], v[160:163], v[184:187], v[120:123]
	v_mfma_f32_16x16x32_bf16 v[108:111], v[152:155], v[192:195], v[108:111]
	v_mfma_f32_16x16x32_bf16 v[104:107], v[160:163], v[192:195], v[104:107]
	v_mfma_f32_16x16x32_bf16 v[92:95], v[152:155], v[200:203], v[92:95]
	v_mfma_f32_16x16x32_bf16 v[88:91], v[160:163], v[200:203], v[88:91]
	v_mfma_f32_16x16x32_bf16 v[76:79], v[152:155], v[208:211], v[76:79]
	v_mfma_f32_16x16x32_bf16 v[72:75], v[160:163], v[208:211], v[72:75]
	v_mfma_f32_16x16x32_bf16 v[116:119], v[164:167], v[180:183], v[116:119]
	v_mfma_f32_16x16x32_bf16 v[112:115], v[172:175], v[180:183], v[112:115]
	v_mfma_f32_16x16x32_bf16 v[100:103], v[164:167], v[188:191], v[100:103]
	v_mfma_f32_16x16x32_bf16 v[96:99], v[172:175], v[188:191], v[96:99]
	v_mfma_f32_16x16x32_bf16 v[84:87], v[164:167], v[196:199], v[84:87]
	v_mfma_f32_16x16x32_bf16 v[80:83], v[172:175], v[196:199], v[80:83]
	v_mfma_f32_16x16x32_bf16 v[68:71], v[164:167], v[204:207], v[68:71]
	v_mfma_f32_16x16x32_bf16 v[64:67], v[172:175], v[204:207], v[64:67]
	v_mfma_f32_16x16x32_bf16 v[116:119], v[168:171], v[184:187], v[116:119]
	v_mfma_f32_16x16x32_bf16 v[112:115], v[176:179], v[184:187], v[112:115]
	v_mfma_f32_16x16x32_bf16 v[100:103], v[168:171], v[192:195], v[100:103]
	v_mfma_f32_16x16x32_bf16 v[96:99], v[176:179], v[192:195], v[96:99]
	v_mfma_f32_16x16x32_bf16 v[84:87], v[168:171], v[200:203], v[84:87]
	v_mfma_f32_16x16x32_bf16 v[80:83], v[176:179], v[200:203], v[80:83]
	v_mfma_f32_16x16x32_bf16 v[68:71], v[168:171], v[208:211], v[68:71]
	v_mfma_f32_16x16x32_bf16 v[64:67], v[176:179], v[208:211], v[64:67]
	s_barrier
	s_add_i32 s26, s52, s3
	s_mov_b32 m0, s26
	ds_read_b128 v[180:183], v147 offset:49152
	ds_read_b128 v[184:187], v147 offset:50176
	ds_read_b128 v[188:191], v147 offset:51200
	ds_read_b128 v[192:195], v147 offset:52224
	ds_read_b128 v[196:199], v147 offset:53248
	ds_read_b128 v[200:203], v147 offset:54272
	ds_read_b128 v[204:207], v147 offset:55296
	ds_read_b128 v[208:211], v147 offset:56320
	global_load_lds_dwordx4 v132, s[98:99]
	s_add_i32 m0, s26, 0x2000
	s_add_u32 s24, s24, 0x40080
	s_addc_u32 s25, s25, 0
	s_add_i32 s26, s53, s3
	global_load_lds_dwordx4 v128, s[98:99]
	s_mov_b32 m0, s26
	s_nop 0
	global_load_lds_dwordx4 v132, s[24:25]
	s_add_i32 m0, s26, 0x2000
	s_nop 0
	global_load_lds_dwordx4 v128, s[24:25]
	s_mov_b32 m0, s38
	s_nop 0
	global_load_lds_dwordx4 v134, s[100:101]
	s_mov_b32 m0, s39
	s_nop 0
	global_load_lds_dwordx4 v130, s[100:101]
	s_waitcnt vmcnt(8)
	s_waitcnt lgkmcnt(0)
	s_barrier
	s_waitcnt lgkmcnt(0)
	v_mfma_f32_16x16x32_bf16 v[60:63], v[148:151], v[180:183], v[60:63]
	v_mfma_f32_16x16x32_bf16 v[56:59], v[156:159], v[180:183], v[56:59]
	v_mfma_f32_16x16x32_bf16 v[44:47], v[148:151], v[188:191], v[44:47]
	v_mfma_f32_16x16x32_bf16 v[40:43], v[156:159], v[188:191], v[40:43]
	v_mfma_f32_16x16x32_bf16 v[28:31], v[148:151], v[196:199], v[28:31]
	v_mfma_f32_16x16x32_bf16 v[24:27], v[156:159], v[196:199], v[24:27]
	v_mfma_f32_16x16x32_bf16 v[12:15], v[148:151], v[204:207], v[12:15]
	v_mfma_f32_16x16x32_bf16 v[8:11], v[156:159], v[204:207], v[8:11]
	v_mfma_f32_16x16x32_bf16 v[60:63], v[152:155], v[184:187], v[60:63]
	v_mfma_f32_16x16x32_bf16 v[56:59], v[160:163], v[184:187], v[56:59]
	v_mfma_f32_16x16x32_bf16 v[44:47], v[152:155], v[192:195], v[44:47]
	v_mfma_f32_16x16x32_bf16 v[40:43], v[160:163], v[192:195], v[40:43]
	v_mfma_f32_16x16x32_bf16 v[28:31], v[152:155], v[200:203], v[28:31]
	v_mfma_f32_16x16x32_bf16 v[24:27], v[160:163], v[200:203], v[24:27]
	v_mfma_f32_16x16x32_bf16 v[12:15], v[152:155], v[208:211], v[12:15]
	v_mfma_f32_16x16x32_bf16 v[8:11], v[160:163], v[208:211], v[8:11]
	v_mfma_f32_16x16x32_bf16 v[52:55], v[164:167], v[180:183], v[52:55]
	v_mfma_f32_16x16x32_bf16 v[48:51], v[172:175], v[180:183], v[48:51]
	v_mfma_f32_16x16x32_bf16 v[36:39], v[164:167], v[188:191], v[36:39]
	v_mfma_f32_16x16x32_bf16 v[32:35], v[172:175], v[188:191], v[32:35]
	v_mfma_f32_16x16x32_bf16 v[20:23], v[164:167], v[196:199], v[20:23]
	v_mfma_f32_16x16x32_bf16 v[16:19], v[172:175], v[196:199], v[16:19]
	v_mfma_f32_16x16x32_bf16 v[4:7], v[164:167], v[204:207], v[4:7]
	v_mfma_f32_16x16x32_bf16 v[0:3], v[172:175], v[204:207], v[0:3]
	v_mfma_f32_16x16x32_bf16 v[52:55], v[168:171], v[184:187], v[52:55]
	v_mfma_f32_16x16x32_bf16 v[48:51], v[176:179], v[184:187], v[48:51]
	v_mfma_f32_16x16x32_bf16 v[36:39], v[168:171], v[192:195], v[36:39]
	v_mfma_f32_16x16x32_bf16 v[32:35], v[176:179], v[192:195], v[32:35]
	v_mfma_f32_16x16x32_bf16 v[20:23], v[168:171], v[200:203], v[20:23]
	v_mfma_f32_16x16x32_bf16 v[16:19], v[176:179], v[200:203], v[16:19]
	v_mfma_f32_16x16x32_bf16 v[4:7], v[168:171], v[208:211], v[4:7]
	v_mfma_f32_16x16x32_bf16 v[0:3], v[176:179], v[208:211], v[0:3]
	s_barrier
	s_add_i32 s55, s55, 2
	s_add_u32 s22, s22, 0x100
	s_addc_u32 s23, s23, 0
	s_add_u32 s51, s51, 0x100
	s_addc_u32 s54, s54, 0
	s_cmp_gt_u32 s55, 13
	s_cbranch_scc0 .LBB0_1052
	s_and_b64 vcc, exec, s[8:9]
	s_cbranch_vccz .LBB0_1055
	s_barrier

;     __device__ bool next(int i, Unit& u) const {
;         const long L = (long)i * G + c; if (L >= nwg) return false;
;         int wgid = (int)L; { const int q = nwg / NXCD, r = nwg % NXCD, xcd = wgid % NXCD, off = wgid / NXCD; wgid = (xcd < r ? xcd * (q + 1) : r * (q + 1) + (xcd - r) * q) + off; }
;         const int nig = WGM * nN, gid = wgid / nig, fm = gid * WGM, gsz = (nM - fm) < WGM ? (nM - fm) : WGM;
;         u.pm = fm + ((wgid % nig) % gsz); u.pn = (wgid % nig) / gsz; return true;
;     }
; template <class Epi, bool ALIGN_EPI, int K, int LDA, int LDB>
; __device__ __forceinline__ void gemm_phase(LAS unsigned char* lds, const int wid, const Gemm g, const StaticOrder& S, const Epi& E) {
;     const int lane = lane_id_(), tid = wid * 64 + lane, wr = wid >> 2, wc = wid & 3, fr = lane & 15, fq = lane >> 4;
;     constexpr int nt = K / BK;
;     unsigned voffA[2], voffB[2];
; #pragma unroll
;     for (int i = 0; i < 2; ++i) { int R, C; stage_rc(tid * 16 + i * 8192, R, C); const int Rb = Epi::PERM ? ((R & ~31) + perm32(R & 31)) : R;
;         voffA[i] = (unsigned)(R * LDA + C) * 2u; voffB[i] = (unsigned)(Rb * LDB + C) * 2u; }
;     constexpr size_t kstep = (size_t)(BK * 2);
;     constexpr size_t hA = (size_t)HALF * LDA * 2, hB = (size_t)HALF * LDB * 2;
;     constexpr size_t tA = 2 * hA, tB = 2 * hB;
;     const unsigned ldsw = (unsigned)wid * 1024u;
;     const int aoff = lds_byte(wr * 64 + fr, fq * 8), boff = lds_byte(wc * 32 + fr, fq * 8);
;     ...
;     Unit cur, nxt; int ui = 0;
;     if (!S.next(0, cur)) return;
;     f32x4 acc[2][2][4][2];
; #pragma unroll
;     for (int a = 0; a < 2; ++a)
; #pragma unroll
;         for (int b = 0; b < 2; ++b)
; #pragma unroll
;             for (int m = 0; m < 4; ++m)
; #pragma unroll
;                 for (int n = 0; n < 2; ++n) acc[a][b][m][n] = (f32x4){0.f, 0.f, 0.f, 0.f};
;     bf16x8 At[4][2], B0[2][2], B1[2][2];
;     const char* cA = (const char*)g.A + (size_t)cur.pm * tA; const char* cB = (const char*)g.Bt + (size_t)cur.pn * tB;
;     PG8_STAGE(PG8_SB(0, 0), cB, voffB); PG8_STAGE(PG8_SB(0, 1), cB + hB, voffB); PG8_STAGE(PG8_SA(0, 0), cA, voffA); PG8_STAGE(PG8_SA(0, 1), cA + hA, voffA);
;     if (wr == 1) PG8_BAR;
;     PG8_WAIT_V(2); PG8_BAR;
;     PG8_STAGE(PG8_SB(1, 0), cB + kstep, voffB); PG8_STAGE(PG8_SA(1, 0), cA + kstep, voffA); PG8_STAGE(PG8_SB(1, 1), cB + hB + kstep, voffB);
.LBB0_1121:
	s_ashr_i32 s7, s1, 3
	s_add_u32 s1, s46, 0x2e00000
	s_addc_u32 s3, s47, 0
	s_lshl_b32 s33, s50, 10
	s_waitcnt lgkmcnt(0)
	v_lshl_add_u32 v0, v8, 4, s33
	v_ashrrev_i32_e32 v1, 31, v0
	v_lshrrev_b32_e32 v1, 22, v1
	v_add_u32_e32 v1, v0, v1
	v_ashrrev_i32_e32 v9, 10, v1
	v_mul_i32_i24_e32 v1, 0x400, v9
	v_sub_u32_e32 v1, v0, v1
	v_lshrrev_b32_e32 v2, 4, v1
	v_bitop3_b32 v1, v2, v1, 32 bitop3:0x6c
	v_ashrrev_i32_e32 v3, 31, v1
	v_lshrrev_b32_e32 v3, 26, v3
	v_lshlrev_b32_e32 v2, 3, v9
	v_add_u32_e32 v3, v1, v3
	v_and_b32_e32 v2, -16, v2
	v_ashrrev_i32_e32 v11, 6, v3
	v_and_b32_e32 v3, 0xc0, v3
	v_add_u32_e32 v2, v11, v2
	v_lshlrev_b32_e32 v4, 5, v9
	v_sub_u32_e32 v1, v1, v3
	v_mov_b32_e32 v3, 1
	v_and_b32_e32 v10, 32, v4
	v_ashrrev_i16_sdwa v1, v3, sext(v1) dst_sel:DWORD dst_unused:UNUSED_PAD src0_sel:DWORD src1_sel:BYTE_0
	v_lshlrev_b32_e32 v4, 1, v2
	v_lshrrev_b32_e32 v5, 2, v2
	v_and_b32_e32 v6, 3, v11
	s_mov_b32 s8, 0xffffe0
	v_bfe_i32 v12, v1, 0, 16
	v_and_b32_e32 v4, 24, v4
	v_and_b32_e32 v5, 4, v5
	v_and_or_b32 v6, v2, s8, v6
	s_movk_i32 s4, 0xb00
	v_add_u32_e32 v1, v10, v12
	v_or3_b32 v4, v6, v5, v4
	v_mul_lo_u32 v2, v2, s4
	v_add_lshl_u32 v148, v1, v2, 1
	v_mul_u32_u24_e32 v2, 0xb00, v4
	v_add_u32_e32 v0, 0x2000, v0
	v_add_lshl_u32 v150, v2, v1, 1
	v_ashrrev_i32_e32 v1, 31, v0
	v_lshrrev_b32_e32 v1, 22, v1
	v_add_u32_e32 v1, v0, v1
	v_ashrrev_i32_e32 v13, 10, v1
	v_mul_i32_i24_e32 v1, 0x400, v13
	v_sub_u32_e32 v0, v0, v1
	v_lshrrev_b32_e32 v1, 4, v0
	v_bitop3_b32 v0, v1, v0, 32 bitop3:0x6c
	v_ashrrev_i32_e32 v2, 31, v0
	v_lshrrev_b32_e32 v2, 26, v2
	s_add_i32 s6, s6, s7
	v_lshlrev_b32_e32 v1, 3, v13
	v_add_u32_e32 v2, v0, v2
	s_ashr_i32 s7, s6, 31
	v_and_b32_e32 v1, -16, v1
	v_ashrrev_i32_e32 v14, 6, v2
	v_lshlrev_b32_e32 v4, 5, v13
	s_lshr_b32 s7, s7, 27
	v_add_u32_e32 v1, v14, v1
	v_and_b32_e32 v15, 32, v4
	v_and_b32_e32 v4, 3, v14
	s_add_i32 s7, s6, s7
	v_and_or_b32 v4, v1, s8, v4
	s_ashr_i32 s8, s7, 5
	s_andn2_b32 s7, s7, 31
	s_sub_i32 s7, s6, s7
	s_bfe_i32 s6, s7, 0x80000
	s_bfe_u32 s6, s6, 0x3000c
	s_add_i32 s9, s7, s6
	v_and_b32_e32 v2, 0xffc0, v2
	s_bfe_i32 s6, s9, 0x80000
	s_and_b32 s9, s9, 0xf8
	v_sub_u32_e32 v0, v0, v2
	s_sub_i32 s7, s7, s9
	v_lshrrev_b16_e32 v2, 7, v0
	s_lshl_b32 s8, s8, 3
	s_sext_i32_i16 s10, s6
	s_sext_i32_i8 s7, s7
	v_and_b32_e32 v2, 1, v2
	s_add_i32 s63, s8, s7
	s_ashr_i32 s8, s10, 3
	s_lshr_b32 s5, s86, 8
	v_add_u16_e32 v0, v0, v2
	s_lshr_b32 s6, s10, 3
	s_mul_hi_i32 s9, s8, 0x160000
	s_mul_i32 s8, s8, 0x160000
	v_ashrrev_i16_sdwa v0, v3, sext(v0) dst_sel:DWORD dst_unused:UNUSED_PAD src0_sel:DWORD src1_sel:BYTE_0
	v_lshlrev_b32_e32 v2, 1, v1
	v_lshrrev_b32_e32 v3, 2, v1
	s_add_u32 s28, s1, s8
	v_bfe_i32 v16, v0, 0, 16
	v_and_b32_e32 v2, 24, v2
	v_and_b32_e32 v3, 4, v3
	s_addc_u32 s29, s3, s9
	s_add_i32 s36, s33, 0
	v_add_u32_e32 v0, v15, v16
	v_or3_b32 v2, v4, v3, v2
	v_mul_lo_u32 v1, v1, s4
	s_add_i32 m0, s36, 0x10000
	v_add_lshl_u32 v152, v0, v1, 1
	v_mul_u32_u24_e32 v1, 0xb00, v2
	global_load_lds_dwordx4 v150, s[28:29]
	s_add_i32 m0, s36, 0x12000
	v_add_lshl_u32 v154, v1, v0, 1
	s_add_u32 s8, s28, 0xb0000
	global_load_lds_dwordx4 v154, s[28:29]
	s_addc_u32 s9, s29, 0
	s_add_i32 m0, s36, 0x14000
	s_mul_i32 s11, s63, 0x160000
	global_load_lds_dwordx4 v150, s[8:9]
	s_add_i32 m0, s36, 0x16000
	s_mul_hi_i32 s7, s63, 0x160000
	s_add_u32 s26, s70, s11
	s_addc_u32 s27, s71, s7
	s_add_i32 s37, s36, 0x2000
	global_load_lds_dwordx4 v154, s[8:9]
	s_mov_b32 m0, s36
	s_add_u32 s8, s26, 0xb0000
	global_load_lds_dwordx4 v148, s[26:27]
	s_mov_b32 m0, s37
	s_addc_u32 s9, s27, 0
	s_add_i32 s38, s36, 0x4000
	global_load_lds_dwordx4 v152, s[26:27]
	s_mov_b32 m0, s38
	s_add_i32 s39, s36, 0x6000
	global_load_lds_dwordx4 v148, s[8:9]
	s_mov_b32 m0, s39
	v_mov_b32_e32 v151, 0
	global_load_lds_dwordx4 v152, s[8:9]
	v_mov_b32_e32 v155, v151
	v_mov_b32_e32 v149, v151
	v_mov_b32_e32 v153, v151
	s_cmp_eq_u32 s5, 1
	s_mov_b32 s9, 0
	v_lshl_add_u64 v[6:7], s[28:29], 0, v[150:151]
	v_lshl_add_u64 v[4:5], s[28:29], 0, v[154:155]
	v_lshl_add_u64 v[0:1], s[26:27], 0, v[148:149]
	s_cselect_b64 s[10:11], -1, 0
	s_cmp_lg_u32 s5, 1
	v_lshl_add_u64 v[2:3], s[26:27], 0, v[152:153]
	s_cbranch_scc1 .LBB0_1123
	s_setprio 1
	s_barrier

; #define PG8_STAGE(bufoff, gbase, voff) do { _Pragma("unroll") for (int _i = 0; _i < 2; ++_i) \
;         __builtin_amdgcn_global_load_lds((const unsigned*)((const char*)(gbase) + (voff)[_i]), (LAS unsigned*)(lds + (bufoff) + ldsw + _i * 8192), 16, 0, 0); } while (0)
; #define PG8_LDA(dst, b, h) do { _Pragma("unroll") for (int m = 0; m < 4; ++m) _Pragma("unroll") for (int k = 0; k < 2; ++k) dst[m][k] = *(const LAS bf16x8*)(lds + PG8_SA(b, h) + aoff + m * 2048 + k * 1024); } while (0)
; #define PG8_LDB(dst, b, h) do { _Pragma("unroll") for (int n = 0; n < 2; ++n) _Pragma("unroll") for (int k = 0; k < 2; ++k) dst[n][k] = *(const LAS bf16x8*)(lds + PG8_SB(b, h) + boff + n * 2048 + k * 1024); } while (0)
; #define PG8_MMA(ai, bj, At, Bt) do { __builtin_amdgcn_s_setprio(1); _Pragma("unroll") for (int m = 0; m < 4; ++m) _Pragma("unroll") for (int n = 0; n < 2; ++n) _Pragma("unroll") for (int k = 0; k < 2; ++k) \
;         acc[ai][bj][m][n] = __builtin_amdgcn_mfma_f32_16x16x32_bf16(Bt[n][k], At[m][k], acc[ai][bj][m][n], 0, 0, 0); __builtin_amdgcn_s_setprio(0); } while (0)
; #define PG8_WAIT_V(n) asm volatile("s_waitcnt vmcnt(" #n ")" ::: "memory")
; #define PG8_WAIT_L(n) asm volatile("s_waitcnt lgkmcnt(" #n ")" ::: "memory")
; #define PG8_BAR __builtin_amdgcn_s_barrier()
; #define PG8_SCHED __builtin_amdgcn_sched_barrier(0)
; template <class Epi, bool ALIGN_EPI, int K, int LDA, int LDB>
; __device__ __forceinline__ void gemm_phase(LAS unsigned char* lds, const int wid, const Gemm g, const StaticOrder& S, const Epi& E) {
;     ...
;             const bool last = (t == nt - 2);
;             const char* a1 = cA + (size_t)(t + 1) * kstep;
;             const char* a2 = last ? nA : cA + (size_t)(t + 2) * kstep; const char* b2 = last ? nB : cB + (size_t)(t + 2) * kstep;
;             const char* a3 = a2 + kstep; const char* b3 = b2 + kstep;
;             PG8_LDB(B0, 0, 0); PG8_LDB(B1, 0, 1); PG8_SCHED; PG8_LDA(At, 0, 0); PG8_STAGE(PG8_SA(1, 1), a1 + hA, voffA);
;             PG8_WAIT_V(8); PG8_WAIT_L(0); PG8_BAR; PG8_MMA(0, 0, At, B0); PG8_MMA(0, 1, At, B1); PG8_BAR; PG8_SCHED;
;             PG8_LDA(At, 0, 1); PG8_STAGE(PG8_SB(0, 0), b2, voffB); PG8_STAGE(PG8_SB(0, 1), b2 + hB, voffB); PG8_STAGE(PG8_SA(0, 0), a2, voffA);
;             PG8_WAIT_V(8); PG8_WAIT_L(0); PG8_BAR; PG8_MMA(1, 0, At, B0); PG8_MMA(1, 1, At, B1); PG8_BAR; PG8_SCHED;
.LBB0_1137:
	ds_read_b128 v[128:131], v175
	ds_read_b128 v[132:135], v175 offset:1024
	ds_read_b128 v[136:139], v175 offset:2048
	ds_read_b128 v[140:143], v175 offset:3072
	ds_read_b128 v[144:147], v176
	ds_read_b128 v[164:167], v176 offset:1024
	ds_read_b128 v[168:171], v176 offset:2048
	ds_read_b128 v[178:181], v176 offset:3072
	s_add_u32 s28, s26, 0x100
	s_addc_u32 s29, s27, 0
	s_cmp_eq_u32 s67, 40
	s_cselect_b32 s35, s7, s29
	s_cselect_b32 s34, s6, s28
	s_cselect_b32 s31, s25, s66
	s_cselect_b32 s30, s24, s65
	s_add_i32 m0, s36, 0xc000
	ds_read_b128 v[182:185], v177
	ds_read_b128 v[186:189], v177 offset:1024
	ds_read_b128 v[190:193], v177 offset:2048
	ds_read_b128 v[194:197], v177 offset:3072
	ds_read_b128 v[198:201], v177 offset:4096
	ds_read_b128 v[202:205], v177 offset:5120
	ds_read_b128 v[206:209], v177 offset:6144
	ds_read_b128 v[210:213], v177 offset:7168
	global_load_lds_dwordx4 v156, s[26:27]
	s_add_i32 m0, s36, 0xe000
	s_nop 0
	global_load_lds_dwordx4 v158, s[26:27]
	s_waitcnt vmcnt(8)
	s_waitcnt lgkmcnt(0)
	s_barrier
	s_waitcnt lgkmcnt(0)
	v_mfma_f32_16x16x32_bf16 v[124:127], v[128:131], v[182:185], v[124:127]
	v_mfma_f32_16x16x32_bf16 v[116:119], v[136:139], v[182:185], v[116:119]
	v_mfma_f32_16x16x32_bf16 v[120:123], v[128:131], v[190:193], v[120:123]
	v_mfma_f32_16x16x32_bf16 v[112:115], v[136:139], v[190:193], v[112:115]
	v_mfma_f32_16x16x32_bf16 v[92:95], v[128:131], v[198:201], v[92:95]
	v_mfma_f32_16x16x32_bf16 v[88:91], v[136:139], v[198:201], v[88:91]
	v_mfma_f32_16x16x32_bf16 v[76:79], v[128:131], v[206:209], v[76:79]
	v_mfma_f32_16x16x32_bf16 v[72:75], v[136:139], v[206:209], v[72:75]
	v_mfma_f32_16x16x32_bf16 v[124:127], v[132:135], v[186:189], v[124:127]
	v_mfma_f32_16x16x32_bf16 v[116:119], v[140:143], v[186:189], v[116:119]
	v_mfma_f32_16x16x32_bf16 v[120:123], v[132:135], v[194:197], v[120:123]
	v_mfma_f32_16x16x32_bf16 v[112:115], v[140:143], v[194:197], v[112:115]
	v_mfma_f32_16x16x32_bf16 v[92:95], v[132:135], v[202:205], v[92:95]
	v_mfma_f32_16x16x32_bf16 v[88:91], v[140:143], v[202:205], v[88:91]
	v_mfma_f32_16x16x32_bf16 v[76:79], v[132:135], v[210:213], v[76:79]
	v_mfma_f32_16x16x32_bf16 v[72:75], v[140:143], v[210:213], v[72:75]
	v_mfma_f32_16x16x32_bf16 v[108:111], v[144:147], v[182:185], v[108:111]
	v_mfma_f32_16x16x32_bf16 v[104:107], v[168:171], v[182:185], v[104:107]
	v_mfma_f32_16x16x32_bf16 v[100:103], v[144:147], v[190:193], v[100:103]
	v_mfma_f32_16x16x32_bf16 v[96:99], v[168:171], v[190:193], v[96:99]
	v_mfma_f32_16x16x32_bf16 v[84:87], v[144:147], v[198:201], v[84:87]
	v_mfma_f32_16x16x32_bf16 v[80:83], v[168:171], v[198:201], v[80:83]
	v_mfma_f32_16x16x32_bf16 v[68:71], v[144:147], v[206:209], v[68:71]
	v_mfma_f32_16x16x32_bf16 v[64:67], v[168:171], v[206:209], v[64:67]
	v_mfma_f32_16x16x32_bf16 v[108:111], v[164:167], v[186:189], v[108:111]
	v_mfma_f32_16x16x32_bf16 v[104:107], v[178:181], v[186:189], v[104:107]
	v_mfma_f32_16x16x32_bf16 v[100:103], v[164:167], v[194:197], v[100:103]
	v_mfma_f32_16x16x32_bf16 v[96:99], v[178:181], v[194:197], v[96:99]
	v_mfma_f32_16x16x32_bf16 v[84:87], v[164:167], v[202:205], v[84:87]
	v_mfma_f32_16x16x32_bf16 v[80:83], v[178:181], v[202:205], v[80:83]
	v_mfma_f32_16x16x32_bf16 v[68:71], v[164:167], v[210:213], v[68:71]
	v_mfma_f32_16x16x32_bf16 v[64:67], v[178:181], v[210:213], v[64:67]
	s_barrier
	s_add_u32 s98, s30, s12
	s_addc_u32 s99, s31, s13
	s_add_u32 s100, s34, s12
	s_addc_u32 s101, s35, s13
	s_add_i32 s26, s54, s33
	s_mov_b32 m0, s26
	ds_read_b128 v[182:185], v177 offset:16384
	ds_read_b128 v[186:189], v177 offset:17408
	ds_read_b128 v[190:193], v177 offset:18432
	ds_read_b128 v[194:197], v177 offset:19456
	ds_read_b128 v[198:201], v177 offset:20480
	ds_read_b128 v[202:205], v177 offset:21504
	ds_read_b128 v[206:209], v177 offset:22528
	ds_read_b128 v[210:213], v177 offset:23552
	global_load_lds_dwordx4 v150, s[30:31]
	s_add_i32 m0, s26, 0x2000
	s_add_u32 s26, s30, 0xb0000
	s_addc_u32 s27, s31, 0
	s_add_i32 s52, s55, s33
	global_load_lds_dwordx4 v154, s[30:31]
	s_mov_b32 m0, s52
	s_nop 0
	global_load_lds_dwordx4 v150, s[26:27]
	s_add_i32 m0, s52, 0x2000
	s_nop 0
	global_load_lds_dwordx4 v154, s[26:27]
	s_mov_b32 m0, s36
	s_nop 0
	global_load_lds_dwordx4 v148, s[34:35]
	s_mov_b32 m0, s37
	s_nop 0
	global_load_lds_dwordx4 v152, s[34:35]
	s_waitcnt vmcnt(8)
	s_waitcnt lgkmcnt(0)
	s_barrier
	s_waitcnt lgkmcnt(0)
	v_mfma_f32_16x16x32_bf16 v[60:63], v[128:131], v[182:185], v[60:63]
	v_mfma_f32_16x16x32_bf16 v[56:59], v[136:139], v[182:185], v[56:59]
	v_mfma_f32_16x16x32_bf16 v[44:47], v[128:131], v[190:193], v[44:47]
	v_mfma_f32_16x16x32_bf16 v[40:43], v[136:139], v[190:193], v[40:43]
	v_mfma_f32_16x16x32_bf16 v[36:39], v[128:131], v[198:201], v[36:39]
	v_mfma_f32_16x16x32_bf16 v[32:35], v[136:139], v[198:201], v[32:35]
	v_mfma_f32_16x16x32_bf16 v[20:23], v[128:131], v[206:209], v[20:23]
	v_mfma_f32_16x16x32_bf16 v[16:19], v[136:139], v[206:209], v[16:19]
	v_mfma_f32_16x16x32_bf16 v[60:63], v[132:135], v[186:189], v[60:63]
	v_mfma_f32_16x16x32_bf16 v[56:59], v[140:143], v[186:189], v[56:59]
	v_mfma_f32_16x16x32_bf16 v[44:47], v[132:135], v[194:197], v[44:47]
	v_mfma_f32_16x16x32_bf16 v[40:43], v[140:143], v[194:197], v[40:43]
	v_mfma_f32_16x16x32_bf16 v[36:39], v[132:135], v[202:205], v[36:39]
	v_mfma_f32_16x16x32_bf16 v[32:35], v[140:143], v[202:205], v[32:35]
	v_mfma_f32_16x16x32_bf16 v[20:23], v[132:135], v[210:213], v[20:23]
	v_mfma_f32_16x16x32_bf16 v[16:19], v[140:143], v[210:213], v[16:19]
	v_mfma_f32_16x16x32_bf16 v[52:55], v[144:147], v[182:185], v[52:55]
	v_mfma_f32_16x16x32_bf16 v[48:51], v[168:171], v[182:185], v[48:51]
	v_mfma_f32_16x16x32_bf16 v[28:31], v[144:147], v[190:193], v[28:31]
	v_mfma_f32_16x16x32_bf16 v[24:27], v[168:171], v[190:193], v[24:27]
	v_mfma_f32_16x16x32_bf16 v[12:15], v[144:147], v[198:201], v[12:15]
	v_mfma_f32_16x16x32_bf16 v[8:11], v[168:171], v[198:201], v[8:11]
	v_mfma_f32_16x16x32_bf16 v[4:7], v[144:147], v[206:209], v[4:7]
	v_mfma_f32_16x16x32_bf16 v[0:3], v[168:171], v[206:209], v[0:3]
	v_mfma_f32_16x16x32_bf16 v[52:55], v[164:167], v[186:189], v[52:55]
	v_mfma_f32_16x16x32_bf16 v[48:51], v[178:181], v[186:189], v[48:51]
	v_mfma_f32_16x16x32_bf16 v[28:31], v[164:167], v[194:197], v[28:31]
	v_mfma_f32_16x16x32_bf16 v[24:27], v[178:181], v[194:197], v[24:27]
	v_mfma_f32_16x16x32_bf16 v[12:15], v[164:167], v[202:205], v[12:15]
	v_mfma_f32_16x16x32_bf16 v[8:11], v[178:181], v[202:205], v[8:11]
	v_mfma_f32_16x16x32_bf16 v[4:7], v[164:167], v[210:213], v[4:7]
	v_mfma_f32_16x16x32_bf16 v[0:3], v[178:181], v[210:213], v[0:3]
	s_barrier
; #define PG8_STAGE(bufoff, gbase, voff) do { _Pragma("unroll") for (int _i = 0; _i < 2; ++_i) \
;         __builtin_amdgcn_global_load_lds((const unsigned*)((const char*)(gbase) + (voff)[_i]), (LAS unsigned*)(lds + (bufoff) + ldsw + _i * 8192), 16, 0, 0); } while (0)
; #define PG8_LDA(dst, b, h) do { _Pragma("unroll") for (int m = 0; m < 4; ++m) _Pragma("unroll") for (int k = 0; k < 2; ++k) dst[m][k] = *(const LAS bf16x8*)(lds + PG8_SA(b, h) + aoff + m * 2048 + k * 1024); } while (0)
; #define PG8_LDB(dst, b, h) do { _Pragma("unroll") for (int n = 0; n < 2; ++n) _Pragma("unroll") for (int k = 0; k < 2; ++k) dst[n][k] = *(const LAS bf16x8*)(lds + PG8_SB(b, h) + boff + n * 2048 + k * 1024); } while (0)
; #define PG8_MMA(ai, bj, At, Bt) do { __builtin_amdgcn_s_setprio(1); _Pragma("unroll") for (int m = 0; m < 4; ++m) _Pragma("unroll") for (int n = 0; n < 2; ++n) _Pragma("unroll") for (int k = 0; k < 2; ++k) \
;         acc[ai][bj][m][n] = __builtin_amdgcn_mfma_f32_16x16x32_bf16(Bt[n][k], At[m][k], acc[ai][bj][m][n], 0, 0, 0); __builtin_amdgcn_s_setprio(0); } while (0)
; #define PG8_WAIT_V(n) asm volatile("s_waitcnt vmcnt(" #n ")" ::: "memory")
; #define PG8_WAIT_L(n) asm volatile("s_waitcnt lgkmcnt(" #n ")" ::: "memory")
; #define PG8_BAR __builtin_amdgcn_s_barrier()
; #define PG8_SCHED __builtin_amdgcn_sched_barrier(0)
; template <class Epi, bool ALIGN_EPI, int K, int LDA, int LDB>
; __device__ __forceinline__ void gemm_phase(LAS unsigned char* lds, const int wid, const Gemm g, const StaticOrder& S, const Epi& E) {
;     ...
;             PG8_LDB(B0, 1, 0); PG8_LDB(B1, 1, 1); PG8_SCHED; PG8_LDA(At, 1, 0); PG8_STAGE(PG8_SA(0, 1), a2 + hA, voffA);
;             PG8_WAIT_V(8); PG8_WAIT_L(0); PG8_BAR; PG8_MMA(0, 0, At, B0); PG8_MMA(0, 1, At, B1); PG8_BAR; PG8_SCHED;
;             PG8_LDA(At, 1, 1); PG8_STAGE(PG8_SB(1, 0), b3, voffB); PG8_STAGE(PG8_SB(1, 1), b3 + hB, voffB); PG8_STAGE(PG8_SA(1, 0), a3, voffA);
;             PG8_WAIT_V(8); PG8_WAIT_L(0); PG8_BAR; PG8_MMA(1, 0, At, B0); PG8_MMA(1, 1, At, B1); PG8_BAR; PG8_SCHED;
;         }
;         if constexpr (ALIGN_EPI) { if (wr == 0) PG8_BAR; }
	s_add_i32 s52, 0, 0x18000
	s_add_i32 s53, 0, 0x1c000
	v_add_u32_e32 v140, s52, v174
	v_add_u32_e32 v178, s53, v174
	ds_read_b128 v[128:131], v140
	ds_read_b128 v[132:135], v140 offset:1024
	ds_read_b128 v[136:139], v140 offset:2048
	ds_read_b128 v[140:143], v140 offset:3072
	ds_read_b128 v[144:147], v178
	ds_read_b128 v[164:167], v178 offset:1024
	ds_read_b128 v[168:171], v178 offset:2048
	ds_read_b128 v[178:181], v178 offset:3072
	s_add_u32 s26, s34, 0xb0000
	s_addc_u32 s27, s35, 0
	s_mov_b32 m0, s38
	ds_read_b128 v[182:185], v177 offset:32768
	ds_read_b128 v[186:189], v177 offset:33792
	ds_read_b128 v[190:193], v177 offset:34816
	ds_read_b128 v[194:197], v177 offset:35840
	ds_read_b128 v[198:201], v177 offset:36864
	ds_read_b128 v[202:205], v177 offset:37888
	ds_read_b128 v[206:209], v177 offset:38912
	ds_read_b128 v[210:213], v177 offset:39936
	global_load_lds_dwordx4 v148, s[26:27]
	s_mov_b32 m0, s39
	s_nop 0
	global_load_lds_dwordx4 v152, s[26:27]
	s_waitcnt vmcnt(8)
	s_waitcnt lgkmcnt(0)
	s_barrier
	s_waitcnt lgkmcnt(0)
	v_mfma_f32_16x16x32_bf16 v[124:127], v[128:131], v[182:185], v[124:127]
	v_mfma_f32_16x16x32_bf16 v[116:119], v[136:139], v[182:185], v[116:119]
	v_mfma_f32_16x16x32_bf16 v[120:123], v[128:131], v[190:193], v[120:123]
	v_mfma_f32_16x16x32_bf16 v[112:115], v[136:139], v[190:193], v[112:115]
	v_mfma_f32_16x16x32_bf16 v[92:95], v[128:131], v[198:201], v[92:95]
	v_mfma_f32_16x16x32_bf16 v[88:91], v[136:139], v[198:201], v[88:91]
	v_mfma_f32_16x16x32_bf16 v[76:79], v[128:131], v[206:209], v[76:79]
	v_mfma_f32_16x16x32_bf16 v[72:75], v[136:139], v[206:209], v[72:75]
	v_mfma_f32_16x16x32_bf16 v[124:127], v[132:135], v[186:189], v[124:127]
	v_mfma_f32_16x16x32_bf16 v[116:119], v[140:143], v[186:189], v[116:119]
	v_mfma_f32_16x16x32_bf16 v[120:123], v[132:135], v[194:197], v[120:123]
	v_mfma_f32_16x16x32_bf16 v[112:115], v[140:143], v[194:197], v[112:115]
	v_mfma_f32_16x16x32_bf16 v[92:95], v[132:135], v[202:205], v[92:95]
	v_mfma_f32_16x16x32_bf16 v[88:91], v[140:143], v[202:205], v[88:91]
	v_mfma_f32_16x16x32_bf16 v[76:79], v[132:135], v[210:213], v[76:79]
	v_mfma_f32_16x16x32_bf16 v[72:75], v[140:143], v[210:213], v[72:75]
	v_mfma_f32_16x16x32_bf16 v[108:111], v[144:147], v[182:185], v[108:111]
	v_mfma_f32_16x16x32_bf16 v[104:107], v[168:171], v[182:185], v[104:107]
	v_mfma_f32_16x16x32_bf16 v[100:103], v[144:147], v[190:193], v[100:103]
	v_mfma_f32_16x16x32_bf16 v[96:99], v[168:171], v[190:193], v[96:99]
	v_mfma_f32_16x16x32_bf16 v[84:87], v[144:147], v[198:201], v[84:87]
	v_mfma_f32_16x16x32_bf16 v[80:83], v[168:171], v[198:201], v[80:83]
	v_mfma_f32_16x16x32_bf16 v[68:71], v[144:147], v[206:209], v[68:71]
	v_mfma_f32_16x16x32_bf16 v[64:67], v[168:171], v[206:209], v[64:67]
	v_mfma_f32_16x16x32_bf16 v[108:111], v[164:167], v[186:189], v[108:111]
	v_mfma_f32_16x16x32_bf16 v[104:107], v[178:181], v[186:189], v[104:107]
	v_mfma_f32_16x16x32_bf16 v[100:103], v[164:167], v[194:197], v[100:103]
	v_mfma_f32_16x16x32_bf16 v[96:99], v[178:181], v[194:197], v[96:99]
	v_mfma_f32_16x16x32_bf16 v[84:87], v[164:167], v[202:205], v[84:87]
	v_mfma_f32_16x16x32_bf16 v[80:83], v[178:181], v[202:205], v[80:83]
	v_mfma_f32_16x16x32_bf16 v[68:71], v[164:167], v[210:213], v[68:71]
	v_mfma_f32_16x16x32_bf16 v[64:67], v[178:181], v[210:213], v[64:67]
	s_barrier
	s_add_i32 s26, s52, s33
	s_mov_b32 m0, s26
	ds_read_b128 v[182:185], v177 offset:49152
	ds_read_b128 v[186:189], v177 offset:50176
	ds_read_b128 v[190:193], v177 offset:51200
	ds_read_b128 v[194:197], v177 offset:52224
	ds_read_b128 v[198:201], v177 offset:53248
	ds_read_b128 v[202:205], v177 offset:54272
	ds_read_b128 v[206:209], v177 offset:55296
	ds_read_b128 v[210:213], v177 offset:56320
	global_load_lds_dwordx4 v150, s[98:99]
	s_add_i32 m0, s26, 0x2000
	s_add_u32 s26, s30, 0xb0080
	s_addc_u32 s27, s31, 0
	s_add_i32 s30, s53, s33
	global_load_lds_dwordx4 v154, s[98:99]
	s_mov_b32 m0, s30
	s_nop 0
	global_load_lds_dwordx4 v150, s[26:27]
	s_add_i32 m0, s30, 0x2000
	s_nop 0
	global_load_lds_dwordx4 v154, s[26:27]
	s_mov_b32 m0, s48
	s_nop 0
	global_load_lds_dwordx4 v148, s[100:101]
	s_mov_b32 m0, s49
	s_nop 0
	global_load_lds_dwordx4 v152, s[100:101]
	s_waitcnt vmcnt(8)
	s_waitcnt lgkmcnt(0)
	s_barrier
	s_waitcnt lgkmcnt(0)
	v_mfma_f32_16x16x32_bf16 v[60:63], v[128:131], v[182:185], v[60:63]
	v_mfma_f32_16x16x32_bf16 v[56:59], v[136:139], v[182:185], v[56:59]
	v_mfma_f32_16x16x32_bf16 v[44:47], v[128:131], v[190:193], v[44:47]
	v_mfma_f32_16x16x32_bf16 v[40:43], v[136:139], v[190:193], v[40:43]
	v_mfma_f32_16x16x32_bf16 v[36:39], v[128:131], v[198:201], v[36:39]
	v_mfma_f32_16x16x32_bf16 v[32:35], v[136:139], v[198:201], v[32:35]
	v_mfma_f32_16x16x32_bf16 v[20:23], v[128:131], v[206:209], v[20:23]
	v_mfma_f32_16x16x32_bf16 v[16:19], v[136:139], v[206:209], v[16:19]
	v_mfma_f32_16x16x32_bf16 v[60:63], v[132:135], v[186:189], v[60:63]
	v_mfma_f32_16x16x32_bf16 v[56:59], v[140:143], v[186:189], v[56:59]
	v_mfma_f32_16x16x32_bf16 v[44:47], v[132:135], v[194:197], v[44:47]
	v_mfma_f32_16x16x32_bf16 v[40:43], v[140:143], v[194:197], v[40:43]
	v_mfma_f32_16x16x32_bf16 v[36:39], v[132:135], v[202:205], v[36:39]
	v_mfma_f32_16x16x32_bf16 v[32:35], v[140:143], v[202:205], v[32:35]
	v_mfma_f32_16x16x32_bf16 v[20:23], v[132:135], v[210:213], v[20:23]
	v_mfma_f32_16x16x32_bf16 v[16:19], v[140:143], v[210:213], v[16:19]
	v_mfma_f32_16x16x32_bf16 v[52:55], v[144:147], v[182:185], v[52:55]
	v_mfma_f32_16x16x32_bf16 v[48:51], v[168:171], v[182:185], v[48:51]
	v_mfma_f32_16x16x32_bf16 v[28:31], v[144:147], v[190:193], v[28:31]
	v_mfma_f32_16x16x32_bf16 v[24:27], v[168:171], v[190:193], v[24:27]
	v_mfma_f32_16x16x32_bf16 v[12:15], v[144:147], v[198:201], v[12:15]
	v_mfma_f32_16x16x32_bf16 v[8:11], v[168:171], v[198:201], v[8:11]
	v_mfma_f32_16x16x32_bf16 v[4:7], v[144:147], v[206:209], v[4:7]
	v_mfma_f32_16x16x32_bf16 v[0:3], v[168:171], v[206:209], v[0:3]
	v_mfma_f32_16x16x32_bf16 v[52:55], v[164:167], v[186:189], v[52:55]
	v_mfma_f32_16x16x32_bf16 v[48:51], v[178:181], v[186:189], v[48:51]
	v_mfma_f32_16x16x32_bf16 v[28:31], v[164:167], v[194:197], v[28:31]
	v_mfma_f32_16x16x32_bf16 v[24:27], v[178:181], v[194:197], v[24:27]
	v_mfma_f32_16x16x32_bf16 v[12:15], v[164:167], v[202:205], v[12:15]
	v_mfma_f32_16x16x32_bf16 v[8:11], v[178:181], v[202:205], v[8:11]
	v_mfma_f32_16x16x32_bf16 v[4:7], v[164:167], v[210:213], v[4:7]
	v_mfma_f32_16x16x32_bf16 v[0:3], v[178:181], v[210:213], v[0:3]
	s_barrier
	s_add_i32 s67, s67, 2
	s_add_u32 s65, s65, 0x100
	s_addc_u32 s66, s66, 0
	s_cmp_gt_u32 s67, 41
	s_mov_b64 s[26:27], s[28:29]
	s_cbranch_scc0 .LBB0_1137
	s_and_b64 vcc, exec, s[14:15]
	s_cbranch_vccz .LBB0_1140
	s_barrier

; __device__ __forceinline__ int lane_id_() { int l; asm volatile("v_mbcnt_lo_u32_b32 %0, -1, 0\n\tv_mbcnt_hi_u32_b32 %0, -1, %0" : "=v"(l)); return l; }
; #define PG8_STAGE(bufoff, gbase, voff) do { _Pragma("unroll") for (int _i = 0; _i < 2; ++_i) \
;         __builtin_amdgcn_global_load_lds((const unsigned*)((const char*)(gbase) + (voff)[_i]), (LAS unsigned*)(lds + (bufoff) + ldsw + _i * 8192), 16, 0, 0); } while (0)
; #define PG8_WAIT_V(n) asm volatile("s_waitcnt vmcnt(" #n ")" ::: "memory")
; template <class Epi, bool ALIGN_EPI, int K, int LDA, int LDB>
; __device__ __forceinline__ void gemm_phase(LAS unsigned char* lds, const int wid, const Gemm g, const StaticOrder& S, const Epi& E) {
;     const int lane = lane_id_(), tid = wid * 64 + lane, wr = wid >> 2, wc = wid & 3, fr = lane & 15, fq = lane >> 4;
;     constexpr int nt = K / BK;
;     unsigned voffA[2], voffB[2];
; #pragma unroll
;     for (int i = 0; i < 2; ++i) { int R, C; stage_rc(tid * 16 + i * 8192, R, C); const int Rb = Epi::PERM ? ((R & ~31) + perm32(R & 31)) : R;
;         voffA[i] = (unsigned)(R * LDA + C) * 2u; voffB[i] = (unsigned)(Rb * LDB + C) * 2u; }
;     constexpr size_t kstep = (size_t)(BK * 2);
;     constexpr size_t hA = (size_t)HALF * LDA * 2, hB = (size_t)HALF * LDB * 2;
;     constexpr size_t tA = 2 * hA, tB = 2 * hB;
;     const unsigned ldsw = (unsigned)wid * 1024u;
;     const int aoff = lds_byte(wr * 64 + fr, fq * 8), boff = lds_byte(wc * 32 + fr, fq * 8);
;     ...
;     Unit cur, nxt; int ui = 0;
;     if (!S.next(0, cur)) return;
;     f32x4 acc[2][2][4][2];
; #pragma unroll
;     for (int a = 0; a < 2; ++a)
; #pragma unroll
;         for (int b = 0; b < 2; ++b)
; #pragma unroll
;             for (int m = 0; m < 4; ++m)
; #pragma unroll
;                 for (int n = 0; n < 2; ++n) acc[a][b][m][n] = (f32x4){0.f, 0.f, 0.f, 0.f};
;     bf16x8 At[4][2], B0[2][2], B1[2][2];
;     const char* cA = (const char*)g.A + (size_t)cur.pm * tA; const char* cB = (const char*)g.Bt + (size_t)cur.pn * tB;
;     PG8_STAGE(PG8_SB(0, 0), cB, voffB); PG8_STAGE(PG8_SB(0, 1), cB + hB, voffB); PG8_STAGE(PG8_SA(0, 0), cA, voffA); PG8_STAGE(PG8_SA(0, 1), cA + hA, voffA);
;     if (wr == 1) PG8_BAR;
;     PG8_WAIT_V(2); PG8_BAR;
;     PG8_STAGE(PG8_SB(1, 0), cB + kstep, voffB); PG8_STAGE(PG8_SA(1, 0), cA + kstep, voffA); PG8_STAGE(PG8_SB(1, 1), cB + hB + kstep, voffB);
;     PG8_WAIT_V(6); PG8_BAR;
.LBB0_1267:
	s_add_u32 s0, s46, 0xe00000
	s_addc_u32 s1, s47, 0
	s_lshl_b32 s3, s50, 10
	s_waitcnt lgkmcnt(0)
	v_lshl_add_u32 v0, v8, 4, s3
	v_ashrrev_i32_e32 v1, 31, v0
	v_lshrrev_b32_e32 v1, 22, v1
	v_add_u32_e32 v1, v0, v1
	v_ashrrev_i32_e32 v9, 10, v1
	v_mul_i32_i24_e32 v1, 0x400, v9
	s_lshr_b32 s12, s86, 8
	v_sub_u32_e32 v1, v0, v1
	s_cmp_eq_u32 s12, 1
	v_lshrrev_b32_e32 v2, 4, v1
	s_cselect_b64 s[8:9], -1, 0
	s_ashr_i32 s31, s30, 31
	s_ashr_i32 s7, s6, 31
	v_bitop3_b32 v1, v2, v1, 32 bitop3:0x6c
	s_lshl_b64 s[4:5], s[30:31], 19
	s_lshl_b64 s[10:11], s[6:7], 19
	v_ashrrev_i32_e32 v3, 31, v1
	s_add_u32 s36, s0, s10
	v_lshrrev_b32_e32 v3, 26, v3
	s_addc_u32 s37, s1, s11
	s_add_i32 s31, s3, 0
	v_add_u32_e32 v3, v1, v3
	s_add_i32 m0, s31, 0x10000
	s_add_i32 s7, s31, 0x12000
	v_lshlrev_b32_e32 v2, 3, v9
	v_ashrrev_i32_e32 v10, 6, v3
	v_and_b32_e32 v3, 0xc0, v3
	s_add_u32 s10, s36, 0x40000
	v_and_b32_e32 v2, -16, v2
	v_sub_u32_e32 v1, v1, v3
	v_mov_b32_e32 v3, 1
	s_addc_u32 s11, s37, 0
	s_add_i32 s13, s31, 0x14000
	s_add_i32 s14, s31, 0x16000
	v_readlane_b32 s15, v254, 0
	v_add_u32_e32 v2, v10, v2
	v_ashrrev_i16_sdwa v1, v3, sext(v1) dst_sel:DWORD dst_unused:UNUSED_PAD src0_sel:DWORD src1_sel:BYTE_0
	s_add_u32 s34, s15, s4
	v_lshlrev_b32_e32 v4, 5, v9
	v_bfe_i32 v11, v1, 0, 16
	v_lshlrev_b32_e32 v1, 1, v2
	v_lshrrev_b32_e32 v5, 2, v2
	v_and_b32_e32 v6, 3, v10
	s_mov_b32 s15, 0x1fffe0
	v_and_b32_e32 v4, 32, v4
	v_and_b32_e32 v1, 24, v1
	v_and_b32_e32 v5, 4, v5
	v_and_or_b32 v6, v2, s15, v6
	v_or3_b32 v1, v6, v5, v1
	v_add_lshl_u32 v4, v4, v11, 1
	v_add_u32_e32 v0, 0x2000, v0
	v_lshl_add_u32 v130, v1, 11, v4
	v_ashrrev_i32_e32 v1, 31, v0
	v_lshrrev_b32_e32 v1, 22, v1
	v_add_u32_e32 v1, v0, v1
	v_ashrrev_i32_e32 v12, 10, v1
	v_mul_i32_i24_e32 v1, 0x400, v12
	v_sub_u32_e32 v0, v0, v1
	v_lshrrev_b32_e32 v1, 4, v0
	v_bitop3_b32 v0, v1, v0, 32 bitop3:0x6c
	v_lshl_add_u32 v128, v2, 11, v4
	v_ashrrev_i32_e32 v2, 31, v0
	v_lshrrev_b32_e32 v2, 26, v2
	v_add_u32_e32 v2, v0, v2
	v_ashrrev_i32_e32 v13, 6, v2
	v_and_b32_e32 v2, 0xffc0, v2
	v_sub_u32_e32 v0, v0, v2
	v_lshrrev_b16_e32 v2, 7, v0
	v_lshlrev_b32_e32 v1, 3, v12
	v_and_b32_e32 v2, 1, v2
	v_and_b32_e32 v1, -16, v1
	v_add_u16_e32 v0, v0, v2
	v_add_u32_e32 v1, v13, v1
	v_ashrrev_i16_sdwa v0, v3, sext(v0) dst_sel:DWORD dst_unused:UNUSED_PAD src0_sel:DWORD src1_sel:BYTE_0
	v_lshlrev_b32_e32 v4, 5, v12
	v_bfe_i32 v14, v0, 0, 16
	v_lshlrev_b32_e32 v0, 1, v1
	v_lshrrev_b32_e32 v2, 2, v1
	v_and_b32_e32 v3, 3, v13
	v_and_b32_e32 v4, 32, v4
	v_and_b32_e32 v0, 24, v0
	v_and_b32_e32 v2, 4, v2
	v_and_or_b32 v3, v1, s15, v3
	v_or3_b32 v0, v3, v2, v0
	v_add_lshl_u32 v2, v4, v14, 1
	v_lshl_add_u32 v134, v0, 11, v2
	global_load_lds_dwordx4 v130, s[36:37]
	s_mov_b32 m0, s7
	v_readlane_b32 s4, v254, 1
	global_load_lds_dwordx4 v134, s[36:37]
	s_mov_b32 m0, s13
	s_addc_u32 s35, s4, s5
	s_add_i32 s33, s31, 0x2000
	global_load_lds_dwordx4 v130, s[10:11]
	s_mov_b32 m0, s14
	s_add_u32 s4, s34, 0x40000
	global_load_lds_dwordx4 v134, s[10:11]
	s_mov_b32 m0, s31
	s_addc_u32 s5, s35, 0
	s_add_i32 s40, s31, 0x4000
	v_lshl_add_u32 v132, v1, 11, v2
	global_load_lds_dwordx4 v128, s[34:35]
	s_mov_b32 m0, s33
	s_add_i32 s41, s31, 0x6000
	global_load_lds_dwordx4 v132, s[34:35]
	s_mov_b32 m0, s40
	v_mov_b32_e32 v131, 0
	global_load_lds_dwordx4 v128, s[4:5]
	s_mov_b32 m0, s41
	v_mov_b32_e32 v135, v131
	global_load_lds_dwordx4 v132, s[4:5]
	v_mov_b32_e32 v129, v131
	v_mov_b32_e32 v133, v131
	s_mov_b32 s43, 0
	s_cmp_lg_u32 s12, 1
	v_lshl_add_u64 v[6:7], s[36:37], 0, v[130:131]
	v_lshl_add_u64 v[4:5], s[36:37], 0, v[134:135]
	v_lshl_add_u64 v[2:3], s[34:35], 0, v[128:129]
	v_lshl_add_u64 v[0:1], s[34:35], 0, v[132:133]
	s_cbranch_scc1 .LBB0_1269
	s_setprio 1
	s_barrier

; #define PG8_STAGE(bufoff, gbase, voff) do { _Pragma("unroll") for (int _i = 0; _i < 2; ++_i) \
;         __builtin_amdgcn_global_load_lds((const unsigned*)((const char*)(gbase) + (voff)[_i]), (LAS unsigned*)(lds + (bufoff) + ldsw + _i * 8192), 16, 0, 0); } while (0)
; #define PG8_LDA(dst, b, h) do { _Pragma("unroll") for (int m = 0; m < 4; ++m) _Pragma("unroll") for (int k = 0; k < 2; ++k) dst[m][k] = *(const LAS bf16x8*)(lds + PG8_SA(b, h) + aoff + m * 2048 + k * 1024); } while (0)
; #define PG8_LDB(dst, b, h) do { _Pragma("unroll") for (int n = 0; n < 2; ++n) _Pragma("unroll") for (int k = 0; k < 2; ++k) dst[n][k] = *(const LAS bf16x8*)(lds + PG8_SB(b, h) + boff + n * 2048 + k * 1024); } while (0)
; #define PG8_MMA(ai, bj, At, Bt) do { __builtin_amdgcn_s_setprio(1); _Pragma("unroll") for (int m = 0; m < 4; ++m) _Pragma("unroll") for (int n = 0; n < 2; ++n) _Pragma("unroll") for (int k = 0; k < 2; ++k) \
;         acc[ai][bj][m][n] = __builtin_amdgcn_mfma_f32_16x16x32_bf16(Bt[n][k], At[m][k], acc[ai][bj][m][n], 0, 0, 0); __builtin_amdgcn_s_setprio(0); } while (0)
; #define PG8_WAIT_V(n) asm volatile("s_waitcnt vmcnt(" #n ")" ::: "memory")
; #define PG8_WAIT_L(n) asm volatile("s_waitcnt lgkmcnt(" #n ")" ::: "memory")
; #define PG8_BAR __builtin_amdgcn_s_barrier()
; #define PG8_SCHED __builtin_amdgcn_sched_barrier(0)
; template <class Epi, bool ALIGN_EPI, int K, int LDA, int LDB>
; __device__ __forceinline__ void gemm_phase(LAS unsigned char* lds, const int wid, const Gemm g, const StaticOrder& S, const Epi& E) {
;     ...
;             const bool last = (t == nt - 2);
;             const char* a1 = cA + (size_t)(t + 1) * kstep;
;             const char* a2 = last ? nA : cA + (size_t)(t + 2) * kstep; const char* b2 = last ? nB : cB + (size_t)(t + 2) * kstep;
;             const char* a3 = a2 + kstep; const char* b3 = b2 + kstep;
;             PG8_LDB(B0, 0, 0); PG8_LDB(B1, 0, 1); PG8_SCHED; PG8_LDA(At, 0, 0); PG8_STAGE(PG8_SA(1, 1), a1 + hA, voffA);
;             PG8_WAIT_V(8); PG8_WAIT_L(0); PG8_BAR; PG8_MMA(0, 0, At, B0); PG8_MMA(0, 1, At, B1); PG8_BAR; PG8_SCHED;
;             PG8_LDA(At, 0, 1); PG8_STAGE(PG8_SB(0, 0), b2, voffB); PG8_STAGE(PG8_SB(0, 1), b2 + hB, voffB); PG8_STAGE(PG8_SA(0, 0), a2, voffA);
;             PG8_WAIT_V(8); PG8_WAIT_L(0); PG8_BAR; PG8_MMA(1, 0, At, B0); PG8_MMA(1, 1, At, B1); PG8_BAR; PG8_SCHED;
.LBB0_1279:
	ds_read_b128 v[144:147], v151
	ds_read_b128 v[154:157], v151 offset:1024
	ds_read_b128 v[158:161], v151 offset:2048
	ds_read_b128 v[162:165], v151 offset:3072
	ds_read_b128 v[166:169], v152
	ds_read_b128 v[170:173], v152 offset:1024
	ds_read_b128 v[174:177], v152 offset:2048
	ds_read_b128 v[178:181], v152 offset:3072
	s_add_u32 s36, s34, 0xfffc0080
	s_addc_u32 s37, s35, -1
	s_cmp_eq_u32 s61, 12
	s_cselect_b32 s39, s7, s37
	s_cselect_b32 s38, s25, s36
	s_cselect_b32 s37, s23, s60
	s_cselect_b32 s36, s42, s59
	s_add_i32 m0, s31, 0xc000
	ds_read_b128 v[182:185], v153
	ds_read_b128 v[186:189], v153 offset:1024
	ds_read_b128 v[190:193], v153 offset:2048
	ds_read_b128 v[194:197], v153 offset:3072
	ds_read_b128 v[198:201], v153 offset:4096
	ds_read_b128 v[202:205], v153 offset:5120
	ds_read_b128 v[206:209], v153 offset:6144
	ds_read_b128 v[210:213], v153 offset:7168
	global_load_lds_dwordx4 v136, s[34:35]
	s_add_i32 m0, s31, 0xe000
	s_nop 0
	global_load_lds_dwordx4 v138, s[34:35]
	s_waitcnt vmcnt(8)
	s_waitcnt lgkmcnt(0)
	s_barrier
	s_waitcnt lgkmcnt(0)
	v_mfma_f32_16x16x32_bf16 v[124:127], v[144:147], v[182:185], v[124:127]
	v_mfma_f32_16x16x32_bf16 v[120:123], v[158:161], v[182:185], v[120:123]
	v_mfma_f32_16x16x32_bf16 v[108:111], v[144:147], v[190:193], v[108:111]
	v_mfma_f32_16x16x32_bf16 v[104:107], v[158:161], v[190:193], v[104:107]
	v_mfma_f32_16x16x32_bf16 v[92:95], v[144:147], v[198:201], v[92:95]
	v_mfma_f32_16x16x32_bf16 v[88:91], v[158:161], v[198:201], v[88:91]
	v_mfma_f32_16x16x32_bf16 v[76:79], v[144:147], v[206:209], v[76:79]
	v_mfma_f32_16x16x32_bf16 v[72:75], v[158:161], v[206:209], v[72:75]
	v_mfma_f32_16x16x32_bf16 v[124:127], v[154:157], v[186:189], v[124:127]
	v_mfma_f32_16x16x32_bf16 v[120:123], v[162:165], v[186:189], v[120:123]
	v_mfma_f32_16x16x32_bf16 v[108:111], v[154:157], v[194:197], v[108:111]
	v_mfma_f32_16x16x32_bf16 v[104:107], v[162:165], v[194:197], v[104:107]
	v_mfma_f32_16x16x32_bf16 v[92:95], v[154:157], v[202:205], v[92:95]
	v_mfma_f32_16x16x32_bf16 v[88:91], v[162:165], v[202:205], v[88:91]
	v_mfma_f32_16x16x32_bf16 v[76:79], v[154:157], v[210:213], v[76:79]
	v_mfma_f32_16x16x32_bf16 v[72:75], v[162:165], v[210:213], v[72:75]
	v_mfma_f32_16x16x32_bf16 v[116:119], v[166:169], v[182:185], v[116:119]
	v_mfma_f32_16x16x32_bf16 v[112:115], v[174:177], v[182:185], v[112:115]
	v_mfma_f32_16x16x32_bf16 v[100:103], v[166:169], v[190:193], v[100:103]
	v_mfma_f32_16x16x32_bf16 v[96:99], v[174:177], v[190:193], v[96:99]
	v_mfma_f32_16x16x32_bf16 v[84:87], v[166:169], v[198:201], v[84:87]
	v_mfma_f32_16x16x32_bf16 v[80:83], v[174:177], v[198:201], v[80:83]
	v_mfma_f32_16x16x32_bf16 v[68:71], v[166:169], v[206:209], v[68:71]
	v_mfma_f32_16x16x32_bf16 v[64:67], v[174:177], v[206:209], v[64:67]
	v_mfma_f32_16x16x32_bf16 v[116:119], v[170:173], v[186:189], v[116:119]
	v_mfma_f32_16x16x32_bf16 v[112:115], v[178:181], v[186:189], v[112:115]
	v_mfma_f32_16x16x32_bf16 v[100:103], v[170:173], v[194:197], v[100:103]
	v_mfma_f32_16x16x32_bf16 v[96:99], v[178:181], v[194:197], v[96:99]
	v_mfma_f32_16x16x32_bf16 v[84:87], v[170:173], v[202:205], v[84:87]
	v_mfma_f32_16x16x32_bf16 v[80:83], v[178:181], v[202:205], v[80:83]
	v_mfma_f32_16x16x32_bf16 v[68:71], v[170:173], v[210:213], v[68:71]
	v_mfma_f32_16x16x32_bf16 v[64:67], v[178:181], v[210:213], v[64:67]
	s_barrier
	s_add_u32 s98, s36, s12
	s_addc_u32 s99, s37, s13
	s_add_u32 s100, s38, s12
	s_addc_u32 s101, s39, s13
	s_add_i32 s52, s57, s3
	s_mov_b32 m0, s52
	ds_read_b128 v[182:185], v153 offset:16384
	ds_read_b128 v[186:189], v153 offset:17408
	ds_read_b128 v[190:193], v153 offset:18432
	ds_read_b128 v[194:197], v153 offset:19456
	ds_read_b128 v[198:201], v153 offset:20480
	ds_read_b128 v[202:205], v153 offset:21504
	ds_read_b128 v[206:209], v153 offset:22528
	ds_read_b128 v[210:213], v153 offset:23552
	global_load_lds_dwordx4 v130, s[36:37]
	s_add_i32 m0, s52, 0x2000
	s_add_u32 s62, s36, 0x40000
	s_addc_u32 s63, s37, 0
	s_add_i32 s52, s58, s3
	global_load_lds_dwordx4 v134, s[36:37]
	s_mov_b32 m0, s52
	s_nop 0
	global_load_lds_dwordx4 v130, s[62:63]
	s_add_i32 m0, s52, 0x2000
	s_nop 0
	global_load_lds_dwordx4 v134, s[62:63]
	s_mov_b32 m0, s31
	s_nop 0
	global_load_lds_dwordx4 v128, s[38:39]
	s_mov_b32 m0, s33
	s_nop 0
	global_load_lds_dwordx4 v132, s[38:39]
	s_waitcnt vmcnt(8)
	s_waitcnt lgkmcnt(0)
	s_barrier
	s_waitcnt lgkmcnt(0)
	v_mfma_f32_16x16x32_bf16 v[60:63], v[144:147], v[182:185], v[60:63]
	v_mfma_f32_16x16x32_bf16 v[56:59], v[158:161], v[182:185], v[56:59]
	v_mfma_f32_16x16x32_bf16 v[44:47], v[144:147], v[190:193], v[44:47]
	v_mfma_f32_16x16x32_bf16 v[40:43], v[158:161], v[190:193], v[40:43]
	v_mfma_f32_16x16x32_bf16 v[28:31], v[144:147], v[198:201], v[28:31]
	v_mfma_f32_16x16x32_bf16 v[24:27], v[158:161], v[198:201], v[24:27]
	v_mfma_f32_16x16x32_bf16 v[12:15], v[144:147], v[206:209], v[12:15]
	v_mfma_f32_16x16x32_bf16 v[8:11], v[158:161], v[206:209], v[8:11]
	v_mfma_f32_16x16x32_bf16 v[60:63], v[154:157], v[186:189], v[60:63]
	v_mfma_f32_16x16x32_bf16 v[56:59], v[162:165], v[186:189], v[56:59]
	v_mfma_f32_16x16x32_bf16 v[44:47], v[154:157], v[194:197], v[44:47]
	v_mfma_f32_16x16x32_bf16 v[40:43], v[162:165], v[194:197], v[40:43]
	v_mfma_f32_16x16x32_bf16 v[28:31], v[154:157], v[202:205], v[28:31]
	v_mfma_f32_16x16x32_bf16 v[24:27], v[162:165], v[202:205], v[24:27]
	v_mfma_f32_16x16x32_bf16 v[12:15], v[154:157], v[210:213], v[12:15]
	v_mfma_f32_16x16x32_bf16 v[8:11], v[162:165], v[210:213], v[8:11]
	v_mfma_f32_16x16x32_bf16 v[52:55], v[166:169], v[182:185], v[52:55]
	v_mfma_f32_16x16x32_bf16 v[48:51], v[174:177], v[182:185], v[48:51]
	v_mfma_f32_16x16x32_bf16 v[36:39], v[166:169], v[190:193], v[36:39]
	v_mfma_f32_16x16x32_bf16 v[32:35], v[174:177], v[190:193], v[32:35]
	v_mfma_f32_16x16x32_bf16 v[20:23], v[166:169], v[198:201], v[20:23]
	v_mfma_f32_16x16x32_bf16 v[16:19], v[174:177], v[198:201], v[16:19]
	v_mfma_f32_16x16x32_bf16 v[4:7], v[166:169], v[206:209], v[4:7]
	v_mfma_f32_16x16x32_bf16 v[0:3], v[174:177], v[206:209], v[0:3]
	v_mfma_f32_16x16x32_bf16 v[52:55], v[170:173], v[186:189], v[52:55]
	v_mfma_f32_16x16x32_bf16 v[48:51], v[178:181], v[186:189], v[48:51]
	v_mfma_f32_16x16x32_bf16 v[36:39], v[170:173], v[194:197], v[36:39]
	v_mfma_f32_16x16x32_bf16 v[32:35], v[178:181], v[194:197], v[32:35]
	v_mfma_f32_16x16x32_bf16 v[20:23], v[170:173], v[202:205], v[20:23]
	v_mfma_f32_16x16x32_bf16 v[16:19], v[178:181], v[202:205], v[16:19]
	v_mfma_f32_16x16x32_bf16 v[4:7], v[170:173], v[210:213], v[4:7]
	v_mfma_f32_16x16x32_bf16 v[0:3], v[178:181], v[210:213], v[0:3]
	s_barrier
; #define PG8_STAGE(bufoff, gbase, voff) do { _Pragma("unroll") for (int _i = 0; _i < 2; ++_i) \
;         __builtin_amdgcn_global_load_lds((const unsigned*)((const char*)(gbase) + (voff)[_i]), (LAS unsigned*)(lds + (bufoff) + ldsw + _i * 8192), 16, 0, 0); } while (0)
; #define PG8_LDA(dst, b, h) do { _Pragma("unroll") for (int m = 0; m < 4; ++m) _Pragma("unroll") for (int k = 0; k < 2; ++k) dst[m][k] = *(const LAS bf16x8*)(lds + PG8_SA(b, h) + aoff + m * 2048 + k * 1024); } while (0)
; #define PG8_LDB(dst, b, h) do { _Pragma("unroll") for (int n = 0; n < 2; ++n) _Pragma("unroll") for (int k = 0; k < 2; ++k) dst[n][k] = *(const LAS bf16x8*)(lds + PG8_SB(b, h) + boff + n * 2048 + k * 1024); } while (0)
; #define PG8_MMA(ai, bj, At, Bt) do { __builtin_amdgcn_s_setprio(1); _Pragma("unroll") for (int m = 0; m < 4; ++m) _Pragma("unroll") for (int n = 0; n < 2; ++n) _Pragma("unroll") for (int k = 0; k < 2; ++k) \
;         acc[ai][bj][m][n] = __builtin_amdgcn_mfma_f32_16x16x32_bf16(Bt[n][k], At[m][k], acc[ai][bj][m][n], 0, 0, 0); __builtin_amdgcn_s_setprio(0); } while (0)
; #define PG8_WAIT_V(n) asm volatile("s_waitcnt vmcnt(" #n ")" ::: "memory")
; #define PG8_WAIT_L(n) asm volatile("s_waitcnt lgkmcnt(" #n ")" ::: "memory")
; #define PG8_BAR __builtin_amdgcn_s_barrier()
; #define PG8_SCHED __builtin_amdgcn_sched_barrier(0)
; template <class Epi, bool ALIGN_EPI, int K, int LDA, int LDB>
; __device__ __forceinline__ void gemm_phase(LAS unsigned char* lds, const int wid, const Gemm g, const StaticOrder& S, const Epi& E) {
;     ...
;             PG8_LDB(B0, 1, 0); PG8_LDB(B1, 1, 1); PG8_SCHED; PG8_LDA(At, 1, 0); PG8_STAGE(PG8_SA(0, 1), a2 + hA, voffA);
;             PG8_WAIT_V(8); PG8_WAIT_L(0); PG8_BAR; PG8_MMA(0, 0, At, B0); PG8_MMA(0, 1, At, B1); PG8_BAR; PG8_SCHED;
;             PG8_LDA(At, 1, 1); PG8_STAGE(PG8_SB(1, 0), b3, voffB); PG8_STAGE(PG8_SB(1, 1), b3 + hB, voffB); PG8_STAGE(PG8_SA(1, 0), a3, voffA);
;             PG8_WAIT_V(8); PG8_WAIT_L(0); PG8_BAR; PG8_MMA(1, 0, At, B0); PG8_MMA(1, 1, At, B1); PG8_BAR; PG8_SCHED;
;         }
;         if constexpr (ALIGN_EPI) { if (wr == 0) PG8_BAR; }
	s_add_i32 s52, 0, 0x18000
	s_add_i32 s53, 0, 0x1c000
	v_add_u32_e32 v162, s52, v150
	v_add_u32_e32 v178, s53, v150
	ds_read_b128 v[144:147], v162
	ds_read_b128 v[154:157], v162 offset:1024
	ds_read_b128 v[158:161], v162 offset:2048
	ds_read_b128 v[162:165], v162 offset:3072
	ds_read_b128 v[166:169], v178
	ds_read_b128 v[170:173], v178 offset:1024
	ds_read_b128 v[174:177], v178 offset:2048
	ds_read_b128 v[178:181], v178 offset:3072
	s_add_u32 s38, s38, 0x40000
	s_addc_u32 s39, s39, 0
	s_mov_b32 m0, s40
	ds_read_b128 v[182:185], v153 offset:32768
	ds_read_b128 v[186:189], v153 offset:33792
	ds_read_b128 v[190:193], v153 offset:34816
	ds_read_b128 v[194:197], v153 offset:35840
	ds_read_b128 v[198:201], v153 offset:36864
	ds_read_b128 v[202:205], v153 offset:37888
	ds_read_b128 v[206:209], v153 offset:38912
	ds_read_b128 v[210:213], v153 offset:39936
	global_load_lds_dwordx4 v128, s[38:39]
	s_mov_b32 m0, s41
	s_nop 0
	global_load_lds_dwordx4 v132, s[38:39]
	s_waitcnt vmcnt(8)
	s_waitcnt lgkmcnt(0)
	s_barrier
	s_waitcnt lgkmcnt(0)
	v_mfma_f32_16x16x32_bf16 v[124:127], v[144:147], v[182:185], v[124:127]
	v_mfma_f32_16x16x32_bf16 v[120:123], v[158:161], v[182:185], v[120:123]
	v_mfma_f32_16x16x32_bf16 v[108:111], v[144:147], v[190:193], v[108:111]
	v_mfma_f32_16x16x32_bf16 v[104:107], v[158:161], v[190:193], v[104:107]
	v_mfma_f32_16x16x32_bf16 v[92:95], v[144:147], v[198:201], v[92:95]
	v_mfma_f32_16x16x32_bf16 v[88:91], v[158:161], v[198:201], v[88:91]
	v_mfma_f32_16x16x32_bf16 v[76:79], v[144:147], v[206:209], v[76:79]
	v_mfma_f32_16x16x32_bf16 v[72:75], v[158:161], v[206:209], v[72:75]
	v_mfma_f32_16x16x32_bf16 v[124:127], v[154:157], v[186:189], v[124:127]
	v_mfma_f32_16x16x32_bf16 v[120:123], v[162:165], v[186:189], v[120:123]
	v_mfma_f32_16x16x32_bf16 v[108:111], v[154:157], v[194:197], v[108:111]
	v_mfma_f32_16x16x32_bf16 v[104:107], v[162:165], v[194:197], v[104:107]
	v_mfma_f32_16x16x32_bf16 v[92:95], v[154:157], v[202:205], v[92:95]
	v_mfma_f32_16x16x32_bf16 v[88:91], v[162:165], v[202:205], v[88:91]
	v_mfma_f32_16x16x32_bf16 v[76:79], v[154:157], v[210:213], v[76:79]
	v_mfma_f32_16x16x32_bf16 v[72:75], v[162:165], v[210:213], v[72:75]
	v_mfma_f32_16x16x32_bf16 v[116:119], v[166:169], v[182:185], v[116:119]
	v_mfma_f32_16x16x32_bf16 v[112:115], v[174:177], v[182:185], v[112:115]
	v_mfma_f32_16x16x32_bf16 v[100:103], v[166:169], v[190:193], v[100:103]
	v_mfma_f32_16x16x32_bf16 v[96:99], v[174:177], v[190:193], v[96:99]
	v_mfma_f32_16x16x32_bf16 v[84:87], v[166:169], v[198:201], v[84:87]
	v_mfma_f32_16x16x32_bf16 v[80:83], v[174:177], v[198:201], v[80:83]
	v_mfma_f32_16x16x32_bf16 v[68:71], v[166:169], v[206:209], v[68:71]
	v_mfma_f32_16x16x32_bf16 v[64:67], v[174:177], v[206:209], v[64:67]
	v_mfma_f32_16x16x32_bf16 v[116:119], v[170:173], v[186:189], v[116:119]
	v_mfma_f32_16x16x32_bf16 v[112:115], v[178:181], v[186:189], v[112:115]
	v_mfma_f32_16x16x32_bf16 v[100:103], v[170:173], v[194:197], v[100:103]
	v_mfma_f32_16x16x32_bf16 v[96:99], v[178:181], v[194:197], v[96:99]
	v_mfma_f32_16x16x32_bf16 v[84:87], v[170:173], v[202:205], v[84:87]
	v_mfma_f32_16x16x32_bf16 v[80:83], v[178:181], v[202:205], v[80:83]
	v_mfma_f32_16x16x32_bf16 v[68:71], v[170:173], v[210:213], v[68:71]
	v_mfma_f32_16x16x32_bf16 v[64:67], v[178:181], v[210:213], v[64:67]
	s_barrier
	s_add_i32 s38, s52, s3
	s_mov_b32 m0, s38
	ds_read_b128 v[182:185], v153 offset:49152
	ds_read_b128 v[186:189], v153 offset:50176
	ds_read_b128 v[190:193], v153 offset:51200
	ds_read_b128 v[194:197], v153 offset:52224
	ds_read_b128 v[198:201], v153 offset:53248
	ds_read_b128 v[202:205], v153 offset:54272
	ds_read_b128 v[206:209], v153 offset:55296
	ds_read_b128 v[210:213], v153 offset:56320
	global_load_lds_dwordx4 v130, s[98:99]
	s_add_i32 m0, s38, 0x2000
	s_add_u32 s36, s36, 0x40080
	s_addc_u32 s37, s37, 0
	s_add_i32 s38, s53, s3
	global_load_lds_dwordx4 v134, s[98:99]
	s_mov_b32 m0, s38
	s_nop 0
	global_load_lds_dwordx4 v130, s[36:37]
	s_add_i32 m0, s38, 0x2000
	s_nop 0
	global_load_lds_dwordx4 v134, s[36:37]
	s_mov_b32 m0, s55
	s_nop 0
	global_load_lds_dwordx4 v128, s[100:101]
	s_mov_b32 m0, s56
	s_nop 0
	global_load_lds_dwordx4 v132, s[100:101]
	s_waitcnt vmcnt(8)
	s_waitcnt lgkmcnt(0)
	s_barrier
	s_waitcnt lgkmcnt(0)
	v_mfma_f32_16x16x32_bf16 v[60:63], v[144:147], v[182:185], v[60:63]
	v_mfma_f32_16x16x32_bf16 v[56:59], v[158:161], v[182:185], v[56:59]
	v_mfma_f32_16x16x32_bf16 v[44:47], v[144:147], v[190:193], v[44:47]
	v_mfma_f32_16x16x32_bf16 v[40:43], v[158:161], v[190:193], v[40:43]
	v_mfma_f32_16x16x32_bf16 v[28:31], v[144:147], v[198:201], v[28:31]
	v_mfma_f32_16x16x32_bf16 v[24:27], v[158:161], v[198:201], v[24:27]
	v_mfma_f32_16x16x32_bf16 v[12:15], v[144:147], v[206:209], v[12:15]
	v_mfma_f32_16x16x32_bf16 v[8:11], v[158:161], v[206:209], v[8:11]
	v_mfma_f32_16x16x32_bf16 v[60:63], v[154:157], v[186:189], v[60:63]
	v_mfma_f32_16x16x32_bf16 v[56:59], v[162:165], v[186:189], v[56:59]
	v_mfma_f32_16x16x32_bf16 v[44:47], v[154:157], v[194:197], v[44:47]
	v_mfma_f32_16x16x32_bf16 v[40:43], v[162:165], v[194:197], v[40:43]
	v_mfma_f32_16x16x32_bf16 v[28:31], v[154:157], v[202:205], v[28:31]
	v_mfma_f32_16x16x32_bf16 v[24:27], v[162:165], v[202:205], v[24:27]
	v_mfma_f32_16x16x32_bf16 v[12:15], v[154:157], v[210:213], v[12:15]
	v_mfma_f32_16x16x32_bf16 v[8:11], v[162:165], v[210:213], v[8:11]
	v_mfma_f32_16x16x32_bf16 v[52:55], v[166:169], v[182:185], v[52:55]
	v_mfma_f32_16x16x32_bf16 v[48:51], v[174:177], v[182:185], v[48:51]
	v_mfma_f32_16x16x32_bf16 v[36:39], v[166:169], v[190:193], v[36:39]
	v_mfma_f32_16x16x32_bf16 v[32:35], v[174:177], v[190:193], v[32:35]
	v_mfma_f32_16x16x32_bf16 v[20:23], v[166:169], v[198:201], v[20:23]
	v_mfma_f32_16x16x32_bf16 v[16:19], v[174:177], v[198:201], v[16:19]
	v_mfma_f32_16x16x32_bf16 v[4:7], v[166:169], v[206:209], v[4:7]
	v_mfma_f32_16x16x32_bf16 v[0:3], v[174:177], v[206:209], v[0:3]
	v_mfma_f32_16x16x32_bf16 v[52:55], v[170:173], v[186:189], v[52:55]
	v_mfma_f32_16x16x32_bf16 v[48:51], v[178:181], v[186:189], v[48:51]
	v_mfma_f32_16x16x32_bf16 v[36:39], v[170:173], v[194:197], v[36:39]
	v_mfma_f32_16x16x32_bf16 v[32:35], v[178:181], v[194:197], v[32:35]
	v_mfma_f32_16x16x32_bf16 v[20:23], v[170:173], v[202:205], v[20:23]
	v_mfma_f32_16x16x32_bf16 v[16:19], v[178:181], v[202:205], v[16:19]
	v_mfma_f32_16x16x32_bf16 v[4:7], v[170:173], v[210:213], v[4:7]
	v_mfma_f32_16x16x32_bf16 v[0:3], v[178:181], v[210:213], v[0:3]
	s_barrier
	s_add_i32 s61, s61, 2
	s_add_u32 s34, s34, 0x100
	s_addc_u32 s35, s35, 0
	s_add_u32 s59, s59, 0x100
	s_addc_u32 s60, s60, 0
	s_cmp_gt_u32 s61, 13
	s_cbranch_scc0 .LBB0_1279
	s_and_b64 vcc, exec, s[10:11]
	s_cbranch_vccz .LBB0_1282
	s_barrier

; #define PG8_WAIT_V(n) asm volatile("s_waitcnt vmcnt(" #n ")" ::: "memory")
; #define PG8_BAR __builtin_amdgcn_s_barrier()
; template <class Epi, bool ALIGN_EPI, int K, int LDA, int LDB>
; __device__ __forceinline__ void gemm_phase(LAS unsigned char* lds, const int wid, const Gemm g, const StaticOrder& S, const Epi& E) {
;     ...
;     PG8_WAIT_V(0);
;     if constexpr (!ALIGN_EPI) { if (wr == 0) PG8_BAR; }
;     PG8_BAR;
.LBB0_1317:
	s_setprio 0
	s_waitcnt vmcnt(0)
	s_barrier
	s_cmp_lg_u32 s85, 12
	s_cbranch_scc0 .LBB0_1373

;     __device__ bool next(int i, Unit& u) const {
;         const long L = (long)i * G + c; if (L >= nwg) return false;
;         int wgid = (int)L; { const int q = nwg / NXCD, r = nwg % NXCD, xcd = wgid % NXCD, off = wgid / NXCD; wgid = (xcd < r ? xcd * (q + 1) : r * (q + 1) + (xcd - r) * q) + off; }
;         const int nig = WGM * nN, gid = wgid / nig, fm = gid * WGM, gsz = (nM - fm) < WGM ? (nM - fm) : WGM;
;         u.pm = fm + ((wgid % nig) % gsz); u.pn = (wgid % nig) / gsz; return true;
;     }
; template <class Epi, bool ALIGN_EPI, int K, int LDA, int LDB>
; __device__ __forceinline__ void gemm_phase(LAS unsigned char* lds, const int wid, const Gemm g, const StaticOrder& S, const Epi& E) {
;     const int lane = lane_id_(), tid = wid * 64 + lane, wr = wid >> 2, wc = wid & 3, fr = lane & 15, fq = lane >> 4;
;     constexpr int nt = K / BK;
;     unsigned voffA[2], voffB[2];
; #pragma unroll
;     for (int i = 0; i < 2; ++i) { int R, C; stage_rc(tid * 16 + i * 8192, R, C); const int Rb = Epi::PERM ? ((R & ~31) + perm32(R & 31)) : R;
;         voffA[i] = (unsigned)(R * LDA + C) * 2u; voffB[i] = (unsigned)(Rb * LDB + C) * 2u; }
;     constexpr size_t kstep = (size_t)(BK * 2);
;     constexpr size_t hA = (size_t)HALF * LDA * 2, hB = (size_t)HALF * LDB * 2;
;     constexpr size_t tA = 2 * hA, tB = 2 * hB;
;     const unsigned ldsw = (unsigned)wid * 1024u;
;     const int aoff = lds_byte(wr * 64 + fr, fq * 8), boff = lds_byte(wc * 32 + fr, fq * 8);
;     ...
;     Unit cur, nxt; int ui = 0;
;     if (!S.next(0, cur)) return;
;     f32x4 acc[2][2][4][2];
; #pragma unroll
;     for (int a = 0; a < 2; ++a)
; #pragma unroll
;         for (int b = 0; b < 2; ++b)
; #pragma unroll
;             for (int m = 0; m < 4; ++m)
; #pragma unroll
;                 for (int n = 0; n < 2; ++n) acc[a][b][m][n] = (f32x4){0.f, 0.f, 0.f, 0.f};
;     bf16x8 At[4][2], B0[2][2], B1[2][2];
;     const char* cA = (const char*)g.A + (size_t)cur.pm * tA; const char* cB = (const char*)g.Bt + (size_t)cur.pn * tB;
;     PG8_STAGE(PG8_SB(0, 0), cB, voffB); PG8_STAGE(PG8_SB(0, 1), cB + hB, voffB); PG8_STAGE(PG8_SA(0, 0), cA, voffA); PG8_STAGE(PG8_SA(0, 1), cA + hA, voffA);
;     if (wr == 1) PG8_BAR;
;     PG8_WAIT_V(2); PG8_BAR;
;     PG8_STAGE(PG8_SB(1, 0), cB + kstep, voffB); PG8_STAGE(PG8_SA(1, 0), cA + kstep, voffA); PG8_STAGE(PG8_SB(1, 1), cB + hB + kstep, voffB);
.LBB0_1465:
	s_ashr_i32 s4, s1, 3
	s_add_u32 s1, s46, 0x1600000
	s_addc_u32 s3, s47, 0
	s_lshl_b32 s33, s50, 10
	s_waitcnt lgkmcnt(0)
	v_lshl_add_u32 v0, v8, 4, s33
	v_ashrrev_i32_e32 v1, 31, v0
	v_lshrrev_b32_e32 v1, 22, v1
	v_add_u32_e32 v1, v0, v1
	v_ashrrev_i32_e32 v9, 10, v1
	v_mul_i32_i24_e32 v1, 0x400, v9
	v_sub_u32_e32 v1, v0, v1
	v_lshrrev_b32_e32 v2, 4, v1
	v_bitop3_b32 v1, v2, v1, 32 bitop3:0x6c
	v_ashrrev_i32_e32 v3, 31, v1
	v_lshrrev_b32_e32 v3, 26, v3
	v_add_u32_e32 v3, v1, v3
	v_lshlrev_b32_e32 v2, 3, v9
	v_ashrrev_i32_e32 v10, 6, v3
	v_and_b32_e32 v3, 0xc0, v3
	v_and_b32_e32 v2, -16, v2
	v_sub_u32_e32 v1, v1, v3
	v_mov_b32_e32 v3, 1
	v_add_u32_e32 v2, v10, v2
	v_ashrrev_i16_sdwa v1, v3, sext(v1) dst_sel:DWORD dst_unused:UNUSED_PAD src0_sel:DWORD src1_sel:BYTE_0
	v_lshlrev_b32_e32 v4, 5, v9
	v_bfe_i32 v11, v1, 0, 16
	v_lshlrev_b32_e32 v1, 1, v2
	v_lshrrev_b32_e32 v5, 2, v2
	v_and_b32_e32 v6, 3, v10
	s_mov_b32 s7, 0x1fffe0
	v_and_b32_e32 v4, 32, v4
	v_and_b32_e32 v1, 24, v1
	v_and_b32_e32 v5, 4, v5
	v_and_or_b32 v6, v2, s7, v6
	v_or3_b32 v1, v6, v5, v1
	v_add_lshl_u32 v4, v4, v11, 1
	v_add_u32_e32 v0, 0x2000, v0
	v_lshl_add_u32 v150, v1, 11, v4
	v_ashrrev_i32_e32 v1, 31, v0
	v_lshrrev_b32_e32 v1, 22, v1
	v_add_u32_e32 v1, v0, v1
	v_ashrrev_i32_e32 v12, 10, v1
	v_mul_i32_i24_e32 v1, 0x400, v12
	v_sub_u32_e32 v0, v0, v1
	v_lshrrev_b32_e32 v1, 4, v0
	v_bitop3_b32 v0, v1, v0, 32 bitop3:0x6c
	v_lshl_add_u32 v148, v2, 11, v4
	v_ashrrev_i32_e32 v2, 31, v0
	v_lshrrev_b32_e32 v2, 26, v2
	v_add_u32_e32 v2, v0, v2
	v_ashrrev_i32_e32 v13, 6, v2
	v_and_b32_e32 v2, 0xffc0, v2
	v_sub_u32_e32 v0, v0, v2
	v_lshrrev_b16_e32 v2, 7, v0
	s_add_i32 s4, s6, s4
	v_lshlrev_b32_e32 v1, 3, v12
	v_and_b32_e32 v2, 1, v2
	s_ashr_i32 s6, s4, 31
	v_and_b32_e32 v1, -16, v1
	v_add_u16_e32 v0, v0, v2
	s_lshr_b32 s6, s6, 27
	v_add_u32_e32 v1, v13, v1
	v_ashrrev_i16_sdwa v0, v3, sext(v0) dst_sel:DWORD dst_unused:UNUSED_PAD src0_sel:DWORD src1_sel:BYTE_0
	v_and_b32_e32 v3, 3, v13
	s_add_i32 s6, s4, s6
	v_and_or_b32 v3, v1, s7, v3
	s_ashr_i32 s7, s6, 5
	s_andn2_b32 s6, s6, 31
	s_sub_i32 s6, s4, s6
	s_bfe_i32 s4, s6, 0x80000
	s_bfe_u32 s4, s4, 0x3000c
	s_add_i32 s8, s6, s4
	s_bfe_i32 s4, s8, 0x80000
	s_and_b32 s8, s8, 0xf8
	s_sub_i32 s6, s6, s8
	s_lshl_b32 s7, s7, 3
	s_sext_i32_i16 s4, s4
	s_sext_i32_i8 s6, s6
	s_lshr_b32 s5, s86, 8
	s_lshr_b32 s4, s4, 3
	s_add_i32 s30, s7, s6
	s_ashr_i32 s31, s30, 31
	s_bfe_i64 s[8:9], s[4:5], 0x100000
	s_lshl_b64 s[6:7], s[30:31], 19
	s_lshl_b64 s[8:9], s[8:9], 19
	s_add_u32 s36, s1, s8
	v_lshlrev_b32_e32 v4, 5, v12
	v_bfe_i32 v14, v0, 0, 16
	v_lshlrev_b32_e32 v0, 1, v1
	v_lshrrev_b32_e32 v2, 2, v1
	s_addc_u32 s37, s3, s9
	s_add_i32 s40, s33, 0
	v_and_b32_e32 v4, 32, v4
	v_and_b32_e32 v0, 24, v0
	v_and_b32_e32 v2, 4, v2
	s_add_i32 m0, s40, 0x10000
	v_or3_b32 v0, v3, v2, v0
	v_add_lshl_u32 v2, v4, v14, 1
	global_load_lds_dwordx4 v150, s[36:37]
	s_add_i32 m0, s40, 0x12000
	v_lshl_add_u32 v154, v0, 11, v2
	s_add_u32 s8, s36, 0x40000
	global_load_lds_dwordx4 v154, s[36:37]
	s_addc_u32 s9, s37, 0
	s_add_i32 m0, s40, 0x14000
	v_lshl_add_u32 v152, v1, 11, v2
	global_load_lds_dwordx4 v150, s[8:9]
	s_add_i32 m0, s40, 0x16000
	v_mov_b32_e32 v151, 0
	global_load_lds_dwordx4 v154, s[8:9]
	v_readlane_b32 s8, v254, 0
	s_add_u32 s34, s8, s6
	v_readlane_b32 s6, v254, 1
	s_addc_u32 s35, s6, s7
	s_add_i32 s41, s40, 0x2000
	s_mov_b32 m0, s40
	s_add_u32 s6, s34, 0x40000
	global_load_lds_dwordx4 v148, s[34:35]
	s_mov_b32 m0, s41
	s_addc_u32 s7, s35, 0
	s_add_i32 s43, s40, 0x4000
	global_load_lds_dwordx4 v152, s[34:35]
	s_mov_b32 m0, s43
	s_add_i32 s48, s40, 0x6000
	global_load_lds_dwordx4 v148, s[6:7]
	s_mov_b32 m0, s48
	v_mov_b32_e32 v155, v151
	global_load_lds_dwordx4 v152, s[6:7]
	v_mov_b32_e32 v149, v151
	v_mov_b32_e32 v153, v151
	s_cmp_eq_u32 s5, 1
	s_mov_b32 s7, 0
	v_lshl_add_u64 v[6:7], s[36:37], 0, v[150:151]
	v_lshl_add_u64 v[2:3], s[36:37], 0, v[154:155]
	s_mov_b64 s[8:9], 0x40000
	v_lshl_add_u64 v[0:1], s[34:35], 0, v[148:149]
	s_cselect_b64 s[10:11], -1, 0
	s_cmp_lg_u32 s5, 1
	v_lshl_add_u64 v[4:5], s[34:35], 0, v[152:153]
	s_cbranch_scc1 .LBB0_1467
	s_setprio 1
	s_barrier

; #define PG8_STAGE(bufoff, gbase, voff) do { _Pragma("unroll") for (int _i = 0; _i < 2; ++_i) \
;         __builtin_amdgcn_global_load_lds((const unsigned*)((const char*)(gbase) + (voff)[_i]), (LAS unsigned*)(lds + (bufoff) + ldsw + _i * 8192), 16, 0, 0); } while (0)
; #define PG8_LDA(dst, b, h) do { _Pragma("unroll") for (int m = 0; m < 4; ++m) _Pragma("unroll") for (int k = 0; k < 2; ++k) dst[m][k] = *(const LAS bf16x8*)(lds + PG8_SA(b, h) + aoff + m * 2048 + k * 1024); } while (0)
; #define PG8_LDB(dst, b, h) do { _Pragma("unroll") for (int n = 0; n < 2; ++n) _Pragma("unroll") for (int k = 0; k < 2; ++k) dst[n][k] = *(const LAS bf16x8*)(lds + PG8_SB(b, h) + boff + n * 2048 + k * 1024); } while (0)
; #define PG8_MMA(ai, bj, At, Bt) do { __builtin_amdgcn_s_setprio(1); _Pragma("unroll") for (int m = 0; m < 4; ++m) _Pragma("unroll") for (int n = 0; n < 2; ++n) _Pragma("unroll") for (int k = 0; k < 2; ++k) \
;         acc[ai][bj][m][n] = __builtin_amdgcn_mfma_f32_16x16x32_bf16(Bt[n][k], At[m][k], acc[ai][bj][m][n], 0, 0, 0); __builtin_amdgcn_s_setprio(0); } while (0)
; #define PG8_WAIT_V(n) asm volatile("s_waitcnt vmcnt(" #n ")" ::: "memory")
; #define PG8_WAIT_L(n) asm volatile("s_waitcnt lgkmcnt(" #n ")" ::: "memory")
; #define PG8_BAR __builtin_amdgcn_s_barrier()
; #define PG8_SCHED __builtin_amdgcn_sched_barrier(0)
; template <class Epi, bool ALIGN_EPI, int K, int LDA, int LDB>
; __device__ __forceinline__ void gemm_phase(LAS unsigned char* lds, const int wid, const Gemm g, const StaticOrder& S, const Epi& E) {
;     ...
;             const bool last = (t == nt - 2);
;             const char* a1 = cA + (size_t)(t + 1) * kstep;
;             const char* a2 = last ? nA : cA + (size_t)(t + 2) * kstep; const char* b2 = last ? nB : cB + (size_t)(t + 2) * kstep;
;             const char* a3 = a2 + kstep; const char* b3 = b2 + kstep;
;             PG8_LDB(B0, 0, 0); PG8_LDB(B1, 0, 1); PG8_SCHED; PG8_LDA(At, 0, 0); PG8_STAGE(PG8_SA(1, 1), a1 + hA, voffA);
;             PG8_WAIT_V(8); PG8_WAIT_L(0); PG8_BAR; PG8_MMA(0, 0, At, B0); PG8_MMA(0, 1, At, B1); PG8_BAR; PG8_SCHED;
;             PG8_LDA(At, 0, 1); PG8_STAGE(PG8_SB(0, 0), b2, voffB); PG8_STAGE(PG8_SB(0, 1), b2 + hB, voffB); PG8_STAGE(PG8_SA(0, 0), a2, voffA);
;             PG8_WAIT_V(8); PG8_WAIT_L(0); PG8_BAR; PG8_MMA(1, 0, At, B0); PG8_MMA(1, 1, At, B1); PG8_BAR; PG8_SCHED;
.LBB0_1477:
	ds_read_b128 v[128:131], v175
	ds_read_b128 v[132:135], v175 offset:1024
	ds_read_b128 v[136:139], v175 offset:2048
	ds_read_b128 v[140:143], v175 offset:3072
	ds_read_b128 v[144:147], v176
	ds_read_b128 v[164:167], v176 offset:1024
	ds_read_b128 v[168:171], v176 offset:2048
	ds_read_b128 v[178:181], v176 offset:3072
	s_add_u32 s36, s34, 0xfffc0080
	s_addc_u32 s37, s35, -1
	s_cmp_eq_u32 s69, 12
	s_cselect_b32 s39, s25, s37
	s_cselect_b32 s38, s42, s36
	s_cselect_b32 s37, s23, s68
	s_cselect_b32 s36, s66, s67
	s_add_i32 m0, s40, 0xc000
	ds_read_b128 v[182:185], v177
	ds_read_b128 v[186:189], v177 offset:1024
	ds_read_b128 v[190:193], v177 offset:2048
	ds_read_b128 v[194:197], v177 offset:3072
	ds_read_b128 v[198:201], v177 offset:4096
	ds_read_b128 v[202:205], v177 offset:5120
	ds_read_b128 v[206:209], v177 offset:6144
	ds_read_b128 v[210:213], v177 offset:7168
	global_load_lds_dwordx4 v156, s[34:35]
	s_add_i32 m0, s40, 0xe000
	s_nop 0
	global_load_lds_dwordx4 v158, s[34:35]
	s_waitcnt vmcnt(8)
	s_waitcnt lgkmcnt(0)
	s_barrier
	s_waitcnt lgkmcnt(0)
	v_mfma_f32_16x16x32_bf16 v[124:127], v[128:131], v[182:185], v[124:127]
	v_mfma_f32_16x16x32_bf16 v[116:119], v[136:139], v[182:185], v[116:119]
	v_mfma_f32_16x16x32_bf16 v[120:123], v[128:131], v[190:193], v[120:123]
	v_mfma_f32_16x16x32_bf16 v[112:115], v[136:139], v[190:193], v[112:115]
	v_mfma_f32_16x16x32_bf16 v[92:95], v[128:131], v[198:201], v[92:95]
	v_mfma_f32_16x16x32_bf16 v[88:91], v[136:139], v[198:201], v[88:91]
	v_mfma_f32_16x16x32_bf16 v[76:79], v[128:131], v[206:209], v[76:79]
	v_mfma_f32_16x16x32_bf16 v[72:75], v[136:139], v[206:209], v[72:75]
	v_mfma_f32_16x16x32_bf16 v[124:127], v[132:135], v[186:189], v[124:127]
	v_mfma_f32_16x16x32_bf16 v[116:119], v[140:143], v[186:189], v[116:119]
	v_mfma_f32_16x16x32_bf16 v[120:123], v[132:135], v[194:197], v[120:123]
	v_mfma_f32_16x16x32_bf16 v[112:115], v[140:143], v[194:197], v[112:115]
	v_mfma_f32_16x16x32_bf16 v[92:95], v[132:135], v[202:205], v[92:95]
	v_mfma_f32_16x16x32_bf16 v[88:91], v[140:143], v[202:205], v[88:91]
	v_mfma_f32_16x16x32_bf16 v[76:79], v[132:135], v[210:213], v[76:79]
	v_mfma_f32_16x16x32_bf16 v[72:75], v[140:143], v[210:213], v[72:75]
	v_mfma_f32_16x16x32_bf16 v[108:111], v[144:147], v[182:185], v[108:111]
	v_mfma_f32_16x16x32_bf16 v[104:107], v[168:171], v[182:185], v[104:107]
	v_mfma_f32_16x16x32_bf16 v[100:103], v[144:147], v[190:193], v[100:103]
	v_mfma_f32_16x16x32_bf16 v[96:99], v[168:171], v[190:193], v[96:99]
	v_mfma_f32_16x16x32_bf16 v[84:87], v[144:147], v[198:201], v[84:87]
	v_mfma_f32_16x16x32_bf16 v[80:83], v[168:171], v[198:201], v[80:83]
	v_mfma_f32_16x16x32_bf16 v[68:71], v[144:147], v[206:209], v[68:71]
	v_mfma_f32_16x16x32_bf16 v[64:67], v[168:171], v[206:209], v[64:67]
	v_mfma_f32_16x16x32_bf16 v[108:111], v[164:167], v[186:189], v[108:111]
	v_mfma_f32_16x16x32_bf16 v[104:107], v[178:181], v[186:189], v[104:107]
	v_mfma_f32_16x16x32_bf16 v[100:103], v[164:167], v[194:197], v[100:103]
	v_mfma_f32_16x16x32_bf16 v[96:99], v[178:181], v[194:197], v[96:99]
	v_mfma_f32_16x16x32_bf16 v[84:87], v[164:167], v[202:205], v[84:87]
	v_mfma_f32_16x16x32_bf16 v[80:83], v[178:181], v[202:205], v[80:83]
	v_mfma_f32_16x16x32_bf16 v[68:71], v[164:167], v[210:213], v[68:71]
	v_mfma_f32_16x16x32_bf16 v[64:67], v[178:181], v[210:213], v[64:67]
	s_barrier
	s_add_u32 s98, s36, s12
	s_addc_u32 s99, s37, s13
	s_add_u32 s100, s38, s12
	s_addc_u32 s101, s39, s13
	s_add_i32 s52, s58, s33
	s_mov_b32 m0, s52
	ds_read_b128 v[182:185], v177 offset:16384
	ds_read_b128 v[186:189], v177 offset:17408
	ds_read_b128 v[190:193], v177 offset:18432
	ds_read_b128 v[194:197], v177 offset:19456
	ds_read_b128 v[198:201], v177 offset:20480
	ds_read_b128 v[202:205], v177 offset:21504
	ds_read_b128 v[206:209], v177 offset:22528
	ds_read_b128 v[210:213], v177 offset:23552
	global_load_lds_dwordx4 v150, s[36:37]
	s_add_i32 m0, s52, 0x2000
	s_add_u32 s70, s36, 0x40000
	s_addc_u32 s71, s37, 0
	s_add_i32 s52, s59, s33
	global_load_lds_dwordx4 v154, s[36:37]
	s_mov_b32 m0, s52
	s_nop 0
	global_load_lds_dwordx4 v150, s[70:71]
	s_add_i32 m0, s52, 0x2000
	s_nop 0
	global_load_lds_dwordx4 v154, s[70:71]
	s_mov_b32 m0, s40
	s_nop 0
	global_load_lds_dwordx4 v148, s[38:39]
	s_mov_b32 m0, s41
	s_nop 0
	global_load_lds_dwordx4 v152, s[38:39]
	s_waitcnt vmcnt(8)
	s_waitcnt lgkmcnt(0)
	s_barrier
	s_waitcnt lgkmcnt(0)
	v_mfma_f32_16x16x32_bf16 v[60:63], v[128:131], v[182:185], v[60:63]
	v_mfma_f32_16x16x32_bf16 v[56:59], v[136:139], v[182:185], v[56:59]
	v_mfma_f32_16x16x32_bf16 v[44:47], v[128:131], v[190:193], v[44:47]
	v_mfma_f32_16x16x32_bf16 v[40:43], v[136:139], v[190:193], v[40:43]
	v_mfma_f32_16x16x32_bf16 v[36:39], v[128:131], v[198:201], v[36:39]
	v_mfma_f32_16x16x32_bf16 v[32:35], v[136:139], v[198:201], v[32:35]
	v_mfma_f32_16x16x32_bf16 v[20:23], v[128:131], v[206:209], v[20:23]
	v_mfma_f32_16x16x32_bf16 v[16:19], v[136:139], v[206:209], v[16:19]
	v_mfma_f32_16x16x32_bf16 v[60:63], v[132:135], v[186:189], v[60:63]
	v_mfma_f32_16x16x32_bf16 v[56:59], v[140:143], v[186:189], v[56:59]
	v_mfma_f32_16x16x32_bf16 v[44:47], v[132:135], v[194:197], v[44:47]
	v_mfma_f32_16x16x32_bf16 v[40:43], v[140:143], v[194:197], v[40:43]
	v_mfma_f32_16x16x32_bf16 v[36:39], v[132:135], v[202:205], v[36:39]
	v_mfma_f32_16x16x32_bf16 v[32:35], v[140:143], v[202:205], v[32:35]
	v_mfma_f32_16x16x32_bf16 v[20:23], v[132:135], v[210:213], v[20:23]
	v_mfma_f32_16x16x32_bf16 v[16:19], v[140:143], v[210:213], v[16:19]
	v_mfma_f32_16x16x32_bf16 v[52:55], v[144:147], v[182:185], v[52:55]
	v_mfma_f32_16x16x32_bf16 v[48:51], v[168:171], v[182:185], v[48:51]
	v_mfma_f32_16x16x32_bf16 v[28:31], v[144:147], v[190:193], v[28:31]
	v_mfma_f32_16x16x32_bf16 v[24:27], v[168:171], v[190:193], v[24:27]
	v_mfma_f32_16x16x32_bf16 v[12:15], v[144:147], v[198:201], v[12:15]
	v_mfma_f32_16x16x32_bf16 v[8:11], v[168:171], v[198:201], v[8:11]
	v_mfma_f32_16x16x32_bf16 v[4:7], v[144:147], v[206:209], v[4:7]
	v_mfma_f32_16x16x32_bf16 v[0:3], v[168:171], v[206:209], v[0:3]
	v_mfma_f32_16x16x32_bf16 v[52:55], v[164:167], v[186:189], v[52:55]
	v_mfma_f32_16x16x32_bf16 v[48:51], v[178:181], v[186:189], v[48:51]
	v_mfma_f32_16x16x32_bf16 v[28:31], v[164:167], v[194:197], v[28:31]
	v_mfma_f32_16x16x32_bf16 v[24:27], v[178:181], v[194:197], v[24:27]
	v_mfma_f32_16x16x32_bf16 v[12:15], v[164:167], v[202:205], v[12:15]
	v_mfma_f32_16x16x32_bf16 v[8:11], v[178:181], v[202:205], v[8:11]
	v_mfma_f32_16x16x32_bf16 v[4:7], v[164:167], v[210:213], v[4:7]
	v_mfma_f32_16x16x32_bf16 v[0:3], v[178:181], v[210:213], v[0:3]
	s_barrier
; #define PG8_STAGE(bufoff, gbase, voff) do { _Pragma("unroll") for (int _i = 0; _i < 2; ++_i) \
;         __builtin_amdgcn_global_load_lds((const unsigned*)((const char*)(gbase) + (voff)[_i]), (LAS unsigned*)(lds + (bufoff) + ldsw + _i * 8192), 16, 0, 0); } while (0)
; #define PG8_LDA(dst, b, h) do { _Pragma("unroll") for (int m = 0; m < 4; ++m) _Pragma("unroll") for (int k = 0; k < 2; ++k) dst[m][k] = *(const LAS bf16x8*)(lds + PG8_SA(b, h) + aoff + m * 2048 + k * 1024); } while (0)
; #define PG8_LDB(dst, b, h) do { _Pragma("unroll") for (int n = 0; n < 2; ++n) _Pragma("unroll") for (int k = 0; k < 2; ++k) dst[n][k] = *(const LAS bf16x8*)(lds + PG8_SB(b, h) + boff + n * 2048 + k * 1024); } while (0)
; #define PG8_MMA(ai, bj, At, Bt) do { __builtin_amdgcn_s_setprio(1); _Pragma("unroll") for (int m = 0; m < 4; ++m) _Pragma("unroll") for (int n = 0; n < 2; ++n) _Pragma("unroll") for (int k = 0; k < 2; ++k) \
;         acc[ai][bj][m][n] = __builtin_amdgcn_mfma_f32_16x16x32_bf16(Bt[n][k], At[m][k], acc[ai][bj][m][n], 0, 0, 0); __builtin_amdgcn_s_setprio(0); } while (0)
; #define PG8_WAIT_V(n) asm volatile("s_waitcnt vmcnt(" #n ")" ::: "memory")
; #define PG8_WAIT_L(n) asm volatile("s_waitcnt lgkmcnt(" #n ")" ::: "memory")
; #define PG8_BAR __builtin_amdgcn_s_barrier()
; #define PG8_SCHED __builtin_amdgcn_sched_barrier(0)
; template <class Epi, bool ALIGN_EPI, int K, int LDA, int LDB>
; __device__ __forceinline__ void gemm_phase(LAS unsigned char* lds, const int wid, const Gemm g, const StaticOrder& S, const Epi& E) {
;     ...
;             PG8_LDB(B0, 1, 0); PG8_LDB(B1, 1, 1); PG8_SCHED; PG8_LDA(At, 1, 0); PG8_STAGE(PG8_SA(0, 1), a2 + hA, voffA);
;             PG8_WAIT_V(8); PG8_WAIT_L(0); PG8_BAR; PG8_MMA(0, 0, At, B0); PG8_MMA(0, 1, At, B1); PG8_BAR; PG8_SCHED;
;             PG8_LDA(At, 1, 1); PG8_STAGE(PG8_SB(1, 0), b3, voffB); PG8_STAGE(PG8_SB(1, 1), b3 + hB, voffB); PG8_STAGE(PG8_SA(1, 0), a3, voffA);
;             PG8_WAIT_V(8); PG8_WAIT_L(0); PG8_BAR; PG8_MMA(1, 0, At, B0); PG8_MMA(1, 1, At, B1); PG8_BAR; PG8_SCHED;
;         }
;         if constexpr (ALIGN_EPI) { if (wr == 0) PG8_BAR; }
	s_add_i32 s52, 0, 0x18000
	s_add_i32 s53, 0, 0x1c000
	v_add_u32_e32 v140, s52, v174
	v_add_u32_e32 v178, s53, v174
	ds_read_b128 v[128:131], v140
	ds_read_b128 v[132:135], v140 offset:1024
	ds_read_b128 v[136:139], v140 offset:2048
	ds_read_b128 v[140:143], v140 offset:3072
	ds_read_b128 v[144:147], v178
	ds_read_b128 v[164:167], v178 offset:1024
	ds_read_b128 v[168:171], v178 offset:2048
	ds_read_b128 v[178:181], v178 offset:3072
	s_add_u32 s38, s38, 0x40000
	s_addc_u32 s39, s39, 0
	s_mov_b32 m0, s43
	ds_read_b128 v[182:185], v177 offset:32768
	ds_read_b128 v[186:189], v177 offset:33792
	ds_read_b128 v[190:193], v177 offset:34816
	ds_read_b128 v[194:197], v177 offset:35840
	ds_read_b128 v[198:201], v177 offset:36864
	ds_read_b128 v[202:205], v177 offset:37888
	ds_read_b128 v[206:209], v177 offset:38912
	ds_read_b128 v[210:213], v177 offset:39936
	global_load_lds_dwordx4 v148, s[38:39]
	s_mov_b32 m0, s48
	s_nop 0
	global_load_lds_dwordx4 v152, s[38:39]
	s_waitcnt vmcnt(8)
	s_waitcnt lgkmcnt(0)
	s_barrier
	s_waitcnt lgkmcnt(0)
	v_mfma_f32_16x16x32_bf16 v[124:127], v[128:131], v[182:185], v[124:127]
	v_mfma_f32_16x16x32_bf16 v[116:119], v[136:139], v[182:185], v[116:119]
	v_mfma_f32_16x16x32_bf16 v[120:123], v[128:131], v[190:193], v[120:123]
	v_mfma_f32_16x16x32_bf16 v[112:115], v[136:139], v[190:193], v[112:115]
	v_mfma_f32_16x16x32_bf16 v[92:95], v[128:131], v[198:201], v[92:95]
	v_mfma_f32_16x16x32_bf16 v[88:91], v[136:139], v[198:201], v[88:91]
	v_mfma_f32_16x16x32_bf16 v[76:79], v[128:131], v[206:209], v[76:79]
	v_mfma_f32_16x16x32_bf16 v[72:75], v[136:139], v[206:209], v[72:75]
	v_mfma_f32_16x16x32_bf16 v[124:127], v[132:135], v[186:189], v[124:127]
	v_mfma_f32_16x16x32_bf16 v[116:119], v[140:143], v[186:189], v[116:119]
	v_mfma_f32_16x16x32_bf16 v[120:123], v[132:135], v[194:197], v[120:123]
	v_mfma_f32_16x16x32_bf16 v[112:115], v[140:143], v[194:197], v[112:115]
	v_mfma_f32_16x16x32_bf16 v[92:95], v[132:135], v[202:205], v[92:95]
	v_mfma_f32_16x16x32_bf16 v[88:91], v[140:143], v[202:205], v[88:91]
	v_mfma_f32_16x16x32_bf16 v[76:79], v[132:135], v[210:213], v[76:79]
	v_mfma_f32_16x16x32_bf16 v[72:75], v[140:143], v[210:213], v[72:75]
	v_mfma_f32_16x16x32_bf16 v[108:111], v[144:147], v[182:185], v[108:111]
	v_mfma_f32_16x16x32_bf16 v[104:107], v[168:171], v[182:185], v[104:107]
	v_mfma_f32_16x16x32_bf16 v[100:103], v[144:147], v[190:193], v[100:103]
	v_mfma_f32_16x16x32_bf16 v[96:99], v[168:171], v[190:193], v[96:99]
	v_mfma_f32_16x16x32_bf16 v[84:87], v[144:147], v[198:201], v[84:87]
	v_mfma_f32_16x16x32_bf16 v[80:83], v[168:171], v[198:201], v[80:83]
	v_mfma_f32_16x16x32_bf16 v[68:71], v[144:147], v[206:209], v[68:71]
	v_mfma_f32_16x16x32_bf16 v[64:67], v[168:171], v[206:209], v[64:67]
	v_mfma_f32_16x16x32_bf16 v[108:111], v[164:167], v[186:189], v[108:111]
	v_mfma_f32_16x16x32_bf16 v[104:107], v[178:181], v[186:189], v[104:107]
	v_mfma_f32_16x16x32_bf16 v[100:103], v[164:167], v[194:197], v[100:103]
	v_mfma_f32_16x16x32_bf16 v[96:99], v[178:181], v[194:197], v[96:99]
	v_mfma_f32_16x16x32_bf16 v[84:87], v[164:167], v[202:205], v[84:87]
	v_mfma_f32_16x16x32_bf16 v[80:83], v[178:181], v[202:205], v[80:83]
	v_mfma_f32_16x16x32_bf16 v[68:71], v[164:167], v[210:213], v[68:71]
	v_mfma_f32_16x16x32_bf16 v[64:67], v[178:181], v[210:213], v[64:67]
	s_barrier
	s_add_i32 s38, s52, s33
	s_mov_b32 m0, s38
	ds_read_b128 v[182:185], v177 offset:49152
	ds_read_b128 v[186:189], v177 offset:50176
	ds_read_b128 v[190:193], v177 offset:51200
	ds_read_b128 v[194:197], v177 offset:52224
	ds_read_b128 v[198:201], v177 offset:53248
	ds_read_b128 v[202:205], v177 offset:54272
	ds_read_b128 v[206:209], v177 offset:55296
	ds_read_b128 v[210:213], v177 offset:56320
	global_load_lds_dwordx4 v150, s[98:99]
	s_add_i32 m0, s38, 0x2000
	s_add_u32 s36, s36, 0x40080
	s_addc_u32 s37, s37, 0
	s_add_i32 s38, s53, s33
	global_load_lds_dwordx4 v154, s[98:99]
	s_mov_b32 m0, s38
	s_nop 0
	global_load_lds_dwordx4 v150, s[36:37]
	s_add_i32 m0, s38, 0x2000
	s_nop 0
	global_load_lds_dwordx4 v154, s[36:37]
	s_mov_b32 m0, s55
	s_nop 0
	global_load_lds_dwordx4 v148, s[100:101]
	s_mov_b32 m0, s56
	s_nop 0
	global_load_lds_dwordx4 v152, s[100:101]
	s_waitcnt vmcnt(8)
	s_waitcnt lgkmcnt(0)
	s_barrier
	s_waitcnt lgkmcnt(0)
	v_mfma_f32_16x16x32_bf16 v[60:63], v[128:131], v[182:185], v[60:63]
	v_mfma_f32_16x16x32_bf16 v[56:59], v[136:139], v[182:185], v[56:59]
	v_mfma_f32_16x16x32_bf16 v[44:47], v[128:131], v[190:193], v[44:47]
	v_mfma_f32_16x16x32_bf16 v[40:43], v[136:139], v[190:193], v[40:43]
	v_mfma_f32_16x16x32_bf16 v[36:39], v[128:131], v[198:201], v[36:39]
	v_mfma_f32_16x16x32_bf16 v[32:35], v[136:139], v[198:201], v[32:35]
	v_mfma_f32_16x16x32_bf16 v[20:23], v[128:131], v[206:209], v[20:23]
	v_mfma_f32_16x16x32_bf16 v[16:19], v[136:139], v[206:209], v[16:19]
	v_mfma_f32_16x16x32_bf16 v[60:63], v[132:135], v[186:189], v[60:63]
	v_mfma_f32_16x16x32_bf16 v[56:59], v[140:143], v[186:189], v[56:59]
	v_mfma_f32_16x16x32_bf16 v[44:47], v[132:135], v[194:197], v[44:47]
	v_mfma_f32_16x16x32_bf16 v[40:43], v[140:143], v[194:197], v[40:43]
	v_mfma_f32_16x16x32_bf16 v[36:39], v[132:135], v[202:205], v[36:39]
	v_mfma_f32_16x16x32_bf16 v[32:35], v[140:143], v[202:205], v[32:35]
	v_mfma_f32_16x16x32_bf16 v[20:23], v[132:135], v[210:213], v[20:23]
	v_mfma_f32_16x16x32_bf16 v[16:19], v[140:143], v[210:213], v[16:19]
	v_mfma_f32_16x16x32_bf16 v[52:55], v[144:147], v[182:185], v[52:55]
	v_mfma_f32_16x16x32_bf16 v[48:51], v[168:171], v[182:185], v[48:51]
	v_mfma_f32_16x16x32_bf16 v[28:31], v[144:147], v[190:193], v[28:31]
	v_mfma_f32_16x16x32_bf16 v[24:27], v[168:171], v[190:193], v[24:27]
	v_mfma_f32_16x16x32_bf16 v[12:15], v[144:147], v[198:201], v[12:15]
	v_mfma_f32_16x16x32_bf16 v[8:11], v[168:171], v[198:201], v[8:11]
	v_mfma_f32_16x16x32_bf16 v[4:7], v[144:147], v[206:209], v[4:7]
	v_mfma_f32_16x16x32_bf16 v[0:3], v[168:171], v[206:209], v[0:3]
	v_mfma_f32_16x16x32_bf16 v[52:55], v[164:167], v[186:189], v[52:55]
	v_mfma_f32_16x16x32_bf16 v[48:51], v[178:181], v[186:189], v[48:51]
	v_mfma_f32_16x16x32_bf16 v[28:31], v[164:167], v[194:197], v[28:31]
	v_mfma_f32_16x16x32_bf16 v[24:27], v[178:181], v[194:197], v[24:27]
	v_mfma_f32_16x16x32_bf16 v[12:15], v[164:167], v[202:205], v[12:15]
	v_mfma_f32_16x16x32_bf16 v[8:11], v[178:181], v[202:205], v[8:11]
	v_mfma_f32_16x16x32_bf16 v[4:7], v[164:167], v[210:213], v[4:7]
	v_mfma_f32_16x16x32_bf16 v[0:3], v[178:181], v[210:213], v[0:3]
	s_barrier
	s_add_i32 s69, s69, 2
	s_add_u32 s34, s34, 0x100
	s_addc_u32 s35, s35, 0
	s_add_u32 s67, s67, 0x100
	s_addc_u32 s68, s68, 0
	s_cmp_gt_u32 s69, 13
	s_cbranch_scc0 .LBB0_1477
	s_and_b64 vcc, exec, s[14:15]
	s_cbranch_vccz .LBB0_1480
	s_barrier

;     __device__ bool next(int i, Unit& u) const {
;         const long L = (long)i * G + c; if (L >= nwg) return false;
;         int wgid = (int)L; { const int q = nwg / NXCD, r = nwg % NXCD, xcd = wgid % NXCD, off = wgid / NXCD; wgid = (xcd < r ? xcd * (q + 1) : r * (q + 1) + (xcd - r) * q) + off; }
;         const int nig = WGM * nN, gid = wgid / nig, fm = gid * WGM, gsz = (nM - fm) < WGM ? (nM - fm) : WGM;
;         u.pm = fm + ((wgid % nig) % gsz); u.pn = (wgid % nig) / gsz; return true;
;     }
; template <class Epi, bool ALIGN_EPI, int K, int LDA, int LDB>
; __device__ __forceinline__ void gemm_phase(LAS unsigned char* lds, const int wid, const Gemm g, const StaticOrder& S, const Epi& E) {
;     const int lane = lane_id_(), tid = wid * 64 + lane, wr = wid >> 2, wc = wid & 3, fr = lane & 15, fq = lane >> 4;
;     constexpr int nt = K / BK;
;     unsigned voffA[2], voffB[2];
; #pragma unroll
;     for (int i = 0; i < 2; ++i) { int R, C; stage_rc(tid * 16 + i * 8192, R, C); const int Rb = Epi::PERM ? ((R & ~31) + perm32(R & 31)) : R;
;         voffA[i] = (unsigned)(R * LDA + C) * 2u; voffB[i] = (unsigned)(Rb * LDB + C) * 2u; }
;     constexpr size_t kstep = (size_t)(BK * 2);
;     constexpr size_t hA = (size_t)HALF * LDA * 2, hB = (size_t)HALF * LDB * 2;
;     constexpr size_t tA = 2 * hA, tB = 2 * hB;
;     const unsigned ldsw = (unsigned)wid * 1024u;
;     const int aoff = lds_byte(wr * 64 + fr, fq * 8), boff = lds_byte(wc * 32 + fr, fq * 8);
;     ...
;     Unit cur, nxt; int ui = 0;
;     if (!S.next(0, cur)) return;
;     f32x4 acc[2][2][4][2];
; #pragma unroll
;     for (int a = 0; a < 2; ++a)
; #pragma unroll
;         for (int b = 0; b < 2; ++b)
; #pragma unroll
;             for (int m = 0; m < 4; ++m)
; #pragma unroll
;                 for (int n = 0; n < 2; ++n) acc[a][b][m][n] = (f32x4){0.f, 0.f, 0.f, 0.f};
;     bf16x8 At[4][2], B0[2][2], B1[2][2];
;     const char* cA = (const char*)g.A + (size_t)cur.pm * tA; const char* cB = (const char*)g.Bt + (size_t)cur.pn * tB;
;     PG8_STAGE(PG8_SB(0, 0), cB, voffB); PG8_STAGE(PG8_SB(0, 1), cB + hB, voffB); PG8_STAGE(PG8_SA(0, 0), cA, voffA); PG8_STAGE(PG8_SA(0, 1), cA + hA, voffA);
;     if (wr == 1) PG8_BAR;
;     PG8_WAIT_V(2); PG8_BAR;
;     PG8_STAGE(PG8_SB(1, 0), cB + kstep, voffB); PG8_STAGE(PG8_SA(1, 0), cA + kstep, voffA); PG8_STAGE(PG8_SB(1, 1), cB + hB + kstep, voffB);
.LBB0_1602:
	s_cmp_lt_i32 s84, 16
	s_cselect_b64 s[0:1], -1, 0
	s_cmp_gt_i32 s85, 15
	s_cselect_b64 s[4:5], -1, 0
	s_and_b64 s[0:1], s[0:1], s[4:5]
	s_andn2_b64 vcc, exec, s[0:1]
	s_cbranch_vccnz .LBB0_1675
	s_mov_b64 s[0:1], s[88:89]
	s_cmpk_lt_i32 s2, 0x1600
	v_mbcnt_lo_u32_b32 v8, -1, 0
	v_mbcnt_hi_u32_b32 v8, -1, v8
	s_cbranch_scc0 .LBB0_1619
	s_add_u32 s0, s46, 0x2300000
	s_addc_u32 s1, s47, 0
	s_lshr_b32 s5, s86, 8
	s_lshl_b32 s3, s50, 10
	s_cmp_eq_u32 s5, 1
	s_cselect_b64 s[6:7], -1, 0
	s_ashr_i32 s28, s2, 31
	s_lshr_b32 s4, s28, 29
	s_add_i32 s4, s2, s4
	s_ashr_i32 s8, s4, 3
	s_and_b32 s4, s4, -8
	s_sub_i32 s4, s2, s4
	s_cmp_lt_i32 s4, 0
	s_movk_i32 s29, 0x2c1
	s_cselect_b32 s9, s29, 0x2c0
	s_mul_i32 s4, s4, s9
	s_add_i32 s4, s4, s8
	s_mul_hi_i32 s8, s4, 0x2e8ba2e9
	s_lshr_b32 s9, s8, 31
	s_ashr_i32 s8, s8, 5
	s_add_i32 s8, s8, s9
	s_lshl_b32 s9, s8, 3
	s_mulk_i32 s8, 0xb0
	s_waitcnt lgkmcnt(0)
	v_lshl_add_u32 v0, v8, 4, s3
	s_sub_i32 s8, s4, s8
	v_add_u32_e32 v1, 0x2000, v0
	s_sext_i32_i16 s4, s8
	v_ashrrev_i32_e32 v2, 31, v1
	s_bfe_u32 s4, s4, 0x3001c
	v_lshrrev_b32_e32 v2, 22, v2
	s_add_i32 s10, s8, s4
	v_add_u32_e32 v2, v1, v2
	s_sext_i32_i16 s4, s10
	s_and_b32 s10, s10, 0xfff8
	v_ashrrev_i32_e32 v9, 10, v2
	s_sub_i32 s8, s8, s10
	v_mul_i32_i24_e32 v2, 0x400, v9
	s_sext_i32_i16 s8, s8
	v_sub_u32_e32 v1, v1, v2
	s_lshr_b32 s4, s4, 3
	s_add_i32 s20, s9, s8
	v_lshrrev_b32_e32 v2, 4, v1
	s_ashr_i32 s21, s20, 31
	s_bfe_i64 s[10:11], s[4:5], 0x100000
	v_bitop3_b32 v1, v2, v1, 32 bitop3:0x6c
	s_lshl_b64 s[8:9], s[20:21], 19
	s_lshl_b64 s[10:11], s[10:11], 19
	v_ashrrev_i32_e32 v2, 31, v1
	s_add_u32 s24, s0, s10
	v_lshrrev_b32_e32 v2, 26, v2
	s_addc_u32 s25, s1, s11
	s_add_i32 s21, s3, 0
	v_add_u32_e32 v2, v1, v2
	s_add_i32 m0, s21, 0x10000
	s_add_i32 s12, s21, 0x12000
	v_ashrrev_i32_e32 v10, 6, v2
	v_lshlrev_b32_e32 v3, 3, v9
	v_and_b32_e32 v2, 0xffc0, v2
	s_add_u32 s10, s24, 0x40000
	v_and_b32_e32 v3, -16, v3
	v_sub_u32_e32 v1, v1, v2
	s_addc_u32 s11, s25, 0
	s_add_i32 s13, s21, 0x14000
	s_add_i32 s14, s21, 0x16000
	v_readlane_b32 s15, v254, 0
	v_add_u32_e32 v3, v10, v3
	v_lshrrev_b16_e32 v2, 7, v1
	s_add_u32 s22, s15, s8
	v_and_b32_e32 v4, 3, v10
	s_mov_b32 s15, 0x1fffe0
	v_lshrrev_b32_e32 v5, 2, v3
	v_lshlrev_b32_e32 v6, 1, v3
	v_and_b32_e32 v2, 1, v2
	v_and_or_b32 v4, v3, s15, v4
	v_and_b32_e32 v5, 4, v5
	v_and_b32_e32 v6, 24, v6
	v_add_u16_e32 v1, v1, v2
	v_mov_b32_e32 v2, 1
	v_or3_b32 v4, v4, v5, v6
	v_lshlrev_b32_e32 v5, 5, v9
	v_ashrrev_i16_sdwa v1, v2, sext(v1) dst_sel:DWORD dst_unused:UNUSED_PAD src0_sel:DWORD src1_sel:BYTE_0
	v_and_b32_e32 v5, 32, v5
	v_bfe_i32 v11, v1, 0, 16
	v_add_lshl_u32 v1, v5, v11, 1
	v_lshl_add_u32 v128, v4, 11, v1
	v_lshl_add_u32 v130, v3, 11, v1
	v_ashrrev_i32_e32 v1, 31, v0
	v_lshrrev_b32_e32 v1, 22, v1
	v_add_u32_e32 v1, v0, v1
	v_ashrrev_i32_e32 v12, 10, v1
	v_mul_i32_i24_e32 v1, 0x400, v12
	v_sub_u32_e32 v0, v0, v1
	v_lshrrev_b32_e32 v1, 4, v0
	v_bitop3_b32 v0, v1, v0, 32 bitop3:0x6c
	v_ashrrev_i32_e32 v1, 31, v0
	v_lshrrev_b32_e32 v1, 26, v1
	v_add_u32_e32 v1, v0, v1
	v_lshlrev_b32_e32 v3, 3, v12
	v_ashrrev_i32_e32 v13, 6, v1
	v_and_b32_e32 v3, -16, v3
	v_add_u32_e32 v3, v13, v3
	v_and_b32_e32 v4, 3, v13
	v_lshrrev_b32_e32 v5, 2, v3
	v_lshlrev_b32_e32 v6, 1, v3
	v_and_b32_e32 v1, 0xc0, v1
	v_and_or_b32 v4, v3, s15, v4
	v_and_b32_e32 v5, 4, v5
	v_and_b32_e32 v6, 24, v6
	v_sub_u32_e32 v0, v0, v1
	v_or3_b32 v4, v4, v5, v6
	v_lshlrev_b32_e32 v5, 5, v12
	v_ashrrev_i16_sdwa v0, v2, sext(v0) dst_sel:DWORD dst_unused:UNUSED_PAD src0_sel:DWORD src1_sel:BYTE_0
	v_and_b32_e32 v5, 32, v5
	v_bfe_i32 v14, v0, 0, 16
	v_add_lshl_u32 v0, v5, v14, 1
	v_lshl_add_u32 v132, v4, 11, v0
	global_load_lds_dwordx4 v132, s[24:25]
	s_mov_b32 m0, s12
	v_readlane_b32 s8, v254, 1
	global_load_lds_dwordx4 v128, s[24:25]
	s_mov_b32 m0, s13
	s_addc_u32 s23, s8, s9
	s_add_i32 s30, s21, 0x2000
	global_load_lds_dwordx4 v132, s[10:11]
	s_mov_b32 m0, s14
	s_add_u32 s8, s22, 0x40000
	v_lshl_add_u32 v134, v3, 11, v0
	global_load_lds_dwordx4 v128, s[10:11]
	s_mov_b32 m0, s21
	s_addc_u32 s9, s23, 0
	s_add_i32 s31, s21, 0x4000
	global_load_lds_dwordx4 v134, s[22:23]
	s_mov_b32 m0, s30
	s_add_i32 s33, s21, 0x6000
	global_load_lds_dwordx4 v130, s[22:23]
	s_mov_b32 m0, s31
	v_mov_b32_e32 v133, 0
	global_load_lds_dwordx4 v134, s[8:9]
	s_mov_b32 m0, s33
	v_mov_b32_e32 v129, v133
	global_load_lds_dwordx4 v130, s[8:9]
	v_mov_b32_e32 v135, v133
	v_mov_b32_e32 v131, v133
	s_mov_b32 s34, 0
	s_cmp_lg_u32 s5, 1
	v_lshl_add_u64 v[6:7], s[24:25], 0, v[132:133]
	v_lshl_add_u64 v[4:5], s[24:25], 0, v[128:129]
	v_lshl_add_u64 v[2:3], s[22:23], 0, v[134:135]
	v_lshl_add_u64 v[0:1], s[22:23], 0, v[130:131]
	s_cbranch_scc1 .LBB0_1606
	s_setprio 1
	s_barrier

;     __device__ bool next(int i, Unit& u) const {
;         const long L = (long)i * G + c; if (L >= nwg) return false;
;         int wgid = (int)L; { const int q = nwg / NXCD, r = nwg % NXCD, xcd = wgid % NXCD, off = wgid / NXCD; wgid = (xcd < r ? xcd * (q + 1) : r * (q + 1) + (xcd - r) * q) + off; }
;         const int nig = WGM * nN, gid = wgid / nig, fm = gid * WGM, gsz = (nM - fm) < WGM ? (nM - fm) : WGM;
;         u.pm = fm + ((wgid % nig) % gsz); u.pn = (wgid % nig) / gsz; return true;
;     }
; template <class Epi, bool ALIGN_EPI, int K, int LDA, int LDB>
; __device__ __forceinline__ void gemm_phase(LAS unsigned char* lds, const int wid, const Gemm g, const StaticOrder& S, const Epi& E) {
;     const int lane = lane_id_(), tid = wid * 64 + lane, wr = wid >> 2, wc = wid & 3, fr = lane & 15, fq = lane >> 4;
;     constexpr int nt = K / BK;
;     unsigned voffA[2], voffB[2];
; #pragma unroll
;     for (int i = 0; i < 2; ++i) { int R, C; stage_rc(tid * 16 + i * 8192, R, C); const int Rb = Epi::PERM ? ((R & ~31) + perm32(R & 31)) : R;
;         voffA[i] = (unsigned)(R * LDA + C) * 2u; voffB[i] = (unsigned)(Rb * LDB + C) * 2u; }
;     constexpr size_t kstep = (size_t)(BK * 2);
;     constexpr size_t hA = (size_t)HALF * LDA * 2, hB = (size_t)HALF * LDB * 2;
;     constexpr size_t tA = 2 * hA, tB = 2 * hB;
;     const unsigned ldsw = (unsigned)wid * 1024u;
;     const int aoff = lds_byte(wr * 64 + fr, fq * 8), boff = lds_byte(wc * 32 + fr, fq * 8);
;     ...
;     Unit cur, nxt; int ui = 0;
;     if (!S.next(0, cur)) return;
;     f32x4 acc[2][2][4][2];
; #pragma unroll
;     for (int a = 0; a < 2; ++a)
; #pragma unroll
;         for (int b = 0; b < 2; ++b)
; #pragma unroll
;             for (int m = 0; m < 4; ++m)
; #pragma unroll
;                 for (int n = 0; n < 2; ++n) acc[a][b][m][n] = (f32x4){0.f, 0.f, 0.f, 0.f};
;     bf16x8 At[4][2], B0[2][2], B1[2][2];
;     const char* cA = (const char*)g.A + (size_t)cur.pm * tA; const char* cB = (const char*)g.Bt + (size_t)cur.pn * tB;
;     PG8_STAGE(PG8_SB(0, 0), cB, voffB); PG8_STAGE(PG8_SB(0, 1), cB + hB, voffB); PG8_STAGE(PG8_SA(0, 0), cA, voffA); PG8_STAGE(PG8_SA(0, 1), cA + hA, voffA);
;     if (wr == 1) PG8_BAR;
;     PG8_WAIT_V(2); PG8_BAR;
;     PG8_STAGE(PG8_SB(1, 0), cB + kstep, voffB); PG8_STAGE(PG8_SA(1, 0), cA + kstep, voffA); PG8_STAGE(PG8_SB(1, 1), cB + hB + kstep, voffB);
.LBB0_1681:
	s_add_u32 s1, s46, 0x3380000
	s_addc_u32 s3, s47, 0
	s_lshl_b32 s33, s50, 10
	s_waitcnt lgkmcnt(0)
	v_lshl_add_u32 v0, v8, 4, s33
	v_ashrrev_i32_e32 v1, 31, v0
	v_lshrrev_b32_e32 v1, 22, v1
	v_add_u32_e32 v1, v0, v1
	v_ashrrev_i32_e32 v9, 10, v1
	v_mul_i32_i24_e32 v1, 0x400, v9
	v_sub_u32_e32 v1, v0, v1
	v_lshrrev_b32_e32 v2, 4, v1
	v_bitop3_b32 v1, v2, v1, 32 bitop3:0x6c
	v_ashrrev_i32_e32 v3, 31, v1
	v_lshrrev_b32_e32 v3, 26, v3
	v_lshlrev_b32_e32 v2, 3, v9
	v_add_u32_e32 v3, v1, v3
	v_and_b32_e32 v2, -16, v2
	v_ashrrev_i32_e32 v11, 6, v3
	v_and_b32_e32 v3, 0xc0, v3
	v_add_u32_e32 v2, v11, v2
	v_lshlrev_b32_e32 v4, 5, v9
	v_sub_u32_e32 v1, v1, v3
	v_mov_b32_e32 v3, 1
	v_and_b32_e32 v10, 32, v4
	v_ashrrev_i16_sdwa v1, v3, sext(v1) dst_sel:DWORD dst_unused:UNUSED_PAD src0_sel:DWORD src1_sel:BYTE_0
	v_lshlrev_b32_e32 v4, 1, v2
	v_lshrrev_b32_e32 v5, 2, v2
	v_and_b32_e32 v6, 3, v11
	s_mov_b32 s8, 0xffffe0
	v_bfe_i32 v12, v1, 0, 16
	v_and_b32_e32 v4, 24, v4
	v_and_b32_e32 v5, 4, v5
	v_and_or_b32 v6, v2, s8, v6
	s_movk_i32 s4, 0xb00
	v_add_u32_e32 v1, v10, v12
	v_or3_b32 v4, v6, v5, v4
	v_mul_lo_u32 v2, v2, s4
	v_add_lshl_u32 v144, v1, v2, 1
	v_mul_u32_u24_e32 v2, 0xb00, v4
	v_add_u32_e32 v0, 0x2000, v0
	v_add_lshl_u32 v146, v2, v1, 1
	v_ashrrev_i32_e32 v1, 31, v0
	v_lshrrev_b32_e32 v1, 22, v1
	v_add_u32_e32 v1, v0, v1
	v_ashrrev_i32_e32 v13, 10, v1
	v_mul_i32_i24_e32 v1, 0x400, v13
	v_sub_u32_e32 v0, v0, v1
	v_lshrrev_b32_e32 v1, 4, v0
	v_bitop3_b32 v0, v1, v0, 32 bitop3:0x6c
	v_ashrrev_i32_e32 v2, 31, v0
	v_lshrrev_b32_e32 v2, 26, v2
	s_add_i32 s6, s6, s7
	v_lshlrev_b32_e32 v1, 3, v13
	v_add_u32_e32 v2, v0, v2
	s_ashr_i32 s7, s6, 31
	v_and_b32_e32 v1, -16, v1
	v_ashrrev_i32_e32 v14, 6, v2
	v_lshlrev_b32_e32 v4, 5, v13
	s_lshr_b32 s7, s7, 27
	v_add_u32_e32 v1, v14, v1
	v_and_b32_e32 v15, 32, v4
	v_and_b32_e32 v4, 3, v14
	s_add_i32 s7, s6, s7
	v_and_or_b32 v4, v1, s8, v4
	s_ashr_i32 s8, s7, 5
	s_and_b32 s7, s7, 0xffe0
	s_sub_i32 s7, s6, s7
	s_bfe_i32 s6, s7, 0x80000
	s_bfe_u32 s6, s6, 0x3000c
	s_add_i32 s9, s7, s6
	v_and_b32_e32 v2, 0xffc0, v2
	s_bfe_i32 s6, s9, 0x80000
	s_and_b32 s9, s9, 0xf8
	v_sub_u32_e32 v0, v0, v2
	s_sub_i32 s7, s7, s9
	v_lshrrev_b16_e32 v2, 7, v0
	s_lshl_b32 s8, s8, 3
	s_sext_i32_i16 s10, s6
	s_sext_i32_i8 s7, s7
	v_and_b32_e32 v2, 1, v2
	s_add_i32 s59, s8, s7
	s_ashr_i32 s8, s10, 3
	s_lshr_b32 s5, s86, 8
	v_add_u16_e32 v0, v0, v2
	s_lshr_b32 s6, s10, 3
	s_mul_hi_i32 s9, s8, 0x160000
	s_mul_i32 s8, s8, 0x160000
	v_ashrrev_i16_sdwa v0, v3, sext(v0) dst_sel:DWORD dst_unused:UNUSED_PAD src0_sel:DWORD src1_sel:BYTE_0
	v_lshlrev_b32_e32 v2, 1, v1
	v_lshrrev_b32_e32 v3, 2, v1
	s_add_u32 s28, s1, s8
	v_bfe_i32 v16, v0, 0, 16
	v_and_b32_e32 v2, 24, v2
	v_and_b32_e32 v3, 4, v3
	s_addc_u32 s29, s3, s9
	s_add_i32 s36, s33, 0
	v_add_u32_e32 v0, v15, v16
	v_or3_b32 v2, v4, v3, v2
	v_mul_lo_u32 v1, v1, s4
	s_add_i32 m0, s36, 0x10000
	v_add_lshl_u32 v148, v0, v1, 1
	v_mul_u32_u24_e32 v1, 0xb00, v2
	global_load_lds_dwordx4 v146, s[28:29]
	s_add_i32 m0, s36, 0x12000
	v_add_lshl_u32 v150, v1, v0, 1
	s_add_u32 s8, s28, 0xb0000
	global_load_lds_dwordx4 v150, s[28:29]
	s_addc_u32 s9, s29, 0
	s_add_i32 m0, s36, 0x14000
	s_mul_i32 s11, s59, 0x160000
	global_load_lds_dwordx4 v146, s[8:9]
	s_add_i32 m0, s36, 0x16000
	s_mul_hi_i32 s7, s59, 0x160000
	s_add_u32 s26, s70, s11
	s_addc_u32 s27, s71, s7
	s_add_i32 s37, s36, 0x2000
	global_load_lds_dwordx4 v150, s[8:9]
	s_mov_b32 m0, s36
	s_add_u32 s8, s26, 0xb0000
	global_load_lds_dwordx4 v144, s[26:27]
	s_mov_b32 m0, s37
	s_addc_u32 s9, s27, 0
	s_add_i32 s38, s36, 0x4000
	global_load_lds_dwordx4 v148, s[26:27]
	s_mov_b32 m0, s38
	s_add_i32 s39, s36, 0x6000
	global_load_lds_dwordx4 v144, s[8:9]
	s_mov_b32 m0, s39
	v_mov_b32_e32 v147, 0
	global_load_lds_dwordx4 v148, s[8:9]
	v_mov_b32_e32 v151, v147
	v_mov_b32_e32 v145, v147
	v_mov_b32_e32 v149, v147
	s_cmp_eq_u32 s5, 1
	s_mov_b32 s9, 0
	v_lshl_add_u64 v[6:7], s[28:29], 0, v[146:147]
	v_lshl_add_u64 v[4:5], s[28:29], 0, v[150:151]
	v_lshl_add_u64 v[0:1], s[26:27], 0, v[144:145]
	s_cselect_b64 s[10:11], -1, 0
	s_cmp_lg_u32 s5, 1
	v_lshl_add_u64 v[2:3], s[26:27], 0, v[148:149]
	s_cbranch_scc1 .LBB0_1683
	s_setprio 1
	s_barrier

; #define PG8_STAGE(bufoff, gbase, voff) do { _Pragma("unroll") for (int _i = 0; _i < 2; ++_i) \
;         __builtin_amdgcn_global_load_lds((const unsigned*)((const char*)(gbase) + (voff)[_i]), (LAS unsigned*)(lds + (bufoff) + ldsw + _i * 8192), 16, 0, 0); } while (0)
; #define PG8_LDA(dst, b, h) do { _Pragma("unroll") for (int m = 0; m < 4; ++m) _Pragma("unroll") for (int k = 0; k < 2; ++k) dst[m][k] = *(const LAS bf16x8*)(lds + PG8_SA(b, h) + aoff + m * 2048 + k * 1024); } while (0)
; #define PG8_LDB(dst, b, h) do { _Pragma("unroll") for (int n = 0; n < 2; ++n) _Pragma("unroll") for (int k = 0; k < 2; ++k) dst[n][k] = *(const LAS bf16x8*)(lds + PG8_SB(b, h) + boff + n * 2048 + k * 1024); } while (0)
; #define PG8_MMA(ai, bj, At, Bt) do { __builtin_amdgcn_s_setprio(1); _Pragma("unroll") for (int m = 0; m < 4; ++m) _Pragma("unroll") for (int n = 0; n < 2; ++n) _Pragma("unroll") for (int k = 0; k < 2; ++k) \
;         acc[ai][bj][m][n] = __builtin_amdgcn_mfma_f32_16x16x32_bf16(Bt[n][k], At[m][k], acc[ai][bj][m][n], 0, 0, 0); __builtin_amdgcn_s_setprio(0); } while (0)
; #define PG8_WAIT_V(n) asm volatile("s_waitcnt vmcnt(" #n ")" ::: "memory")
; #define PG8_WAIT_L(n) asm volatile("s_waitcnt lgkmcnt(" #n ")" ::: "memory")
; #define PG8_BAR __builtin_amdgcn_s_barrier()
; #define PG8_SCHED __builtin_amdgcn_sched_barrier(0)
; template <class Epi, bool ALIGN_EPI, int K, int LDA, int LDB>
; __device__ __forceinline__ void gemm_phase(LAS unsigned char* lds, const int wid, const Gemm g, const StaticOrder& S, const Epi& E) {
;     ...
;             const bool last = (t == nt - 2);
;             const char* a1 = cA + (size_t)(t + 1) * kstep;
;             const char* a2 = last ? nA : cA + (size_t)(t + 2) * kstep; const char* b2 = last ? nB : cB + (size_t)(t + 2) * kstep;
;             const char* a3 = a2 + kstep; const char* b3 = b2 + kstep;
;             PG8_LDB(B0, 0, 0); PG8_LDB(B1, 0, 1); PG8_SCHED; PG8_LDA(At, 0, 0); PG8_STAGE(PG8_SA(1, 1), a1 + hA, voffA);
;             PG8_WAIT_V(8); PG8_WAIT_L(0); PG8_BAR; PG8_MMA(0, 0, At, B0); PG8_MMA(0, 1, At, B1); PG8_BAR; PG8_SCHED;
;             PG8_LDA(At, 0, 1); PG8_STAGE(PG8_SB(0, 0), b2, voffB); PG8_STAGE(PG8_SB(0, 1), b2 + hB, voffB); PG8_STAGE(PG8_SA(0, 0), a2, voffA);
;             PG8_WAIT_V(8); PG8_WAIT_L(0); PG8_BAR; PG8_MMA(1, 0, At, B0); PG8_MMA(1, 1, At, B1); PG8_BAR; PG8_SCHED;
.LBB0_1697:
	ds_read_b128 v[120:123], v167
	ds_read_b128 v[124:127], v167 offset:1024
	ds_read_b128 v[128:131], v167 offset:2048
	ds_read_b128 v[132:135], v167 offset:3072
	ds_read_b128 v[160:163], v168
	ds_read_b128 v[170:173], v168 offset:1024
	ds_read_b128 v[174:177], v168 offset:2048
	ds_read_b128 v[178:181], v168 offset:3072
	s_add_u32 s28, s26, 0x100
	s_addc_u32 s29, s27, 0
	s_cmp_eq_u32 s63, 40
	s_cselect_b32 s35, s7, s29
	s_cselect_b32 s34, s6, s28
	s_cselect_b32 s31, s25, s62
	s_cselect_b32 s30, s24, s61
	s_add_i32 m0, s36, 0xc000
	ds_read_b128 v[182:185], v169
	ds_read_b128 v[186:189], v169 offset:1024
	ds_read_b128 v[190:193], v169 offset:2048
	ds_read_b128 v[194:197], v169 offset:3072
	ds_read_b128 v[198:201], v169 offset:4096
	ds_read_b128 v[202:205], v169 offset:5120
	ds_read_b128 v[206:209], v169 offset:6144
	ds_read_b128 v[210:213], v169 offset:7168
	global_load_lds_dwordx4 v152, s[26:27]
	s_add_i32 m0, s36, 0xe000
	s_nop 0
	global_load_lds_dwordx4 v154, s[26:27]
	s_waitcnt vmcnt(8)
	s_waitcnt lgkmcnt(0)
	s_barrier
	s_waitcnt lgkmcnt(0)
	v_mfma_f32_16x16x32_bf16 v[140:143], v[120:123], v[182:185], v[140:143]
	v_mfma_f32_16x16x32_bf16 v[136:139], v[128:131], v[182:185], v[136:139]
	v_mfma_f32_16x16x32_bf16 v[108:111], v[120:123], v[190:193], v[108:111]
	v_mfma_f32_16x16x32_bf16 v[104:107], v[128:131], v[190:193], v[104:107]
	v_mfma_f32_16x16x32_bf16 v[92:95], v[120:123], v[198:201], v[92:95]
	v_mfma_f32_16x16x32_bf16 v[88:91], v[128:131], v[198:201], v[88:91]
	v_mfma_f32_16x16x32_bf16 v[76:79], v[120:123], v[206:209], v[76:79]
	v_mfma_f32_16x16x32_bf16 v[72:75], v[128:131], v[206:209], v[72:75]
	v_mfma_f32_16x16x32_bf16 v[140:143], v[124:127], v[186:189], v[140:143]
	v_mfma_f32_16x16x32_bf16 v[136:139], v[132:135], v[186:189], v[136:139]
	v_mfma_f32_16x16x32_bf16 v[108:111], v[124:127], v[194:197], v[108:111]
	v_mfma_f32_16x16x32_bf16 v[104:107], v[132:135], v[194:197], v[104:107]
	v_mfma_f32_16x16x32_bf16 v[92:95], v[124:127], v[202:205], v[92:95]
	v_mfma_f32_16x16x32_bf16 v[88:91], v[132:135], v[202:205], v[88:91]
	v_mfma_f32_16x16x32_bf16 v[76:79], v[124:127], v[210:213], v[76:79]
	v_mfma_f32_16x16x32_bf16 v[72:75], v[132:135], v[210:213], v[72:75]
	v_mfma_f32_16x16x32_bf16 v[116:119], v[160:163], v[182:185], v[116:119]
	v_mfma_f32_16x16x32_bf16 v[112:115], v[174:177], v[182:185], v[112:115]
	v_mfma_f32_16x16x32_bf16 v[100:103], v[160:163], v[190:193], v[100:103]
	v_mfma_f32_16x16x32_bf16 v[96:99], v[174:177], v[190:193], v[96:99]
	v_mfma_f32_16x16x32_bf16 v[84:87], v[160:163], v[198:201], v[84:87]
	v_mfma_f32_16x16x32_bf16 v[80:83], v[174:177], v[198:201], v[80:83]
	v_mfma_f32_16x16x32_bf16 v[68:71], v[160:163], v[206:209], v[68:71]
	v_mfma_f32_16x16x32_bf16 v[64:67], v[174:177], v[206:209], v[64:67]
	v_mfma_f32_16x16x32_bf16 v[116:119], v[170:173], v[186:189], v[116:119]
	v_mfma_f32_16x16x32_bf16 v[112:115], v[178:181], v[186:189], v[112:115]
	v_mfma_f32_16x16x32_bf16 v[100:103], v[170:173], v[194:197], v[100:103]
	v_mfma_f32_16x16x32_bf16 v[96:99], v[178:181], v[194:197], v[96:99]
	v_mfma_f32_16x16x32_bf16 v[84:87], v[170:173], v[202:205], v[84:87]
	v_mfma_f32_16x16x32_bf16 v[80:83], v[178:181], v[202:205], v[80:83]
	v_mfma_f32_16x16x32_bf16 v[68:71], v[170:173], v[210:213], v[68:71]
	v_mfma_f32_16x16x32_bf16 v[64:67], v[178:181], v[210:213], v[64:67]
	s_barrier
	s_add_u32 s98, s30, s12
	s_addc_u32 s99, s31, s13
	s_add_u32 s100, s34, s12
	s_addc_u32 s101, s35, s13
	s_add_i32 s26, s54, s33
	s_mov_b32 m0, s26
	ds_read_b128 v[182:185], v169 offset:16384
	ds_read_b128 v[186:189], v169 offset:17408
	ds_read_b128 v[190:193], v169 offset:18432
	ds_read_b128 v[194:197], v169 offset:19456
	ds_read_b128 v[198:201], v169 offset:20480
	ds_read_b128 v[202:205], v169 offset:21504
	ds_read_b128 v[206:209], v169 offset:22528
	ds_read_b128 v[210:213], v169 offset:23552
	global_load_lds_dwordx4 v146, s[30:31]
	s_add_i32 m0, s26, 0x2000
	s_add_u32 s26, s30, 0xb0000
	s_addc_u32 s27, s31, 0
	s_add_i32 s52, s55, s33
	global_load_lds_dwordx4 v150, s[30:31]
	s_mov_b32 m0, s52
	s_nop 0
	global_load_lds_dwordx4 v146, s[26:27]
	s_add_i32 m0, s52, 0x2000
	s_nop 0
	global_load_lds_dwordx4 v150, s[26:27]
	s_mov_b32 m0, s36
	s_nop 0
	global_load_lds_dwordx4 v144, s[34:35]
	s_mov_b32 m0, s37
	s_nop 0
	global_load_lds_dwordx4 v148, s[34:35]
	s_waitcnt vmcnt(8)
	s_waitcnt lgkmcnt(0)
	s_barrier
	s_waitcnt lgkmcnt(0)
	v_mfma_f32_16x16x32_bf16 v[60:63], v[120:123], v[182:185], v[60:63]
	v_mfma_f32_16x16x32_bf16 v[56:59], v[128:131], v[182:185], v[56:59]
	v_mfma_f32_16x16x32_bf16 v[44:47], v[120:123], v[190:193], v[44:47]
	v_mfma_f32_16x16x32_bf16 v[40:43], v[128:131], v[190:193], v[40:43]
	v_mfma_f32_16x16x32_bf16 v[28:31], v[120:123], v[198:201], v[28:31]
	v_mfma_f32_16x16x32_bf16 v[24:27], v[128:131], v[198:201], v[24:27]
	v_mfma_f32_16x16x32_bf16 v[12:15], v[120:123], v[206:209], v[12:15]
	v_mfma_f32_16x16x32_bf16 v[8:11], v[128:131], v[206:209], v[8:11]
	v_mfma_f32_16x16x32_bf16 v[60:63], v[124:127], v[186:189], v[60:63]
	v_mfma_f32_16x16x32_bf16 v[56:59], v[132:135], v[186:189], v[56:59]
	v_mfma_f32_16x16x32_bf16 v[44:47], v[124:127], v[194:197], v[44:47]
	v_mfma_f32_16x16x32_bf16 v[40:43], v[132:135], v[194:197], v[40:43]
	v_mfma_f32_16x16x32_bf16 v[28:31], v[124:127], v[202:205], v[28:31]
	v_mfma_f32_16x16x32_bf16 v[24:27], v[132:135], v[202:205], v[24:27]
	v_mfma_f32_16x16x32_bf16 v[12:15], v[124:127], v[210:213], v[12:15]
	v_mfma_f32_16x16x32_bf16 v[8:11], v[132:135], v[210:213], v[8:11]
	v_mfma_f32_16x16x32_bf16 v[52:55], v[160:163], v[182:185], v[52:55]
	v_mfma_f32_16x16x32_bf16 v[48:51], v[174:177], v[182:185], v[48:51]
	v_mfma_f32_16x16x32_bf16 v[36:39], v[160:163], v[190:193], v[36:39]
	v_mfma_f32_16x16x32_bf16 v[32:35], v[174:177], v[190:193], v[32:35]
	v_mfma_f32_16x16x32_bf16 v[20:23], v[160:163], v[198:201], v[20:23]
	v_mfma_f32_16x16x32_bf16 v[16:19], v[174:177], v[198:201], v[16:19]
	v_mfma_f32_16x16x32_bf16 v[4:7], v[160:163], v[206:209], v[4:7]
	v_mfma_f32_16x16x32_bf16 v[0:3], v[174:177], v[206:209], v[0:3]
	v_mfma_f32_16x16x32_bf16 v[52:55], v[170:173], v[186:189], v[52:55]
	v_mfma_f32_16x16x32_bf16 v[48:51], v[178:181], v[186:189], v[48:51]
	v_mfma_f32_16x16x32_bf16 v[36:39], v[170:173], v[194:197], v[36:39]
	v_mfma_f32_16x16x32_bf16 v[32:35], v[178:181], v[194:197], v[32:35]
	v_mfma_f32_16x16x32_bf16 v[20:23], v[170:173], v[202:205], v[20:23]
	v_mfma_f32_16x16x32_bf16 v[16:19], v[178:181], v[202:205], v[16:19]
	v_mfma_f32_16x16x32_bf16 v[4:7], v[170:173], v[210:213], v[4:7]
	v_mfma_f32_16x16x32_bf16 v[0:3], v[178:181], v[210:213], v[0:3]
	s_barrier
; #define PG8_STAGE(bufoff, gbase, voff) do { _Pragma("unroll") for (int _i = 0; _i < 2; ++_i) \
;         __builtin_amdgcn_global_load_lds((const unsigned*)((const char*)(gbase) + (voff)[_i]), (LAS unsigned*)(lds + (bufoff) + ldsw + _i * 8192), 16, 0, 0); } while (0)
; #define PG8_LDA(dst, b, h) do { _Pragma("unroll") for (int m = 0; m < 4; ++m) _Pragma("unroll") for (int k = 0; k < 2; ++k) dst[m][k] = *(const LAS bf16x8*)(lds + PG8_SA(b, h) + aoff + m * 2048 + k * 1024); } while (0)
; #define PG8_LDB(dst, b, h) do { _Pragma("unroll") for (int n = 0; n < 2; ++n) _Pragma("unroll") for (int k = 0; k < 2; ++k) dst[n][k] = *(const LAS bf16x8*)(lds + PG8_SB(b, h) + boff + n * 2048 + k * 1024); } while (0)
; #define PG8_MMA(ai, bj, At, Bt) do { __builtin_amdgcn_s_setprio(1); _Pragma("unroll") for (int m = 0; m < 4; ++m) _Pragma("unroll") for (int n = 0; n < 2; ++n) _Pragma("unroll") for (int k = 0; k < 2; ++k) \
;         acc[ai][bj][m][n] = __builtin_amdgcn_mfma_f32_16x16x32_bf16(Bt[n][k], At[m][k], acc[ai][bj][m][n], 0, 0, 0); __builtin_amdgcn_s_setprio(0); } while (0)
; #define PG8_WAIT_V(n) asm volatile("s_waitcnt vmcnt(" #n ")" ::: "memory")
; #define PG8_WAIT_L(n) asm volatile("s_waitcnt lgkmcnt(" #n ")" ::: "memory")
; #define PG8_BAR __builtin_amdgcn_s_barrier()
; #define PG8_SCHED __builtin_amdgcn_sched_barrier(0)
; template <class Epi, bool ALIGN_EPI, int K, int LDA, int LDB>
; __device__ __forceinline__ void gemm_phase(LAS unsigned char* lds, const int wid, const Gemm g, const StaticOrder& S, const Epi& E) {
;     ...
;             PG8_LDB(B0, 1, 0); PG8_LDB(B1, 1, 1); PG8_SCHED; PG8_LDA(At, 1, 0); PG8_STAGE(PG8_SA(0, 1), a2 + hA, voffA);
;             PG8_WAIT_V(8); PG8_WAIT_L(0); PG8_BAR; PG8_MMA(0, 0, At, B0); PG8_MMA(0, 1, At, B1); PG8_BAR; PG8_SCHED;
;             PG8_LDA(At, 1, 1); PG8_STAGE(PG8_SB(1, 0), b3, voffB); PG8_STAGE(PG8_SB(1, 1), b3 + hB, voffB); PG8_STAGE(PG8_SA(1, 0), a3, voffA);
;             PG8_WAIT_V(8); PG8_WAIT_L(0); PG8_BAR; PG8_MMA(1, 0, At, B0); PG8_MMA(1, 1, At, B1); PG8_BAR; PG8_SCHED;
;         }
;         if constexpr (ALIGN_EPI) { if (wr == 0) PG8_BAR; }
	s_add_i32 s52, 0, 0x18000
	s_add_i32 s53, 0, 0x1c000
	v_add_u32_e32 v132, s52, v166
	v_add_u32_e32 v178, s53, v166
	ds_read_b128 v[120:123], v132
	ds_read_b128 v[124:127], v132 offset:1024
	ds_read_b128 v[128:131], v132 offset:2048
	ds_read_b128 v[132:135], v132 offset:3072
	ds_read_b128 v[160:163], v178
	ds_read_b128 v[170:173], v178 offset:1024
	ds_read_b128 v[174:177], v178 offset:2048
	ds_read_b128 v[178:181], v178 offset:3072
	s_add_u32 s26, s34, 0xb0000
	s_addc_u32 s27, s35, 0
	s_mov_b32 m0, s38
	ds_read_b128 v[182:185], v169 offset:32768
	ds_read_b128 v[186:189], v169 offset:33792
	ds_read_b128 v[190:193], v169 offset:34816
	ds_read_b128 v[194:197], v169 offset:35840
	ds_read_b128 v[198:201], v169 offset:36864
	ds_read_b128 v[202:205], v169 offset:37888
	ds_read_b128 v[206:209], v169 offset:38912
	ds_read_b128 v[210:213], v169 offset:39936
	global_load_lds_dwordx4 v144, s[26:27]
	s_mov_b32 m0, s39
	s_nop 0
	global_load_lds_dwordx4 v148, s[26:27]
	s_waitcnt vmcnt(8)
	s_waitcnt lgkmcnt(0)
	s_barrier
	s_waitcnt lgkmcnt(0)
	v_mfma_f32_16x16x32_bf16 v[140:143], v[120:123], v[182:185], v[140:143]
	v_mfma_f32_16x16x32_bf16 v[136:139], v[128:131], v[182:185], v[136:139]
	v_mfma_f32_16x16x32_bf16 v[108:111], v[120:123], v[190:193], v[108:111]
	v_mfma_f32_16x16x32_bf16 v[104:107], v[128:131], v[190:193], v[104:107]
	v_mfma_f32_16x16x32_bf16 v[92:95], v[120:123], v[198:201], v[92:95]
	v_mfma_f32_16x16x32_bf16 v[88:91], v[128:131], v[198:201], v[88:91]
	v_mfma_f32_16x16x32_bf16 v[76:79], v[120:123], v[206:209], v[76:79]
	v_mfma_f32_16x16x32_bf16 v[72:75], v[128:131], v[206:209], v[72:75]
	v_mfma_f32_16x16x32_bf16 v[140:143], v[124:127], v[186:189], v[140:143]
	v_mfma_f32_16x16x32_bf16 v[136:139], v[132:135], v[186:189], v[136:139]
	v_mfma_f32_16x16x32_bf16 v[108:111], v[124:127], v[194:197], v[108:111]
	v_mfma_f32_16x16x32_bf16 v[104:107], v[132:135], v[194:197], v[104:107]
	v_mfma_f32_16x16x32_bf16 v[92:95], v[124:127], v[202:205], v[92:95]
	v_mfma_f32_16x16x32_bf16 v[88:91], v[132:135], v[202:205], v[88:91]
	v_mfma_f32_16x16x32_bf16 v[76:79], v[124:127], v[210:213], v[76:79]
	v_mfma_f32_16x16x32_bf16 v[72:75], v[132:135], v[210:213], v[72:75]
	v_mfma_f32_16x16x32_bf16 v[116:119], v[160:163], v[182:185], v[116:119]
	v_mfma_f32_16x16x32_bf16 v[112:115], v[174:177], v[182:185], v[112:115]
	v_mfma_f32_16x16x32_bf16 v[100:103], v[160:163], v[190:193], v[100:103]
	v_mfma_f32_16x16x32_bf16 v[96:99], v[174:177], v[190:193], v[96:99]
	v_mfma_f32_16x16x32_bf16 v[84:87], v[160:163], v[198:201], v[84:87]
	v_mfma_f32_16x16x32_bf16 v[80:83], v[174:177], v[198:201], v[80:83]
	v_mfma_f32_16x16x32_bf16 v[68:71], v[160:163], v[206:209], v[68:71]
	v_mfma_f32_16x16x32_bf16 v[64:67], v[174:177], v[206:209], v[64:67]
	v_mfma_f32_16x16x32_bf16 v[116:119], v[170:173], v[186:189], v[116:119]
	v_mfma_f32_16x16x32_bf16 v[112:115], v[178:181], v[186:189], v[112:115]
	v_mfma_f32_16x16x32_bf16 v[100:103], v[170:173], v[194:197], v[100:103]
	v_mfma_f32_16x16x32_bf16 v[96:99], v[178:181], v[194:197], v[96:99]
	v_mfma_f32_16x16x32_bf16 v[84:87], v[170:173], v[202:205], v[84:87]
	v_mfma_f32_16x16x32_bf16 v[80:83], v[178:181], v[202:205], v[80:83]
	v_mfma_f32_16x16x32_bf16 v[68:71], v[170:173], v[210:213], v[68:71]
	v_mfma_f32_16x16x32_bf16 v[64:67], v[178:181], v[210:213], v[64:67]
	s_barrier
	s_add_i32 s26, s52, s33
	s_mov_b32 m0, s26
	ds_read_b128 v[182:185], v169 offset:49152
	ds_read_b128 v[186:189], v169 offset:50176
	ds_read_b128 v[190:193], v169 offset:51200
	ds_read_b128 v[194:197], v169 offset:52224
	ds_read_b128 v[198:201], v169 offset:53248
	ds_read_b128 v[202:205], v169 offset:54272
	ds_read_b128 v[206:209], v169 offset:55296
	ds_read_b128 v[210:213], v169 offset:56320
	global_load_lds_dwordx4 v146, s[98:99]
	s_add_i32 m0, s26, 0x2000
	s_add_u32 s26, s30, 0xb0080
	s_addc_u32 s27, s31, 0
	s_add_i32 s30, s53, s33
	global_load_lds_dwordx4 v150, s[98:99]
	s_mov_b32 m0, s30
	s_nop 0
	global_load_lds_dwordx4 v146, s[26:27]
	s_add_i32 m0, s30, 0x2000
	s_nop 0
	global_load_lds_dwordx4 v150, s[26:27]
	s_mov_b32 m0, s48
	s_nop 0
	global_load_lds_dwordx4 v144, s[100:101]
	s_mov_b32 m0, s49
	s_nop 0
	global_load_lds_dwordx4 v148, s[100:101]
	s_waitcnt vmcnt(8)
	s_waitcnt lgkmcnt(0)
	s_barrier
	s_waitcnt lgkmcnt(0)
	v_mfma_f32_16x16x32_bf16 v[60:63], v[120:123], v[182:185], v[60:63]
	v_mfma_f32_16x16x32_bf16 v[56:59], v[128:131], v[182:185], v[56:59]
	v_mfma_f32_16x16x32_bf16 v[44:47], v[120:123], v[190:193], v[44:47]
	v_mfma_f32_16x16x32_bf16 v[40:43], v[128:131], v[190:193], v[40:43]
	v_mfma_f32_16x16x32_bf16 v[28:31], v[120:123], v[198:201], v[28:31]
	v_mfma_f32_16x16x32_bf16 v[24:27], v[128:131], v[198:201], v[24:27]
	v_mfma_f32_16x16x32_bf16 v[12:15], v[120:123], v[206:209], v[12:15]
	v_mfma_f32_16x16x32_bf16 v[8:11], v[128:131], v[206:209], v[8:11]
	v_mfma_f32_16x16x32_bf16 v[60:63], v[124:127], v[186:189], v[60:63]
	v_mfma_f32_16x16x32_bf16 v[56:59], v[132:135], v[186:189], v[56:59]
	v_mfma_f32_16x16x32_bf16 v[44:47], v[124:127], v[194:197], v[44:47]
	v_mfma_f32_16x16x32_bf16 v[40:43], v[132:135], v[194:197], v[40:43]
	v_mfma_f32_16x16x32_bf16 v[28:31], v[124:127], v[202:205], v[28:31]
	v_mfma_f32_16x16x32_bf16 v[24:27], v[132:135], v[202:205], v[24:27]
	v_mfma_f32_16x16x32_bf16 v[12:15], v[124:127], v[210:213], v[12:15]
	v_mfma_f32_16x16x32_bf16 v[8:11], v[132:135], v[210:213], v[8:11]
	v_mfma_f32_16x16x32_bf16 v[52:55], v[160:163], v[182:185], v[52:55]
	v_mfma_f32_16x16x32_bf16 v[48:51], v[174:177], v[182:185], v[48:51]
	v_mfma_f32_16x16x32_bf16 v[36:39], v[160:163], v[190:193], v[36:39]
	v_mfma_f32_16x16x32_bf16 v[32:35], v[174:177], v[190:193], v[32:35]
	v_mfma_f32_16x16x32_bf16 v[20:23], v[160:163], v[198:201], v[20:23]
	v_mfma_f32_16x16x32_bf16 v[16:19], v[174:177], v[198:201], v[16:19]
	v_mfma_f32_16x16x32_bf16 v[4:7], v[160:163], v[206:209], v[4:7]
	v_mfma_f32_16x16x32_bf16 v[0:3], v[174:177], v[206:209], v[0:3]
	v_mfma_f32_16x16x32_bf16 v[52:55], v[170:173], v[186:189], v[52:55]
	v_mfma_f32_16x16x32_bf16 v[48:51], v[178:181], v[186:189], v[48:51]
	v_mfma_f32_16x16x32_bf16 v[36:39], v[170:173], v[194:197], v[36:39]
	v_mfma_f32_16x16x32_bf16 v[32:35], v[178:181], v[194:197], v[32:35]
	v_mfma_f32_16x16x32_bf16 v[20:23], v[170:173], v[202:205], v[20:23]
	v_mfma_f32_16x16x32_bf16 v[16:19], v[178:181], v[202:205], v[16:19]
	v_mfma_f32_16x16x32_bf16 v[4:7], v[170:173], v[210:213], v[4:7]
	v_mfma_f32_16x16x32_bf16 v[0:3], v[178:181], v[210:213], v[0:3]
	s_barrier
	s_add_i32 s63, s63, 2
	s_add_u32 s61, s61, 0x100
	s_addc_u32 s62, s62, 0
	s_cmp_gt_u32 s63, 41
	s_mov_b64 s[26:27], s[28:29]
	s_cbranch_scc0 .LBB0_1697
	s_and_b64 vcc, exec, s[14:15]
	s_cbranch_vccz .LBB0_1700
	s_barrier
